# GEMM mainloops v3: loop-invariant LDS addressing hoisted (fixed buffer per unrolled half), single vmcnt wait per half; plus v_rcp sigmoid
# speedup vs baseline: 1.0265x; 1.0116x over previous
;   DI unsigned rowoff(int r, int sch) const { const int g = r & 3, bc = r >> 2, b = bc / NCMP, c = bc - b * NCMP; return (unsigned)(b * Sn + c * 16) * 512u + g * 64 + sch; }
; template <int NI, class XL, class EP>
; DI void gemm_tile(const u16* __restrict__ W, int ldw, int f0, int t0, int K, XL xl, EP ep, unsigned char* smem) {
;     ...
;   f32x4 acc[4][NI];
; #pragma unroll
;   for (int i = 0; i < 4; ++i)
; #pragma unroll
;     for (int j = 0; j < NI; ++j) acc[i][j] = (f32x4){0.f, 0.f, 0.f, 0.f};
;   u32x4 wr[2], xr[XR];
;   const unsigned wbyte = ((unsigned)(f0 + srow * 2) * 32u + sch) * 2u;
;   const unsigned xbyte = xl.rowoff(t0 + srow * XR, sch) * 2u;
;   const int xrs = xl.rstride();
;   const int nk = K >> 5;
;   auto gload = [&](int it) {
;     const int k = it * 32;
;     const char* wb = (const char*)(W + (size_t)(k >> 5) * ldw * 32);
;     const char* xb = (const char*)xl.kbase(k);
; #pragma unroll
;     for (int i = 0; i < 2; ++i) wr[i] = *(const u32x4*)(wb + wbyte + i * 64);
; #pragma unroll
;     for (int i = 0; i < XR; ++i) xr[i] = *(const u32x4*)(xb + xbyte + i * xrs);
;   };
;   auto lstore = [&](int buf) {
;     u16* Ws = S0 + buf * BUF; u16* Xs = Ws + 128 * LST;
; #pragma unroll
;     for (int i = 0; i < 2; ++i) *(u32x4*)(Ws + (srow * 2 + i) * LST + sch) = wr[i];
; #pragma unroll
;     for (int i = 0; i < XR; ++i) *(u32x4*)(Xs + (srow * XR + i) * LST + sch) = xr[i];
;   };
;   gload(0);
;   __syncthreads();
;   lstore(0);
;   __syncthreads();
;   if (nk > 1) gload(1);
.LBB0_268:
	v_mov_b32_e32 v161, v218
	s_and_b32 s22, s59, 7
	s_or_b32 s61, s22, s53
	v_ashrrev_i32_e32 v44, 2, v161
	s_lshl_b32 s22, s59, 5
	v_lshlrev_b32_e32 v0, 3, v161
	v_lshlrev_b32_e32 v46, 6, v44
	s_and_b32 s60, s22, 0xffffff00
	v_and_b32_e32 v45, 24, v0
	v_lshl_add_u32 v0, s61, 12, v46
	s_add_i32 s60, s60, s54
	v_or_b32_e32 v0, v0, v45
	v_and_b32_e32 v48, 0x3fffffc, v161
	v_lshlrev_b32_e32 v47, 1, v0
	v_add_u32_e32 v0, s60, v48
	v_lshlrev_b32_e32 v162, 1, v45
	v_readlane_b32 s22, v245, 25
	v_lshl_or_b32 v49, v0, 6, v162
	v_readlane_b32 s23, v245, 26
	global_load_dwordx4 v[16:19], v47, s[42:43]
	global_load_dwordx4 v[20:23], v47, s[42:43] offset:64
	s_nop 2
	global_load_dwordx4 v[24:27], v49, s[22:23]
	global_load_dwordx4 v[28:31], v49, s[22:23] offset:64
	global_load_dwordx4 v[32:35], v49, s[22:23] offset:128
	global_load_dwordx4 v[36:39], v49, s[22:23] offset:192
	v_mul_lo_u32 v167, v44, s37
	v_or_b32_e32 v163, v167, v162
	v_add_u32_e32 v164, v163, v167
	s_barrier
	s_and_b32 s23, s58, 0x3ffff00
	s_and_b32 s24, s57, 7
	s_add_i32 s24, s56, s24
	s_add_i32 s23, s54, s23
	v_ashrrev_i32_e32 v51, 1, v161
	v_and_b32_e32 v50, 15, v161
	v_lshrrev_b32_e32 v52, 1, v161
	v_lshlrev_b32_e32 v53, 1, v161
	v_and_b32_e32 v159, 0xffffffc0, v51
	v_add_u32_e32 v44, s23, v48
	v_lshl_add_u32 v46, s24, 12, v46
	v_mov_b32_e32 v0, 0
	v_and_b32_e32 v158, 24, v52
	v_and_or_b32 v160, v53, s44, v50
	v_or_b32_e32 v48, v159, v50
	v_lshl_or_b32 v152, v44, 6, v162
	v_or_b32_e32 v44, v46, v45
	s_mov_b32 s22, 1
	v_mov_b32_e32 v155, v153
	v_mov_b32_e32 v1, v0
	v_mov_b32_e32 v2, v0
	v_mov_b32_e32 v3, v0
	v_mov_b32_e32 v4, v0
	v_mov_b32_e32 v5, v0
	v_mov_b32_e32 v6, v0
	v_mov_b32_e32 v7, v0
	v_mov_b32_e32 v8, v0
	v_mov_b32_e32 v9, v0
	v_mov_b32_e32 v10, v0
	v_mov_b32_e32 v11, v0
	v_mov_b32_e32 v12, v0
	v_mov_b32_e32 v13, v0
	v_mov_b32_e32 v14, v0
	v_mov_b32_e32 v15, v0
	v_mov_b32_e32 v40, v0
	v_mov_b32_e32 v41, v0
	v_mov_b32_e32 v42, v0
	v_mov_b32_e32 v43, v0
	v_mul_u32_u24_e32 v165, 48, v160
	v_lshlrev_b32_e32 v166, 1, v158
	v_mul_lo_u32 v168, v48, 48
	v_lshlrev_b32_e32 v154, 1, v44
	v_mov_b64_e32 v[156:157], v[152:153]
	v_mov_b32_e32 v56, v0
	v_mov_b32_e32 v57, v0
	v_mov_b32_e32 v58, v0
	v_mov_b32_e32 v59, v0
	v_mov_b32_e32 v68, v0
	v_mov_b32_e32 v69, v0
	v_mov_b32_e32 v70, v0
	v_mov_b32_e32 v71, v0
	v_mov_b32_e32 v80, v0
	v_mov_b32_e32 v81, v0
	v_mov_b32_e32 v82, v0
	v_mov_b32_e32 v83, v0
	v_mov_b32_e32 v44, v0
	v_mov_b32_e32 v45, v0
	v_mov_b32_e32 v46, v0
	v_mov_b32_e32 v48, v0
	s_waitcnt vmcnt(5)
	ds_write_b128 v163, v[16:19]
	s_waitcnt vmcnt(4)
	ds_write_b128 v163, v[20:23] offset:96
	s_waitcnt vmcnt(3)
	ds_write_b128 v164, v[24:27] offset:12288
	s_waitcnt vmcnt(2)
	ds_write_b128 v164, v[28:31] offset:12384
	s_waitcnt vmcnt(1)
	ds_write_b128 v164, v[32:35] offset:12480
	s_waitcnt vmcnt(0)
	ds_write_b128 v164, v[36:39] offset:12576
	s_waitcnt lgkmcnt(0)
	s_barrier
	global_load_dwordx4 v[20:23], v47, s[6:7]
	global_load_dwordx4 v[16:19], v47, s[6:7] offset:64
	global_load_dwordx4 v[36:39], v49, s[8:9]
	global_load_dwordx4 v[32:35], v49, s[8:9] offset:64
	global_load_dwordx4 v[28:31], v49, s[8:9] offset:128
	global_load_dwordx4 v[24:27], v49, s[8:9] offset:192
	s_add_u32 s98, s42, s45
	s_addc_u32 s99, s43, 0
	s_add_u32 s100, s42, s46
	s_addc_u32 s101, s43, 0
	global_load_dwordx4 v[200:203], v154, s[98:99]
	global_load_dwordx4 v[204:207], v154, s[98:99] offset:64
	global_load_dwordx4 v[208:211], v156, s[100:101] offset:2048
	global_load_dwordx4 v[212:215], v156, s[100:101] offset:2112
	global_load_dwordx4 v[220:223], v156, s[100:101] offset:2176
	global_load_dwordx4 v[224:227], v156, s[100:101] offset:2240
	s_add_u32 s98, s98, s4
	s_addc_u32 s99, s99, s5
	s_add_u32 s100, s100, s14
	s_addc_u32 s101, s101, s15
	v_mov_b32_e32 v47, v0
	v_mov_b32_e32 v49, v0
	v_mov_b32_e32 v50, v0
	v_mov_b32_e32 v51, v0
	v_mov_b32_e32 v52, v0
	v_mov_b32_e32 v53, v0
	v_mov_b32_e32 v54, v0
	v_mov_b32_e32 v55, v0
	v_mov_b32_e32 v64, v0
	v_mov_b32_e32 v65, v0
	v_mov_b32_e32 v66, v0
	v_mov_b32_e32 v67, v0
	v_mov_b32_e32 v76, v0
	v_mov_b32_e32 v77, v0
	v_mov_b32_e32 v78, v0
	v_mov_b32_e32 v79, v0
	v_mov_b32_e32 v88, v0
	v_mov_b32_e32 v89, v0
	v_mov_b32_e32 v90, v0
	v_mov_b32_e32 v91, v0
	v_mov_b32_e32 v100, v0
	v_mov_b32_e32 v101, v0
	v_mov_b32_e32 v102, v0
	v_mov_b32_e32 v103, v0
	v_mov_b32_e32 v112, v0
	v_mov_b32_e32 v113, v0
	v_mov_b32_e32 v114, v0
	v_mov_b32_e32 v115, v0
	v_mov_b32_e32 v60, v0
	v_mov_b32_e32 v61, v0
	v_mov_b32_e32 v62, v0
	v_mov_b32_e32 v63, v0
	v_mov_b32_e32 v72, v0
	v_mov_b32_e32 v73, v0
	v_mov_b32_e32 v74, v0
	v_mov_b32_e32 v75, v0
	v_mov_b32_e32 v84, v0
	v_mov_b32_e32 v85, v0
	v_mov_b32_e32 v86, v0
	v_mov_b32_e32 v87, v0
	v_mov_b32_e32 v96, v0
	v_mov_b32_e32 v97, v0
	v_mov_b32_e32 v98, v0
	v_mov_b32_e32 v99, v0
	v_mov_b32_e32 v108, v0
	v_mov_b32_e32 v109, v0
	v_mov_b32_e32 v110, v0
	v_mov_b32_e32 v111, v0
	v_mov_b32_e32 v120, v0
	v_mov_b32_e32 v121, v0
	v_mov_b32_e32 v122, v0
	v_mov_b32_e32 v123, v0
	v_mov_b32_e32 v128, v0
	v_mov_b32_e32 v129, v0
	v_mov_b32_e32 v130, v0
	v_mov_b32_e32 v131, v0
	v_mov_b32_e32 v136, v0
	v_mov_b32_e32 v137, v0
	v_mov_b32_e32 v138, v0
	v_mov_b32_e32 v139, v0
	v_mov_b32_e32 v92, v0
	v_mov_b32_e32 v93, v0
	v_mov_b32_e32 v94, v0
	v_mov_b32_e32 v95, v0
	v_mov_b32_e32 v104, v0
	v_mov_b32_e32 v105, v0
	v_mov_b32_e32 v106, v0
	v_mov_b32_e32 v107, v0
	v_mov_b32_e32 v116, v0
	v_mov_b32_e32 v117, v0
	v_mov_b32_e32 v118, v0
	v_mov_b32_e32 v119, v0
	v_mov_b32_e32 v124, v0
	v_mov_b32_e32 v125, v0
	v_mov_b32_e32 v126, v0
	v_mov_b32_e32 v127, v0
	v_mov_b32_e32 v132, v0
	v_mov_b32_e32 v133, v0
	v_mov_b32_e32 v134, v0
	v_mov_b32_e32 v135, v0
	v_mov_b32_e32 v140, v0
	v_mov_b32_e32 v141, v0
	v_mov_b32_e32 v142, v0
	v_mov_b32_e32 v143, v0
	v_mov_b32_e32 v144, v0
	v_mov_b32_e32 v145, v0
	v_mov_b32_e32 v146, v0
	v_mov_b32_e32 v147, v0
	v_mov_b32_e32 v148, v0
	v_mov_b32_e32 v149, v0
	v_mov_b32_e32 v150, v0
	v_mov_b32_e32 v151, v0
	v_lshl_add_u32 v228, v168, 1, v166
	v_lshl_add_u32 v152, v165, 1, v166
	v_add_u32_e32 v194, v167, v162
	v_add_u32_e32 v195, v194, v167
; DI f32x4 mfma16(bf16x8 a, bf16x8 b, f32x4 c) { return __builtin_amdgcn_mfma_f32_16x16x32_bf16(a, b, c, 0, 0, 0); }
; template <int NI, class XL, class EP>
; DI void gemm_tile(const u16* __restrict__ W, int ldw, int f0, int t0, int K, XL xl, EP ep, unsigned char* smem) {
;     ...
;   for (int it = 0; it < nk; ++it) {
;     const u16* Ws = S0 + (it & 1) * BUF; const u16* Xs = Ws + 128 * LST;
;     __builtin_amdgcn_s_setprio(1);
;     bf16x8 a[4];
; #pragma unroll
;     for (int mi = 0; mi < 4; ++mi) a[mi] = *(const bf16x8*)(Ws + (wf * 64 + mi * 16 + lr) * LST + lq * 8);
; #pragma unroll
;     for (int ni = 0; ni < NI; ++ni) {
;       const bf16x8 b = *(const bf16x8*)(Xs + (wt * (NI * 16) + ni * 16 + lr) * LST + lq * 8);
; #pragma unroll
;       for (int mi = 0; mi < 4; ++mi) acc[mi][ni] = mfma16(a[mi], b, acc[mi][ni]);
;     }
;     __builtin_amdgcn_sched_group_barrier(0x100, 6, 0);
; #pragma unroll
;     for (int ni = 0; ni < NI; ++ni) { __builtin_amdgcn_sched_group_barrier(0x008, 4, 0); if (ni + 2 < NI) __builtin_amdgcn_sched_group_barrier(0x100, 1, 0); }
;     __builtin_amdgcn_s_setprio(0);
;     if (it + 1 < nk) lstore((it + 1) & 1);
;     if (it + 2 < nk) gload(it + 2);
;     __syncthreads();
.LBB0_269:
	s_setprio 1
	ds_read_b128 v[170:173], v228 offset:0
	ds_read_b128 v[174:177], v228 offset:1536
	ds_read_b128 v[182:185], v228 offset:3072
	ds_read_b128 v[186:189], v228 offset:4608
	ds_read_b128 v[178:181], v152 offset:12288
	ds_read_b128 v[190:193], v152 offset:13824
	s_waitcnt lgkmcnt(1)
	v_mfma_f32_16x16x32_bf16 v[148:151], v[170:173], v[178:181], v[148:151]
	v_mfma_f32_16x16x32_bf16 v[136:139], v[174:177], v[178:181], v[136:139]
	v_mfma_f32_16x16x32_bf16 v[112:115], v[182:185], v[178:181], v[112:115]
	v_mfma_f32_16x16x32_bf16 v[80:83], v[186:189], v[178:181], v[80:83]
	ds_read_b128 v[178:181], v152 offset:15360
	s_waitcnt vmcnt(6)
	ds_write_b128 v194, v[20:23] offset:36864
	s_waitcnt lgkmcnt(2)
	v_mfma_f32_16x16x32_bf16 v[144:147], v[170:173], v[190:193], v[144:147]
	v_mfma_f32_16x16x32_bf16 v[128:131], v[174:177], v[190:193], v[128:131]
	v_mfma_f32_16x16x32_bf16 v[100:103], v[182:185], v[190:193], v[100:103]
	v_mfma_f32_16x16x32_bf16 v[68:71], v[186:189], v[190:193], v[68:71]
	ds_read_b128 v[190:193], v152 offset:16896
	ds_write_b128 v194, v[16:19] offset:36960
	global_load_dwordx4 v[20:23], v154, s[98:99]
	global_load_dwordx4 v[16:19], v154, s[98:99] offset:64
	s_waitcnt lgkmcnt(3)
	v_mfma_f32_16x16x32_bf16 v[140:143], v[170:173], v[178:181], v[140:143]
	v_mfma_f32_16x16x32_bf16 v[120:123], v[174:177], v[178:181], v[120:123]
	v_mfma_f32_16x16x32_bf16 v[88:91], v[182:185], v[178:181], v[88:91]
	v_mfma_f32_16x16x32_bf16 v[56:59], v[186:189], v[178:181], v[56:59]
	ds_read_b128 v[178:181], v152 offset:18432
	ds_write_b128 v195, v[36:39] offset:49152
	global_load_dwordx4 v[36:39], v156, s[100:101] offset:2048
	s_waitcnt lgkmcnt(3)
	v_mfma_f32_16x16x32_bf16 v[132:135], v[170:173], v[190:193], v[132:135]
	v_mfma_f32_16x16x32_bf16 v[108:111], v[174:177], v[190:193], v[108:111]
	v_mfma_f32_16x16x32_bf16 v[76:79], v[182:185], v[190:193], v[76:79]
	v_mfma_f32_16x16x32_bf16 v[40:43], v[186:189], v[190:193], v[40:43]
	ds_read_b128 v[190:193], v152 offset:19968
	ds_write_b128 v195, v[32:35] offset:49248
	global_load_dwordx4 v[32:35], v156, s[100:101] offset:2112
	s_waitcnt lgkmcnt(3)
	v_mfma_f32_16x16x32_bf16 v[124:127], v[170:173], v[178:181], v[124:127]
	v_mfma_f32_16x16x32_bf16 v[96:99], v[174:177], v[178:181], v[96:99]
	v_mfma_f32_16x16x32_bf16 v[64:67], v[182:185], v[178:181], v[64:67]
	v_mfma_f32_16x16x32_bf16 v[12:15], v[186:189], v[178:181], v[12:15]
	ds_read_b128 v[178:181], v152 offset:21504
	ds_write_b128 v195, v[28:31] offset:49344
	global_load_dwordx4 v[28:31], v156, s[100:101] offset:2176
	s_waitcnt lgkmcnt(3)
	v_mfma_f32_16x16x32_bf16 v[116:119], v[170:173], v[190:193], v[116:119]
	v_mfma_f32_16x16x32_bf16 v[84:87], v[174:177], v[190:193], v[84:87]
	v_mfma_f32_16x16x32_bf16 v[52:55], v[182:185], v[190:193], v[52:55]
	v_mfma_f32_16x16x32_bf16 v[8:11], v[186:189], v[190:193], v[8:11]
	ds_read_b128 v[190:193], v152 offset:23040
	ds_write_b128 v195, v[24:27] offset:49440
	global_load_dwordx4 v[24:27], v156, s[100:101] offset:2240
	s_waitcnt lgkmcnt(3)
	v_mfma_f32_16x16x32_bf16 v[104:107], v[170:173], v[178:181], v[104:107]
	v_mfma_f32_16x16x32_bf16 v[72:75], v[174:177], v[178:181], v[72:75]
	v_mfma_f32_16x16x32_bf16 v[48:51], v[182:185], v[178:181], v[48:51]
	v_mfma_f32_16x16x32_bf16 v[4:7], v[186:189], v[178:181], v[4:7]
	s_add_u32 s98, s98, s4
	s_addc_u32 s99, s99, s5
	s_add_u32 s100, s100, s14
	s_addc_u32 s101, s101, s15
	s_waitcnt lgkmcnt(1)
	v_mfma_f32_16x16x32_bf16 v[92:95], v[170:173], v[190:193], v[92:95]
	v_mfma_f32_16x16x32_bf16 v[60:63], v[174:177], v[190:193], v[60:63]
	v_mfma_f32_16x16x32_bf16 v[44:47], v[182:185], v[190:193], v[44:47]
	v_mfma_f32_16x16x32_bf16 v[0:3], v[186:189], v[190:193], v[0:3]
	s_setprio 0
	s_waitcnt lgkmcnt(0)
	s_barrier
	s_setprio 1
	ds_read_b128 v[170:173], v228 offset:36864
	ds_read_b128 v[174:177], v228 offset:38400
	ds_read_b128 v[182:185], v228 offset:39936
	ds_read_b128 v[186:189], v228 offset:41472
	ds_read_b128 v[178:181], v152 offset:49152
	ds_read_b128 v[190:193], v152 offset:50688
	s_waitcnt lgkmcnt(1)
	v_mfma_f32_16x16x32_bf16 v[148:151], v[170:173], v[178:181], v[148:151]
	v_mfma_f32_16x16x32_bf16 v[136:139], v[174:177], v[178:181], v[136:139]
	v_mfma_f32_16x16x32_bf16 v[112:115], v[182:185], v[178:181], v[112:115]
	v_mfma_f32_16x16x32_bf16 v[80:83], v[186:189], v[178:181], v[80:83]
	ds_read_b128 v[178:181], v152 offset:52224
	s_waitcnt vmcnt(6)
	ds_write_b128 v194, v[200:203] offset:0
	s_waitcnt lgkmcnt(2)
	v_mfma_f32_16x16x32_bf16 v[144:147], v[170:173], v[190:193], v[144:147]
	v_mfma_f32_16x16x32_bf16 v[128:131], v[174:177], v[190:193], v[128:131]
	v_mfma_f32_16x16x32_bf16 v[100:103], v[182:185], v[190:193], v[100:103]
	v_mfma_f32_16x16x32_bf16 v[68:71], v[186:189], v[190:193], v[68:71]
	ds_read_b128 v[190:193], v152 offset:53760
	ds_write_b128 v194, v[204:207] offset:96
	global_load_dwordx4 v[200:203], v154, s[98:99]
	global_load_dwordx4 v[204:207], v154, s[98:99] offset:64
	s_waitcnt lgkmcnt(3)
	v_mfma_f32_16x16x32_bf16 v[140:143], v[170:173], v[178:181], v[140:143]
	v_mfma_f32_16x16x32_bf16 v[120:123], v[174:177], v[178:181], v[120:123]
	v_mfma_f32_16x16x32_bf16 v[88:91], v[182:185], v[178:181], v[88:91]
	v_mfma_f32_16x16x32_bf16 v[56:59], v[186:189], v[178:181], v[56:59]
	ds_read_b128 v[178:181], v152 offset:55296
	ds_write_b128 v195, v[208:211] offset:12288
	global_load_dwordx4 v[208:211], v156, s[100:101] offset:2048
	s_waitcnt lgkmcnt(3)
; DI f32x4 mfma16(bf16x8 a, bf16x8 b, f32x4 c) { return __builtin_amdgcn_mfma_f32_16x16x32_bf16(a, b, c, 0, 0, 0); }
; template <int NI, class XL, class EP>
; DI void gemm_tile(const u16* __restrict__ W, int ldw, int f0, int t0, int K, XL xl, EP ep, unsigned char* smem) {
;     ...
;   for (int it = 0; it < nk; ++it) {
;     const u16* Ws = S0 + (it & 1) * BUF; const u16* Xs = Ws + 128 * LST;
;     __builtin_amdgcn_s_setprio(1);
;     bf16x8 a[4];
; #pragma unroll
;     for (int mi = 0; mi < 4; ++mi) a[mi] = *(const bf16x8*)(Ws + (wf * 64 + mi * 16 + lr) * LST + lq * 8);
; #pragma unroll
;     for (int ni = 0; ni < NI; ++ni) {
;       const bf16x8 b = *(const bf16x8*)(Xs + (wt * (NI * 16) + ni * 16 + lr) * LST + lq * 8);
; #pragma unroll
;       for (int mi = 0; mi < 4; ++mi) acc[mi][ni] = mfma16(a[mi], b, acc[mi][ni]);
;     }
;     __builtin_amdgcn_sched_group_barrier(0x100, 6, 0);
; #pragma unroll
;     for (int ni = 0; ni < NI; ++ni) { __builtin_amdgcn_sched_group_barrier(0x008, 4, 0); if (ni + 2 < NI) __builtin_amdgcn_sched_group_barrier(0x100, 1, 0); }
;     __builtin_amdgcn_s_setprio(0);
;     if (it + 1 < nk) lstore((it + 1) & 1);
;     if (it + 2 < nk) gload(it + 2);
;     __syncthreads();
	v_mfma_f32_16x16x32_bf16 v[132:135], v[170:173], v[190:193], v[132:135]
	v_mfma_f32_16x16x32_bf16 v[108:111], v[174:177], v[190:193], v[108:111]
	v_mfma_f32_16x16x32_bf16 v[76:79], v[182:185], v[190:193], v[76:79]
	v_mfma_f32_16x16x32_bf16 v[40:43], v[186:189], v[190:193], v[40:43]
	ds_read_b128 v[190:193], v152 offset:56832
	ds_write_b128 v195, v[212:215] offset:12384
	global_load_dwordx4 v[212:215], v156, s[100:101] offset:2112
	s_waitcnt lgkmcnt(3)
	v_mfma_f32_16x16x32_bf16 v[124:127], v[170:173], v[178:181], v[124:127]
	v_mfma_f32_16x16x32_bf16 v[96:99], v[174:177], v[178:181], v[96:99]
	v_mfma_f32_16x16x32_bf16 v[64:67], v[182:185], v[178:181], v[64:67]
	v_mfma_f32_16x16x32_bf16 v[12:15], v[186:189], v[178:181], v[12:15]
	ds_read_b128 v[178:181], v152 offset:58368
	ds_write_b128 v195, v[220:223] offset:12480
	global_load_dwordx4 v[220:223], v156, s[100:101] offset:2176
	s_waitcnt lgkmcnt(3)
	v_mfma_f32_16x16x32_bf16 v[116:119], v[170:173], v[190:193], v[116:119]
	v_mfma_f32_16x16x32_bf16 v[84:87], v[174:177], v[190:193], v[84:87]
	v_mfma_f32_16x16x32_bf16 v[52:55], v[182:185], v[190:193], v[52:55]
	v_mfma_f32_16x16x32_bf16 v[8:11], v[186:189], v[190:193], v[8:11]
	ds_read_b128 v[190:193], v152 offset:59904
	ds_write_b128 v195, v[224:227] offset:12576
	global_load_dwordx4 v[224:227], v156, s[100:101] offset:2240
	s_waitcnt lgkmcnt(3)
	v_mfma_f32_16x16x32_bf16 v[104:107], v[170:173], v[178:181], v[104:107]
	v_mfma_f32_16x16x32_bf16 v[72:75], v[174:177], v[178:181], v[72:75]
	v_mfma_f32_16x16x32_bf16 v[48:51], v[182:185], v[178:181], v[48:51]
	v_mfma_f32_16x16x32_bf16 v[4:7], v[186:189], v[178:181], v[4:7]
	s_add_u32 s98, s98, s4
	s_addc_u32 s99, s99, s5
	s_add_u32 s100, s100, s14
	s_addc_u32 s101, s101, s15
	s_add_i32 s22, s22, 2
	s_waitcnt lgkmcnt(1)
	v_mfma_f32_16x16x32_bf16 v[92:95], v[170:173], v[190:193], v[92:95]
	v_mfma_f32_16x16x32_bf16 v[60:63], v[174:177], v[190:193], v[60:63]
	v_mfma_f32_16x16x32_bf16 v[44:47], v[182:185], v[190:193], v[44:47]
	v_mfma_f32_16x16x32_bf16 v[0:3], v[186:189], v[190:193], v[0:3]
	s_setprio 0
	s_cmp_eq_u32 s22, 29
	s_waitcnt lgkmcnt(0)
	s_barrier
	s_cbranch_scc0 .LBB0_269
	s_setprio 1
	ds_read_b128 v[170:173], v228 offset:0
	ds_read_b128 v[174:177], v228 offset:1536
	ds_read_b128 v[182:185], v228 offset:3072
	ds_read_b128 v[186:189], v228 offset:4608
	ds_read_b128 v[178:181], v152 offset:12288
	ds_read_b128 v[190:193], v152 offset:13824
	s_waitcnt lgkmcnt(1)
	v_mfma_f32_16x16x32_bf16 v[148:151], v[170:173], v[178:181], v[148:151]
	v_mfma_f32_16x16x32_bf16 v[136:139], v[174:177], v[178:181], v[136:139]
	v_mfma_f32_16x16x32_bf16 v[112:115], v[182:185], v[178:181], v[112:115]
	v_mfma_f32_16x16x32_bf16 v[80:83], v[186:189], v[178:181], v[80:83]
	ds_read_b128 v[178:181], v152 offset:15360
	s_waitcnt vmcnt(6)
	ds_write_b128 v194, v[20:23] offset:36864
	s_waitcnt lgkmcnt(2)
	v_mfma_f32_16x16x32_bf16 v[144:147], v[170:173], v[190:193], v[144:147]
	v_mfma_f32_16x16x32_bf16 v[128:131], v[174:177], v[190:193], v[128:131]
	v_mfma_f32_16x16x32_bf16 v[100:103], v[182:185], v[190:193], v[100:103]
	v_mfma_f32_16x16x32_bf16 v[68:71], v[186:189], v[190:193], v[68:71]
	ds_read_b128 v[190:193], v152 offset:16896
	ds_write_b128 v194, v[16:19] offset:36960
	global_load_dwordx4 v[20:23], v154, s[98:99]
	global_load_dwordx4 v[16:19], v154, s[98:99] offset:64
	s_waitcnt lgkmcnt(3)
	v_mfma_f32_16x16x32_bf16 v[140:143], v[170:173], v[178:181], v[140:143]
	v_mfma_f32_16x16x32_bf16 v[120:123], v[174:177], v[178:181], v[120:123]
	v_mfma_f32_16x16x32_bf16 v[88:91], v[182:185], v[178:181], v[88:91]
	v_mfma_f32_16x16x32_bf16 v[56:59], v[186:189], v[178:181], v[56:59]
	ds_read_b128 v[178:181], v152 offset:18432
	ds_write_b128 v195, v[36:39] offset:49152
	global_load_dwordx4 v[36:39], v156, s[100:101] offset:2048
	s_waitcnt lgkmcnt(3)
	v_mfma_f32_16x16x32_bf16 v[132:135], v[170:173], v[190:193], v[132:135]
	v_mfma_f32_16x16x32_bf16 v[108:111], v[174:177], v[190:193], v[108:111]
	v_mfma_f32_16x16x32_bf16 v[76:79], v[182:185], v[190:193], v[76:79]
	v_mfma_f32_16x16x32_bf16 v[40:43], v[186:189], v[190:193], v[40:43]
	ds_read_b128 v[190:193], v152 offset:19968
	ds_write_b128 v195, v[32:35] offset:49248
	global_load_dwordx4 v[32:35], v156, s[100:101] offset:2112
	s_waitcnt lgkmcnt(3)
	v_mfma_f32_16x16x32_bf16 v[124:127], v[170:173], v[178:181], v[124:127]
	v_mfma_f32_16x16x32_bf16 v[96:99], v[174:177], v[178:181], v[96:99]
	v_mfma_f32_16x16x32_bf16 v[64:67], v[182:185], v[178:181], v[64:67]
	v_mfma_f32_16x16x32_bf16 v[12:15], v[186:189], v[178:181], v[12:15]
	ds_read_b128 v[178:181], v152 offset:21504
	ds_write_b128 v195, v[28:31] offset:49344
	global_load_dwordx4 v[28:31], v156, s[100:101] offset:2176
	s_waitcnt lgkmcnt(3)
	v_mfma_f32_16x16x32_bf16 v[116:119], v[170:173], v[190:193], v[116:119]
	v_mfma_f32_16x16x32_bf16 v[84:87], v[174:177], v[190:193], v[84:87]
	v_mfma_f32_16x16x32_bf16 v[52:55], v[182:185], v[190:193], v[52:55]
	v_mfma_f32_16x16x32_bf16 v[8:11], v[186:189], v[190:193], v[8:11]
	ds_read_b128 v[190:193], v152 offset:23040
	ds_write_b128 v195, v[24:27] offset:49440
	global_load_dwordx4 v[24:27], v156, s[100:101] offset:2240
	s_waitcnt lgkmcnt(3)
	v_mfma_f32_16x16x32_bf16 v[104:107], v[170:173], v[178:181], v[104:107]
	v_mfma_f32_16x16x32_bf16 v[72:75], v[174:177], v[178:181], v[72:75]
	v_mfma_f32_16x16x32_bf16 v[48:51], v[182:185], v[178:181], v[48:51]
	v_mfma_f32_16x16x32_bf16 v[4:7], v[186:189], v[178:181], v[4:7]
	s_add_u32 s98, s98, s4
	s_addc_u32 s99, s99, s5
	s_add_u32 s100, s100, s14
	s_addc_u32 s101, s101, s15
	s_waitcnt lgkmcnt(1)
	v_mfma_f32_16x16x32_bf16 v[92:95], v[170:173], v[190:193], v[92:95]
	v_mfma_f32_16x16x32_bf16 v[60:63], v[174:177], v[190:193], v[60:63]
	v_mfma_f32_16x16x32_bf16 v[44:47], v[182:185], v[190:193], v[44:47]
	v_mfma_f32_16x16x32_bf16 v[0:3], v[186:189], v[190:193], v[0:3]
	s_setprio 0
	s_waitcnt lgkmcnt(0)
	s_barrier
; DI f32x4 mfma16(bf16x8 a, bf16x8 b, f32x4 c) { return __builtin_amdgcn_mfma_f32_16x16x32_bf16(a, b, c, 0, 0, 0); }
; template <int NI, class XL, class EP>
; DI void gemm_tile(const u16* __restrict__ W, int ldw, int f0, int t0, int K, XL xl, EP ep, unsigned char* smem) {
;     ...
;   for (int it = 0; it < nk; ++it) {
;     const u16* Ws = S0 + (it & 1) * BUF; const u16* Xs = Ws + 128 * LST;
;     __builtin_amdgcn_s_setprio(1);
;     bf16x8 a[4];
; #pragma unroll
;     for (int mi = 0; mi < 4; ++mi) a[mi] = *(const bf16x8*)(Ws + (wf * 64 + mi * 16 + lr) * LST + lq * 8);
; #pragma unroll
;     for (int ni = 0; ni < NI; ++ni) {
;       const bf16x8 b = *(const bf16x8*)(Xs + (wt * (NI * 16) + ni * 16 + lr) * LST + lq * 8);
; #pragma unroll
;       for (int mi = 0; mi < 4; ++mi) acc[mi][ni] = mfma16(a[mi], b, acc[mi][ni]);
;     }
;     __builtin_amdgcn_sched_group_barrier(0x100, 6, 0);
; #pragma unroll
;     for (int ni = 0; ni < NI; ++ni) { __builtin_amdgcn_sched_group_barrier(0x008, 4, 0); if (ni + 2 < NI) __builtin_amdgcn_sched_group_barrier(0x100, 1, 0); }
;     __builtin_amdgcn_s_setprio(0);
;     if (it + 1 < nk) lstore((it + 1) & 1);
;     if (it + 2 < nk) gload(it + 2);
;     __syncthreads();
	s_setprio 1
	ds_read_b128 v[170:173], v228 offset:36864
	ds_read_b128 v[174:177], v228 offset:38400
	ds_read_b128 v[182:185], v228 offset:39936
	ds_read_b128 v[186:189], v228 offset:41472
	ds_read_b128 v[178:181], v152 offset:49152
	ds_read_b128 v[190:193], v152 offset:50688
	s_waitcnt lgkmcnt(1)
	v_mfma_f32_16x16x32_bf16 v[148:151], v[170:173], v[178:181], v[148:151]
	v_mfma_f32_16x16x32_bf16 v[136:139], v[174:177], v[178:181], v[136:139]
	v_mfma_f32_16x16x32_bf16 v[112:115], v[182:185], v[178:181], v[112:115]
	v_mfma_f32_16x16x32_bf16 v[80:83], v[186:189], v[178:181], v[80:83]
	ds_read_b128 v[178:181], v152 offset:52224
	s_waitcnt vmcnt(6)
	ds_write_b128 v194, v[200:203] offset:0
	s_waitcnt lgkmcnt(2)
	v_mfma_f32_16x16x32_bf16 v[144:147], v[170:173], v[190:193], v[144:147]
	v_mfma_f32_16x16x32_bf16 v[128:131], v[174:177], v[190:193], v[128:131]
	v_mfma_f32_16x16x32_bf16 v[100:103], v[182:185], v[190:193], v[100:103]
	v_mfma_f32_16x16x32_bf16 v[68:71], v[186:189], v[190:193], v[68:71]
	ds_read_b128 v[190:193], v152 offset:53760
	ds_write_b128 v194, v[204:207] offset:96
	s_waitcnt lgkmcnt(3)
	v_mfma_f32_16x16x32_bf16 v[140:143], v[170:173], v[178:181], v[140:143]
	v_mfma_f32_16x16x32_bf16 v[120:123], v[174:177], v[178:181], v[120:123]
	v_mfma_f32_16x16x32_bf16 v[88:91], v[182:185], v[178:181], v[88:91]
	v_mfma_f32_16x16x32_bf16 v[56:59], v[186:189], v[178:181], v[56:59]
	ds_read_b128 v[178:181], v152 offset:55296
	ds_write_b128 v195, v[208:211] offset:12288
	s_waitcnt lgkmcnt(3)
	v_mfma_f32_16x16x32_bf16 v[132:135], v[170:173], v[190:193], v[132:135]
	v_mfma_f32_16x16x32_bf16 v[108:111], v[174:177], v[190:193], v[108:111]
	v_mfma_f32_16x16x32_bf16 v[76:79], v[182:185], v[190:193], v[76:79]
	v_mfma_f32_16x16x32_bf16 v[40:43], v[186:189], v[190:193], v[40:43]
	ds_read_b128 v[190:193], v152 offset:56832
	ds_write_b128 v195, v[212:215] offset:12384
	s_waitcnt lgkmcnt(3)
	v_mfma_f32_16x16x32_bf16 v[124:127], v[170:173], v[178:181], v[124:127]
	v_mfma_f32_16x16x32_bf16 v[96:99], v[174:177], v[178:181], v[96:99]
	v_mfma_f32_16x16x32_bf16 v[64:67], v[182:185], v[178:181], v[64:67]
	v_mfma_f32_16x16x32_bf16 v[12:15], v[186:189], v[178:181], v[12:15]
	ds_read_b128 v[178:181], v152 offset:58368
	ds_write_b128 v195, v[220:223] offset:12480
	s_waitcnt lgkmcnt(3)
	v_mfma_f32_16x16x32_bf16 v[116:119], v[170:173], v[190:193], v[116:119]
	v_mfma_f32_16x16x32_bf16 v[84:87], v[174:177], v[190:193], v[84:87]
	v_mfma_f32_16x16x32_bf16 v[52:55], v[182:185], v[190:193], v[52:55]
	v_mfma_f32_16x16x32_bf16 v[8:11], v[186:189], v[190:193], v[8:11]
	ds_read_b128 v[190:193], v152 offset:59904
	ds_write_b128 v195, v[224:227] offset:12576
	s_waitcnt lgkmcnt(3)
	v_mfma_f32_16x16x32_bf16 v[104:107], v[170:173], v[178:181], v[104:107]
	v_mfma_f32_16x16x32_bf16 v[72:75], v[174:177], v[178:181], v[72:75]
	v_mfma_f32_16x16x32_bf16 v[48:51], v[182:185], v[178:181], v[48:51]
	v_mfma_f32_16x16x32_bf16 v[4:7], v[186:189], v[178:181], v[4:7]
	s_add_i32 s22, s22, 2
	s_waitcnt lgkmcnt(1)
	v_mfma_f32_16x16x32_bf16 v[92:95], v[170:173], v[190:193], v[92:95]
	v_mfma_f32_16x16x32_bf16 v[60:63], v[174:177], v[190:193], v[60:63]
	v_mfma_f32_16x16x32_bf16 v[44:47], v[182:185], v[190:193], v[44:47]
	v_mfma_f32_16x16x32_bf16 v[0:3], v[186:189], v[190:193], v[0:3]
	s_setprio 0
	s_waitcnt lgkmcnt(0)
	s_barrier
	s_setprio 1
	v_lshl_add_u32 v152, v168, 1, v166
	ds_read_b128 v[154:157], v152
	v_lshl_add_u32 v228, v165, 1, v166
	ds_read_b128 v[166:169], v152 offset:1536
	ds_read_b128 v[174:177], v152 offset:3072
	ds_read_b128 v[178:181], v152 offset:4608
	ds_read_b128 v[170:173], v228 offset:12288
	ds_read_b128 v[182:185], v228 offset:13824
	s_waitcnt lgkmcnt(1)
	v_mfma_f32_16x16x32_bf16 v[148:151], v[154:157], v[170:173], v[148:151]
	v_mfma_f32_16x16x32_bf16 v[136:139], v[166:169], v[170:173], v[136:139]
	v_mfma_f32_16x16x32_bf16 v[112:115], v[174:177], v[170:173], v[112:115]
	v_mfma_f32_16x16x32_bf16 v[170:173], v[178:181], v[170:173], v[80:83]
	s_nop 2
	ds_read_b128 v[80:83], v228 offset:15360
	s_waitcnt lgkmcnt(1)
	v_mfma_f32_16x16x32_bf16 v[144:147], v[154:157], v[182:185], v[144:147]
	v_mfma_f32_16x16x32_bf16 v[128:131], v[166:169], v[182:185], v[128:131]
	v_mfma_f32_16x16x32_bf16 v[100:103], v[174:177], v[182:185], v[100:103]
	v_mfma_f32_16x16x32_bf16 v[68:71], v[178:181], v[182:185], v[68:71]
	ds_read_b128 v[182:185], v228 offset:16896
	s_waitcnt lgkmcnt(1)
	v_mfma_f32_16x16x32_bf16 v[140:143], v[154:157], v[80:83], v[140:143]
	v_mfma_f32_16x16x32_bf16 v[186:189], v[166:169], v[80:83], v[120:123]
	v_mfma_f32_16x16x32_bf16 v[88:91], v[174:177], v[80:83], v[88:91]
	v_mfma_f32_16x16x32_bf16 v[56:59], v[178:181], v[80:83], v[56:59]
	ds_read_b128 v[80:83], v228 offset:18432
	s_waitcnt lgkmcnt(1)
	v_mfma_f32_16x16x32_bf16 v[132:135], v[154:157], v[182:185], v[132:135]
	v_mfma_f32_16x16x32_bf16 v[108:111], v[166:169], v[182:185], v[108:111]
	v_mfma_f32_16x16x32_bf16 v[76:79], v[174:177], v[182:185], v[76:79]
	v_mfma_f32_16x16x32_bf16 v[182:185], v[178:181], v[182:185], v[40:43]
	s_nop 2
	ds_read_b128 v[40:43], v228 offset:19968
	s_waitcnt lgkmcnt(1)
	v_mfma_f32_16x16x32_bf16 v[190:193], v[154:157], v[80:83], v[124:127]
	v_mfma_f32_16x16x32_bf16 v[96:99], v[166:169], v[80:83], v[96:99]
	v_mfma_f32_16x16x32_bf16 v[194:197], v[174:177], v[80:83], v[64:67]
	v_mfma_f32_16x16x32_bf16 v[198:201], v[178:181], v[80:83], v[12:15]
	s_nop 2
	ds_read_b128 v[12:15], v228 offset:21504
	s_waitcnt lgkmcnt(1)
	v_mfma_f32_16x16x32_bf16 v[202:205], v[154:157], v[40:43], v[116:119]
	v_mfma_f32_16x16x32_bf16 v[84:87], v[166:169], v[40:43], v[84:87]
	v_mfma_f32_16x16x32_bf16 v[52:55], v[174:177], v[40:43], v[52:55]
	v_mfma_f32_16x16x32_bf16 v[206:209], v[178:181], v[40:43], v[8:11]
	s_nop 2
	ds_read_b128 v[8:11], v228 offset:23040
	s_waitcnt lgkmcnt(1)
	v_mfma_f32_16x16x32_bf16 v[210:213], v[154:157], v[12:15], v[104:107]
	v_mfma_f32_16x16x32_bf16 v[214:217], v[166:169], v[12:15], v[72:75]
	v_mfma_f32_16x16x32_bf16 v[220:223], v[174:177], v[12:15], v[48:51]
	v_mfma_f32_16x16x32_bf16 v[224:227], v[178:181], v[12:15], v[4:7]
	s_waitcnt lgkmcnt(0)
	v_mfma_f32_16x16x32_bf16 v[92:95], v[154:157], v[8:11], v[92:95]
	v_mfma_f32_16x16x32_bf16 v[60:63], v[166:169], v[8:11], v[60:63]
	v_mfma_f32_16x16x32_bf16 v[154:157], v[174:177], v[8:11], v[44:47]
	v_mfma_f32_16x16x32_bf16 v[166:169], v[178:181], v[8:11], v[0:3]
	s_setprio 0
	s_waitcnt vmcnt(5)
	ds_write_b128 v163, v[20:23] offset:36864
	s_waitcnt vmcnt(4)
	ds_write_b128 v163, v[16:19] offset:36960
	s_waitcnt vmcnt(3)
	ds_write_b128 v164, v[36:39] offset:49152
	s_waitcnt vmcnt(2)
	ds_write_b128 v164, v[32:35] offset:49248
	s_waitcnt vmcnt(1)
	ds_write_b128 v164, v[28:31] offset:49344
	s_waitcnt vmcnt(0)
	ds_write_b128 v164, v[24:27] offset:49440
	s_waitcnt lgkmcnt(0)
	s_barrier
; DI f32x4 mfma16(bf16x8 a, bf16x8 b, f32x4 c) { return __builtin_amdgcn_mfma_f32_16x16x32_bf16(a, b, c, 0, 0, 0); }
; template <int NI, class XL, class EP>
; DI void gemm_tile(const u16* __restrict__ W, int ldw, int f0, int t0, int K, XL xl, EP ep, unsigned char* smem) {
;     ...
;   for (int it = 0; it < nk; ++it) {
;     const u16* Ws = S0 + (it & 1) * BUF; const u16* Xs = Ws + 128 * LST;
;     __builtin_amdgcn_s_setprio(1);
;     bf16x8 a[4];
; #pragma unroll
;     for (int mi = 0; mi < 4; ++mi) a[mi] = *(const bf16x8*)(Ws + (wf * 64 + mi * 16 + lr) * LST + lq * 8);
; #pragma unroll
;     for (int ni = 0; ni < NI; ++ni) {
;       const bf16x8 b = *(const bf16x8*)(Xs + (wt * (NI * 16) + ni * 16 + lr) * LST + lq * 8);
; #pragma unroll
;       for (int mi = 0; mi < 4; ++mi) acc[mi][ni] = mfma16(a[mi], b, acc[mi][ni]);
;     }
;     __builtin_amdgcn_sched_group_barrier(0x100, 6, 0);
; #pragma unroll
;     for (int ni = 0; ni < NI; ++ni) { __builtin_amdgcn_sched_group_barrier(0x008, 4, 0); if (ni + 2 < NI) __builtin_amdgcn_sched_group_barrier(0x100, 1, 0); }
;     __builtin_amdgcn_s_setprio(0);
;     if (it + 1 < nk) lstore((it + 1) & 1);
;     if (it + 2 < nk) gload(it + 2);
;     __syncthreads();
;   }
; DI void phase1(const Params& p, const Sched& sched, unsigned char* smem) {
;     ...
;       u16* dst; int ld, cb;
;       if (tn < 8) { dst = (u16*)(p.ws + OFF_QB); ld = 1024; cb = 0; }
;       else if (tn < 12) { dst = (u16*)(p.ws + OFF_KVC); ld = 512; cb = 1024; }
;       else if (tn < 16) { dst = (u16*)(p.ws + OFF_KVS); ld = 512; cb = 1536; }
;       else if (tn < 20) { dst = (u16*)(p.ws + OFF_KVW); ld = 512; cb = 2048; }
;       else if (tn < 22) { dst = (u16*)(p.ws + OFF_MQ); ld = 256; cb = 2560; }
;       else if (tn < 24) { dst = (u16*)(p.ws + OFF_MKV); ld = 256; cb = 2816; }
;       else if (tn < 32) { dst = (u16*)(p.ws + OFF_MA); ld = 1024; cb = 3072; }
;       else { dst = (u16*)(p.ws + OFF_MB); ld = 1024; cb = 4096; }
	s_setprio 1
	ds_read_b128 v[36:39], v152 offset:36864
	ds_read_b128 v[162:165], v152 offset:38400
	ds_read_b128 v[174:177], v152 offset:39936
	ds_read_b128 v[178:181], v152 offset:41472
	ds_read_b128 v[0:3], v228 offset:49152
	ds_read_b128 v[4:7], v228 offset:50688
	s_waitcnt lgkmcnt(1)
	v_mfma_f32_16x16x32_bf16 v[124:127], v[36:39], v[0:3], v[148:151]
	v_mfma_f32_16x16x32_bf16 v[80:83], v[162:165], v[0:3], v[136:139]
	v_mfma_f32_16x16x32_bf16 v[28:31], v[174:177], v[0:3], v[112:115]
	v_mfma_f32_16x16x32_bf16 v[0:3], v[178:181], v[0:3], v[170:173]
	ds_read_b128 v[8:11], v228 offset:52224
	s_waitcnt lgkmcnt(1)
	v_mfma_f32_16x16x32_bf16 v[120:123], v[36:39], v[4:7], v[144:147]
	v_mfma_f32_16x16x32_bf16 v[72:75], v[162:165], v[4:7], v[128:131]
	v_mfma_f32_16x16x32_bf16 v[32:35], v[174:177], v[4:7], v[100:103]
	v_mfma_f32_16x16x32_bf16 v[4:7], v[178:181], v[4:7], v[68:71]
	ds_read_b128 v[12:15], v228 offset:53760
	s_waitcnt lgkmcnt(1)
	v_mfma_f32_16x16x32_bf16 v[116:119], v[36:39], v[8:11], v[140:143]
	v_mfma_f32_16x16x32_bf16 v[64:67], v[162:165], v[8:11], v[186:189]
	v_mfma_f32_16x16x32_bf16 v[40:43], v[174:177], v[8:11], v[88:91]
	v_mfma_f32_16x16x32_bf16 v[8:11], v[178:181], v[8:11], v[56:59]
	ds_read_b128 v[16:19], v228 offset:55296
	s_waitcnt lgkmcnt(1)
	v_mfma_f32_16x16x32_bf16 v[112:115], v[36:39], v[12:15], v[132:135]
	v_mfma_f32_16x16x32_bf16 v[68:71], v[162:165], v[12:15], v[108:111]
	v_mfma_f32_16x16x32_bf16 v[44:47], v[174:177], v[12:15], v[76:79]
	v_mfma_f32_16x16x32_bf16 v[12:15], v[178:181], v[12:15], v[182:185]
	ds_read_b128 v[20:23], v228 offset:56832
	s_waitcnt lgkmcnt(1)
	v_mfma_f32_16x16x32_bf16 v[108:111], v[36:39], v[16:19], v[190:193]
	v_mfma_f32_16x16x32_bf16 v[76:79], v[162:165], v[16:19], v[96:99]
	v_mfma_f32_16x16x32_bf16 v[48:51], v[174:177], v[16:19], v[194:197]
	v_mfma_f32_16x16x32_bf16 v[16:19], v[178:181], v[16:19], v[198:201]
	ds_read_b128 v[24:27], v228 offset:58368
	s_waitcnt lgkmcnt(1)
	v_mfma_f32_16x16x32_bf16 v[104:107], v[36:39], v[20:23], v[202:205]
	v_mfma_f32_16x16x32_bf16 v[84:87], v[162:165], v[20:23], v[84:87]
	v_mfma_f32_16x16x32_bf16 v[52:55], v[174:177], v[20:23], v[52:55]
	v_mfma_f32_16x16x32_bf16 v[20:23], v[178:181], v[20:23], v[206:209]
	ds_read_b128 v[128:131], v228 offset:59904
	s_waitcnt lgkmcnt(1)
	v_mfma_f32_16x16x32_bf16 v[100:103], v[36:39], v[24:27], v[210:213]
	v_mfma_f32_16x16x32_bf16 v[88:91], v[162:165], v[24:27], v[214:217]
	v_mfma_f32_16x16x32_bf16 v[56:59], v[174:177], v[24:27], v[220:223]
	v_mfma_f32_16x16x32_bf16 v[24:27], v[178:181], v[24:27], v[224:227]
	s_waitcnt lgkmcnt(0)
	v_mfma_f32_16x16x32_bf16 v[96:99], v[36:39], v[128:131], v[92:95]
	v_mfma_f32_16x16x32_bf16 v[92:95], v[162:165], v[128:131], v[60:63]
	v_mfma_f32_16x16x32_bf16 v[60:63], v[174:177], v[128:131], v[154:157]
	v_mfma_f32_16x16x32_bf16 v[36:39], v[178:181], v[128:131], v[166:169]
	s_setprio 0
	s_cmp_lt_i32 s61, 8
	s_barrier
	s_cbranch_scc1 .LBB0_275
	s_cmp_lt_u32 s61, 12
	s_cselect_b64 s[22:23], -1, 0
	s_or_b64 s[24:25], s[22:23], s[16:17]
	s_and_b64 s[22:23], s[22:23], exec
	s_cselect_b32 s22, s48, 0x17b00800
	s_cselect_b32 s62, s47, 0xfffffa00
	s_add_u32 s22, s42, s22
	s_addc_u32 s23, s43, 0
	s_and_b64 vcc, exec, s[24:25]
	s_cbranch_vccnz .LBB0_276
	s_cmp_lt_u32 s61, 20
	s_cbranch_scc1 .LBB0_277
	s_cmp_lt_u32 s61, 22
	s_cselect_b64 s[22:23], -1, 0
	s_or_b64 s[24:25], s[22:23], s[18:19]
	s_and_b64 s[22:23], s[22:23], exec
	s_cselect_b32 s22, s50, 0x21b00800
	s_cselect_b32 s62, s49, 0xfffff500
	s_add_u32 s22, s42, s22
	s_addc_u32 s23, s43, 0
	s_and_b64 vcc, exec, s[24:25]
	s_cbranch_vccnz .LBB0_278
	s_mov_b64 s[24:25], 0x400
	s_mov_b64 s[22:23], s[20:21]
	s_mov_b32 s62, s55
	s_branch .LBB0_279

;   DI unsigned rowoff(int r, int sch) const { const int g = r & 3, bc = r >> 2, b = bc / NCMP, c = bc - b * NCMP; return (unsigned)(b * Sn + c * 16) * 512u + g * 64 + sch; }
; template <int NI, class XL, class EP>
; DI void gemm_tile(const u16* __restrict__ W, int ldw, int f0, int t0, int K, XL xl, EP ep, unsigned char* smem) {
;     ...
;   f32x4 acc[4][NI];
; #pragma unroll
;   for (int i = 0; i < 4; ++i)
; #pragma unroll
;     for (int j = 0; j < NI; ++j) acc[i][j] = (f32x4){0.f, 0.f, 0.f, 0.f};
;   u32x4 wr[2], xr[XR];
;   const unsigned wbyte = ((unsigned)(f0 + srow * 2) * 32u + sch) * 2u;
;   const unsigned xbyte = xl.rowoff(t0 + srow * XR, sch) * 2u;
;   const int xrs = xl.rstride();
;   const int nk = K >> 5;
;   auto gload = [&](int it) {
;     const int k = it * 32;
;     const char* wb = (const char*)(W + (size_t)(k >> 5) * ldw * 32);
;     const char* xb = (const char*)xl.kbase(k);
; #pragma unroll
;     for (int i = 0; i < 2; ++i) wr[i] = *(const u32x4*)(wb + wbyte + i * 64);
; #pragma unroll
;     for (int i = 0; i < XR; ++i) xr[i] = *(const u32x4*)(xb + xbyte + i * xrs);
;   };
;   auto lstore = [&](int buf) {
;     u16* Ws = S0 + buf * BUF; u16* Xs = Ws + 128 * LST;
; #pragma unroll
;     for (int i = 0; i < 2; ++i) *(u32x4*)(Ws + (srow * 2 + i) * LST + sch) = wr[i];
; #pragma unroll
;     for (int i = 0; i < XR; ++i) *(u32x4*)(Xs + (srow * XR + i) * LST + sch) = xr[i];
;   };
;   gload(0);
;   __syncthreads();
;   lstore(0);
;   __syncthreads();
;   if (nk > 1) gload(1);
; DI void phase6(const Params& p, const Sched& sched, unsigned char* smem) {
;   XBlk xl{(const u16*)(p.ws + OFF_KVU), Tn};
;   const float* mod = (const float*)(p.ws + OFF_MOD);
;   u16* x1b = (u16*)(p.ws + OFF_MA);
;   for_tiles_st(256, 8, sched, [&](int tm, int tn) {
;     gemm_tile<8>((const u16*)(p.ws + OFF_WO), 1024, tn * 128, tm * 256, 1024, xl, [&](f32x4 (&acc)[4][8], int fb, int tb, int lr, int lq, int wf, int wt) {
.LBB0_811:
	v_mov_b32_e32 v46, v218
	s_and_b32 s34, s31, 7
	v_ashrrev_i32_e32 v47, 2, v46
	v_lshlrev_b32_e32 v0, 3, v46
	v_lshlrev_b32_e32 v49, 6, v47
	s_ashr_i32 s37, s31, 3
	v_and_b32_e32 v48, 24, v0
	v_lshl_add_u32 v0, s34, 12, v49
	s_add_i32 s35, s37, s29
	v_or_b32_e32 v0, v0, v48
	s_lshl_b32 s33, s35, 8
	v_lshlrev_b32_e32 v50, 1, v0
	v_and_b32_e32 v0, 0x3fffffc, v46
	v_add_u32_e32 v0, s33, v0
	v_lshlrev_b32_e32 v161, 1, v48
	v_lshl_or_b32 v51, v0, 6, v161
	global_load_dwordx4 v[16:19], v50, s[4:5]
	global_load_dwordx4 v[20:23], v50, s[4:5] offset:64
	global_load_dwordx4 v[24:27], v51, s[16:17]
	global_load_dwordx4 v[28:31], v51, s[16:17] offset:64
	global_load_dwordx4 v[32:35], v51, s[16:17] offset:128
	global_load_dwordx4 v[36:39], v51, s[16:17] offset:192
	v_mul_lo_u32 v166, v47, s22
	v_or_b32_e32 v162, v166, v161
	v_add_u32_e32 v163, v162, v166
	s_barrier
	v_bfe_u32 v158, v46, 4, 2
	v_and_b32_e32 v52, 15, v46
	v_ashrrev_i32_e32 v53, 1, v46
	v_lshlrev_b32_e32 v54, 1, v46
	v_lshlrev_b32_e32 v46, 6, v46
	s_and_b32 s44, s30, 7
	s_add_i32 s37, s20, s37
	v_and_b32_e32 v46, 0xffffff00, v46
	v_and_b32_e32 v160, 0xffffffc0, v53
	v_lshl_add_u32 v46, s37, 14, v46
	v_lshl_add_u32 v49, s44, 12, v49
	v_mov_b32_e32 v0, 0
	v_and_or_b32 v159, v54, s23, v52
	v_or_b32_e32 v47, v160, v52
	v_or_b32_e32 v152, v46, v161
	v_or_b32_e32 v46, v49, v48
	s_mov_b32 s36, 1
	v_mov_b32_e32 v155, v153
	v_mov_b32_e32 v1, v0
	v_mov_b32_e32 v2, v0
	v_mov_b32_e32 v3, v0
	v_mov_b32_e32 v4, v0
	v_mov_b32_e32 v5, v0
	v_mov_b32_e32 v6, v0
	v_mov_b32_e32 v7, v0
	v_mov_b32_e32 v8, v0
	v_mov_b32_e32 v9, v0
	v_mov_b32_e32 v10, v0
	v_mov_b32_e32 v11, v0
	v_mov_b32_e32 v12, v0
	v_mov_b32_e32 v13, v0
	v_mov_b32_e32 v14, v0
	v_mov_b32_e32 v15, v0
	v_mov_b32_e32 v40, v0
	v_mov_b32_e32 v41, v0
	v_mov_b32_e32 v42, v0
	v_mov_b32_e32 v43, v0
	v_mov_b32_e32 v44, v0
	v_mov_b32_e32 v45, v0
	v_lshlrev_b32_e32 v164, 4, v158
	v_mul_u32_u24_e32 v165, 48, v159
	v_mul_lo_u32 v167, v47, 48
	v_lshlrev_b32_e32 v154, 1, v46
	v_mov_b64_e32 v[156:157], v[152:153]
	v_mov_b32_e32 v46, v0
	v_mov_b32_e32 v47, v0
	v_mov_b32_e32 v68, v0
	v_mov_b32_e32 v69, v0
	v_mov_b32_e32 v70, v0
	v_mov_b32_e32 v71, v0
	v_mov_b32_e32 v80, v0
	v_mov_b32_e32 v81, v0
	v_mov_b32_e32 v82, v0
	v_mov_b32_e32 v83, v0
	v_mov_b32_e32 v48, v0
	v_mov_b32_e32 v49, v0
	v_mov_b32_e32 v52, v0
	v_mov_b32_e32 v53, v0
	v_mov_b32_e32 v54, v0
	v_mov_b32_e32 v55, v0
	v_mov_b32_e32 v56, v0
	v_mov_b32_e32 v57, v0
	v_mov_b32_e32 v58, v0
	s_waitcnt vmcnt(5)
	ds_write_b128 v162, v[16:19]
	s_waitcnt vmcnt(4)
	ds_write_b128 v162, v[20:23] offset:96
	s_waitcnt vmcnt(3)
	ds_write_b128 v163, v[24:27] offset:12288
	s_waitcnt vmcnt(2)
	ds_write_b128 v163, v[28:31] offset:12384
	s_waitcnt vmcnt(1)
	ds_write_b128 v163, v[32:35] offset:12480
	s_waitcnt vmcnt(0)
	ds_write_b128 v163, v[36:39] offset:12576
	s_waitcnt lgkmcnt(0)
	s_barrier
	global_load_dwordx4 v[20:23], v50, s[8:9]
	global_load_dwordx4 v[16:19], v50, s[8:9] offset:64
	global_load_dwordx4 v[36:39], v51, s[6:7]
	global_load_dwordx4 v[32:35], v51, s[6:7] offset:64
	global_load_dwordx4 v[28:31], v51, s[6:7] offset:128
	global_load_dwordx4 v[24:27], v51, s[6:7] offset:192
	s_add_u32 s98, s42, s24
	s_addc_u32 s99, s43, 0
	s_add_u32 s100, s42, s25
	s_addc_u32 s101, s43, 0
	global_load_dwordx4 v[200:203], v154, s[98:99]
	global_load_dwordx4 v[204:207], v154, s[98:99] offset:64
	global_load_dwordx4 v[208:211], v156, s[100:101] offset:2048
	global_load_dwordx4 v[212:215], v156, s[100:101] offset:2112
	global_load_dwordx4 v[220:223], v156, s[100:101] offset:2176
	global_load_dwordx4 v[224:227], v156, s[100:101] offset:2240
	s_add_u32 s98, s98, s18
	s_addc_u32 s99, s99, s19
	s_add_u32 s100, s100, s10
	s_addc_u32 s101, s101, s11
	v_mov_b32_e32 v50, v0
	v_mov_b32_e32 v51, v0
	v_mov_b32_e32 v59, v0
	v_mov_b32_e32 v64, v0
	v_mov_b32_e32 v65, v0
	v_mov_b32_e32 v66, v0
	v_mov_b32_e32 v67, v0
	v_mov_b32_e32 v76, v0
	v_mov_b32_e32 v77, v0
	v_mov_b32_e32 v78, v0
	v_mov_b32_e32 v79, v0
	v_mov_b32_e32 v88, v0
	v_mov_b32_e32 v89, v0
	v_mov_b32_e32 v90, v0
	v_mov_b32_e32 v91, v0
	v_mov_b32_e32 v100, v0
	v_mov_b32_e32 v101, v0
	v_mov_b32_e32 v102, v0
	v_mov_b32_e32 v103, v0
	v_mov_b32_e32 v112, v0
	v_mov_b32_e32 v113, v0
	v_mov_b32_e32 v114, v0
	v_mov_b32_e32 v115, v0
	v_mov_b32_e32 v60, v0
	v_mov_b32_e32 v61, v0
	v_mov_b32_e32 v62, v0
	v_mov_b32_e32 v63, v0
	v_mov_b32_e32 v72, v0
	v_mov_b32_e32 v73, v0
	v_mov_b32_e32 v74, v0
	v_mov_b32_e32 v75, v0
	v_mov_b32_e32 v84, v0
	v_mov_b32_e32 v85, v0
	v_mov_b32_e32 v86, v0
	v_mov_b32_e32 v87, v0
	v_mov_b32_e32 v96, v0
	v_mov_b32_e32 v97, v0
	v_mov_b32_e32 v98, v0
	v_mov_b32_e32 v99, v0
	v_mov_b32_e32 v108, v0
	v_mov_b32_e32 v109, v0
	v_mov_b32_e32 v110, v0
	v_mov_b32_e32 v111, v0
	v_mov_b32_e32 v120, v0
	v_mov_b32_e32 v121, v0
	v_mov_b32_e32 v122, v0
	v_mov_b32_e32 v123, v0
	v_mov_b32_e32 v128, v0
	v_mov_b32_e32 v129, v0
	v_mov_b32_e32 v130, v0
	v_mov_b32_e32 v131, v0
	v_mov_b32_e32 v136, v0
	v_mov_b32_e32 v137, v0
	v_mov_b32_e32 v138, v0
	v_mov_b32_e32 v139, v0
	v_mov_b32_e32 v92, v0
	v_mov_b32_e32 v93, v0
	v_mov_b32_e32 v94, v0
	v_mov_b32_e32 v95, v0
	v_mov_b32_e32 v104, v0
	v_mov_b32_e32 v105, v0
	v_mov_b32_e32 v106, v0
	v_mov_b32_e32 v107, v0
	v_mov_b32_e32 v116, v0
	v_mov_b32_e32 v117, v0
	v_mov_b32_e32 v118, v0
	v_mov_b32_e32 v119, v0
	v_mov_b32_e32 v124, v0
	v_mov_b32_e32 v125, v0
	v_mov_b32_e32 v126, v0
	v_mov_b32_e32 v127, v0
	v_mov_b32_e32 v132, v0
	v_mov_b32_e32 v133, v0
	v_mov_b32_e32 v134, v0
	v_mov_b32_e32 v135, v0
	v_mov_b32_e32 v140, v0
	v_mov_b32_e32 v141, v0
	v_mov_b32_e32 v142, v0
	v_mov_b32_e32 v143, v0
	v_mov_b32_e32 v144, v0
	v_mov_b32_e32 v145, v0
	v_mov_b32_e32 v146, v0
	v_mov_b32_e32 v147, v0
	v_mov_b32_e32 v148, v0
	v_mov_b32_e32 v149, v0
	v_mov_b32_e32 v150, v0
	v_mov_b32_e32 v151, v0
	v_lshl_add_u32 v228, v167, 1, v164
	v_lshl_add_u32 v152, v165, 1, v164
	v_add_u32_e32 v229, v166, v161
	v_add_u32_e32 v230, v229, v166
; DI f32x4 mfma16(bf16x8 a, bf16x8 b, f32x4 c) { return __builtin_amdgcn_mfma_f32_16x16x32_bf16(a, b, c, 0, 0, 0); }
; template <int NI, class XL, class EP>
; DI void gemm_tile(const u16* __restrict__ W, int ldw, int f0, int t0, int K, XL xl, EP ep, unsigned char* smem) {
;     ...
;   for (int it = 0; it < nk; ++it) {
;     const u16* Ws = S0 + (it & 1) * BUF; const u16* Xs = Ws + 128 * LST;
;     __builtin_amdgcn_s_setprio(1);
;     bf16x8 a[4];
; #pragma unroll
;     for (int mi = 0; mi < 4; ++mi) a[mi] = *(const bf16x8*)(Ws + (wf * 64 + mi * 16 + lr) * LST + lq * 8);
; #pragma unroll
;     for (int ni = 0; ni < NI; ++ni) {
;       const bf16x8 b = *(const bf16x8*)(Xs + (wt * (NI * 16) + ni * 16 + lr) * LST + lq * 8);
; #pragma unroll
;       for (int mi = 0; mi < 4; ++mi) acc[mi][ni] = mfma16(a[mi], b, acc[mi][ni]);
;     }
;     __builtin_amdgcn_sched_group_barrier(0x100, 6, 0);
; #pragma unroll
;     for (int ni = 0; ni < NI; ++ni) { __builtin_amdgcn_sched_group_barrier(0x008, 4, 0); if (ni + 2 < NI) __builtin_amdgcn_sched_group_barrier(0x100, 1, 0); }
;     __builtin_amdgcn_s_setprio(0);
;     if (it + 1 < nk) lstore((it + 1) & 1);
;     if (it + 2 < nk) gload(it + 2);
;     __syncthreads();
.LBB0_812:
	s_setprio 1
	ds_read_b128 v[168:171], v228 offset:0
	ds_read_b128 v[172:175], v228 offset:1536
	ds_read_b128 v[180:183], v228 offset:3072
	ds_read_b128 v[184:187], v228 offset:4608
	ds_read_b128 v[176:179], v152 offset:12288
	ds_read_b128 v[188:191], v152 offset:13824
	s_waitcnt lgkmcnt(1)
	v_mfma_f32_16x16x32_bf16 v[148:151], v[168:171], v[176:179], v[148:151]
	v_mfma_f32_16x16x32_bf16 v[136:139], v[172:175], v[176:179], v[136:139]
	v_mfma_f32_16x16x32_bf16 v[112:115], v[180:183], v[176:179], v[112:115]
	v_mfma_f32_16x16x32_bf16 v[80:83], v[184:187], v[176:179], v[80:83]
	ds_read_b128 v[176:179], v152 offset:15360
	s_waitcnt vmcnt(6)
	ds_write_b128 v229, v[20:23] offset:36864
	s_waitcnt lgkmcnt(2)
	v_mfma_f32_16x16x32_bf16 v[144:147], v[168:171], v[188:191], v[144:147]
	v_mfma_f32_16x16x32_bf16 v[128:131], v[172:175], v[188:191], v[128:131]
	v_mfma_f32_16x16x32_bf16 v[100:103], v[180:183], v[188:191], v[100:103]
	v_mfma_f32_16x16x32_bf16 v[68:71], v[184:187], v[188:191], v[68:71]
	ds_read_b128 v[188:191], v152 offset:16896
	ds_write_b128 v229, v[16:19] offset:36960
	global_load_dwordx4 v[20:23], v154, s[98:99]
	global_load_dwordx4 v[16:19], v154, s[98:99] offset:64
	s_waitcnt lgkmcnt(3)
	v_mfma_f32_16x16x32_bf16 v[140:143], v[168:171], v[176:179], v[140:143]
	v_mfma_f32_16x16x32_bf16 v[120:123], v[172:175], v[176:179], v[120:123]
	v_mfma_f32_16x16x32_bf16 v[88:91], v[180:183], v[176:179], v[88:91]
	v_mfma_f32_16x16x32_bf16 v[44:47], v[184:187], v[176:179], v[44:47]
	ds_read_b128 v[176:179], v152 offset:18432
	ds_write_b128 v230, v[36:39] offset:49152
	global_load_dwordx4 v[36:39], v156, s[100:101] offset:2048
	s_waitcnt lgkmcnt(3)
	v_mfma_f32_16x16x32_bf16 v[132:135], v[168:171], v[188:191], v[132:135]
	v_mfma_f32_16x16x32_bf16 v[108:111], v[172:175], v[188:191], v[108:111]
	v_mfma_f32_16x16x32_bf16 v[76:79], v[180:183], v[188:191], v[76:79]
	v_mfma_f32_16x16x32_bf16 v[40:43], v[184:187], v[188:191], v[40:43]
	ds_read_b128 v[188:191], v152 offset:19968
	ds_write_b128 v230, v[32:35] offset:49248
	global_load_dwordx4 v[32:35], v156, s[100:101] offset:2112
	s_waitcnt lgkmcnt(3)
	v_mfma_f32_16x16x32_bf16 v[124:127], v[168:171], v[176:179], v[124:127]
	v_mfma_f32_16x16x32_bf16 v[96:99], v[172:175], v[176:179], v[96:99]
	v_mfma_f32_16x16x32_bf16 v[64:67], v[180:183], v[176:179], v[64:67]
	v_mfma_f32_16x16x32_bf16 v[12:15], v[184:187], v[176:179], v[12:15]
	ds_read_b128 v[176:179], v152 offset:21504
	ds_write_b128 v230, v[28:31] offset:49344
	global_load_dwordx4 v[28:31], v156, s[100:101] offset:2176
	s_waitcnt lgkmcnt(3)
	v_mfma_f32_16x16x32_bf16 v[116:119], v[168:171], v[188:191], v[116:119]
	v_mfma_f32_16x16x32_bf16 v[84:87], v[172:175], v[188:191], v[84:87]
	v_mfma_f32_16x16x32_bf16 v[56:59], v[180:183], v[188:191], v[56:59]
	v_mfma_f32_16x16x32_bf16 v[8:11], v[184:187], v[188:191], v[8:11]
	ds_read_b128 v[188:191], v152 offset:23040
	ds_write_b128 v230, v[24:27] offset:49440
	global_load_dwordx4 v[24:27], v156, s[100:101] offset:2240
	s_waitcnt lgkmcnt(3)
	v_mfma_f32_16x16x32_bf16 v[104:107], v[168:171], v[176:179], v[104:107]
	v_mfma_f32_16x16x32_bf16 v[72:75], v[172:175], v[176:179], v[72:75]
	v_mfma_f32_16x16x32_bf16 v[52:55], v[180:183], v[176:179], v[52:55]
	v_mfma_f32_16x16x32_bf16 v[4:7], v[184:187], v[176:179], v[4:7]
	s_add_u32 s98, s98, s18
	s_addc_u32 s99, s99, s19
	s_add_u32 s100, s100, s10
	s_addc_u32 s101, s101, s11
	s_waitcnt lgkmcnt(1)
	v_mfma_f32_16x16x32_bf16 v[92:95], v[168:171], v[188:191], v[92:95]
	v_mfma_f32_16x16x32_bf16 v[60:63], v[172:175], v[188:191], v[60:63]
	v_mfma_f32_16x16x32_bf16 v[48:51], v[180:183], v[188:191], v[48:51]
	v_mfma_f32_16x16x32_bf16 v[0:3], v[184:187], v[188:191], v[0:3]
	s_setprio 0
	s_waitcnt lgkmcnt(0)
	s_barrier
	s_setprio 1
	ds_read_b128 v[168:171], v228 offset:36864
	ds_read_b128 v[172:175], v228 offset:38400
	ds_read_b128 v[180:183], v228 offset:39936
	ds_read_b128 v[184:187], v228 offset:41472
	ds_read_b128 v[176:179], v152 offset:49152
	ds_read_b128 v[188:191], v152 offset:50688
	s_waitcnt lgkmcnt(1)
	v_mfma_f32_16x16x32_bf16 v[148:151], v[168:171], v[176:179], v[148:151]
	v_mfma_f32_16x16x32_bf16 v[136:139], v[172:175], v[176:179], v[136:139]
	v_mfma_f32_16x16x32_bf16 v[112:115], v[180:183], v[176:179], v[112:115]
	v_mfma_f32_16x16x32_bf16 v[80:83], v[184:187], v[176:179], v[80:83]
	ds_read_b128 v[176:179], v152 offset:52224
	s_waitcnt vmcnt(6)
	ds_write_b128 v229, v[200:203] offset:0
	s_waitcnt lgkmcnt(2)
	v_mfma_f32_16x16x32_bf16 v[144:147], v[168:171], v[188:191], v[144:147]
	v_mfma_f32_16x16x32_bf16 v[128:131], v[172:175], v[188:191], v[128:131]
	v_mfma_f32_16x16x32_bf16 v[100:103], v[180:183], v[188:191], v[100:103]
	v_mfma_f32_16x16x32_bf16 v[68:71], v[184:187], v[188:191], v[68:71]
	ds_read_b128 v[188:191], v152 offset:53760
	ds_write_b128 v229, v[204:207] offset:96
	global_load_dwordx4 v[200:203], v154, s[98:99]
	global_load_dwordx4 v[204:207], v154, s[98:99] offset:64
	s_waitcnt lgkmcnt(3)
	v_mfma_f32_16x16x32_bf16 v[140:143], v[168:171], v[176:179], v[140:143]
	v_mfma_f32_16x16x32_bf16 v[120:123], v[172:175], v[176:179], v[120:123]
	v_mfma_f32_16x16x32_bf16 v[88:91], v[180:183], v[176:179], v[88:91]
	v_mfma_f32_16x16x32_bf16 v[44:47], v[184:187], v[176:179], v[44:47]
	ds_read_b128 v[176:179], v152 offset:55296
	ds_write_b128 v230, v[208:211] offset:12288
	global_load_dwordx4 v[208:211], v156, s[100:101] offset:2048
	s_waitcnt lgkmcnt(3)
; DI f32x4 mfma16(bf16x8 a, bf16x8 b, f32x4 c) { return __builtin_amdgcn_mfma_f32_16x16x32_bf16(a, b, c, 0, 0, 0); }
; template <int NI, class XL, class EP>
; DI void gemm_tile(const u16* __restrict__ W, int ldw, int f0, int t0, int K, XL xl, EP ep, unsigned char* smem) {
;     ...
;   for (int it = 0; it < nk; ++it) {
;     const u16* Ws = S0 + (it & 1) * BUF; const u16* Xs = Ws + 128 * LST;
;     __builtin_amdgcn_s_setprio(1);
;     bf16x8 a[4];
; #pragma unroll
;     for (int mi = 0; mi < 4; ++mi) a[mi] = *(const bf16x8*)(Ws + (wf * 64 + mi * 16 + lr) * LST + lq * 8);
; #pragma unroll
;     for (int ni = 0; ni < NI; ++ni) {
;       const bf16x8 b = *(const bf16x8*)(Xs + (wt * (NI * 16) + ni * 16 + lr) * LST + lq * 8);
; #pragma unroll
;       for (int mi = 0; mi < 4; ++mi) acc[mi][ni] = mfma16(a[mi], b, acc[mi][ni]);
;     }
;     __builtin_amdgcn_sched_group_barrier(0x100, 6, 0);
; #pragma unroll
;     for (int ni = 0; ni < NI; ++ni) { __builtin_amdgcn_sched_group_barrier(0x008, 4, 0); if (ni + 2 < NI) __builtin_amdgcn_sched_group_barrier(0x100, 1, 0); }
;     __builtin_amdgcn_s_setprio(0);
;     if (it + 1 < nk) lstore((it + 1) & 1);
;     if (it + 2 < nk) gload(it + 2);
;     __syncthreads();
	v_mfma_f32_16x16x32_bf16 v[132:135], v[168:171], v[188:191], v[132:135]
	v_mfma_f32_16x16x32_bf16 v[108:111], v[172:175], v[188:191], v[108:111]
	v_mfma_f32_16x16x32_bf16 v[76:79], v[180:183], v[188:191], v[76:79]
	v_mfma_f32_16x16x32_bf16 v[40:43], v[184:187], v[188:191], v[40:43]
	ds_read_b128 v[188:191], v152 offset:56832
	ds_write_b128 v230, v[212:215] offset:12384
	global_load_dwordx4 v[212:215], v156, s[100:101] offset:2112
	s_waitcnt lgkmcnt(3)
	v_mfma_f32_16x16x32_bf16 v[124:127], v[168:171], v[176:179], v[124:127]
	v_mfma_f32_16x16x32_bf16 v[96:99], v[172:175], v[176:179], v[96:99]
	v_mfma_f32_16x16x32_bf16 v[64:67], v[180:183], v[176:179], v[64:67]
	v_mfma_f32_16x16x32_bf16 v[12:15], v[184:187], v[176:179], v[12:15]
	ds_read_b128 v[176:179], v152 offset:58368
	ds_write_b128 v230, v[220:223] offset:12480
	global_load_dwordx4 v[220:223], v156, s[100:101] offset:2176
	s_waitcnt lgkmcnt(3)
	v_mfma_f32_16x16x32_bf16 v[116:119], v[168:171], v[188:191], v[116:119]
	v_mfma_f32_16x16x32_bf16 v[84:87], v[172:175], v[188:191], v[84:87]
	v_mfma_f32_16x16x32_bf16 v[56:59], v[180:183], v[188:191], v[56:59]
	v_mfma_f32_16x16x32_bf16 v[8:11], v[184:187], v[188:191], v[8:11]
	ds_read_b128 v[188:191], v152 offset:59904
	ds_write_b128 v230, v[224:227] offset:12576
	global_load_dwordx4 v[224:227], v156, s[100:101] offset:2240
	s_waitcnt lgkmcnt(3)
	v_mfma_f32_16x16x32_bf16 v[104:107], v[168:171], v[176:179], v[104:107]
	v_mfma_f32_16x16x32_bf16 v[72:75], v[172:175], v[176:179], v[72:75]
	v_mfma_f32_16x16x32_bf16 v[52:55], v[180:183], v[176:179], v[52:55]
	v_mfma_f32_16x16x32_bf16 v[4:7], v[184:187], v[176:179], v[4:7]
	s_add_u32 s98, s98, s18
	s_addc_u32 s99, s99, s19
	s_add_u32 s100, s100, s10
	s_addc_u32 s101, s101, s11
	s_add_i32 s36, s36, 2
	s_waitcnt lgkmcnt(1)
	v_mfma_f32_16x16x32_bf16 v[92:95], v[168:171], v[188:191], v[92:95]
	v_mfma_f32_16x16x32_bf16 v[60:63], v[172:175], v[188:191], v[60:63]
	v_mfma_f32_16x16x32_bf16 v[48:51], v[180:183], v[188:191], v[48:51]
	v_mfma_f32_16x16x32_bf16 v[0:3], v[184:187], v[188:191], v[0:3]
	s_setprio 0
	s_cmp_lg_u32 s36, 29
	s_waitcnt lgkmcnt(0)
	s_barrier
	s_cbranch_scc1 .LBB0_812
	s_setprio 1
	ds_read_b128 v[168:171], v228 offset:0
	ds_read_b128 v[172:175], v228 offset:1536
	ds_read_b128 v[180:183], v228 offset:3072
	ds_read_b128 v[184:187], v228 offset:4608
	ds_read_b128 v[176:179], v152 offset:12288
	ds_read_b128 v[188:191], v152 offset:13824
	s_waitcnt lgkmcnt(1)
	v_mfma_f32_16x16x32_bf16 v[148:151], v[168:171], v[176:179], v[148:151]
	v_mfma_f32_16x16x32_bf16 v[136:139], v[172:175], v[176:179], v[136:139]
	v_mfma_f32_16x16x32_bf16 v[112:115], v[180:183], v[176:179], v[112:115]
	v_mfma_f32_16x16x32_bf16 v[80:83], v[184:187], v[176:179], v[80:83]
	ds_read_b128 v[176:179], v152 offset:15360
	s_waitcnt vmcnt(6)
	ds_write_b128 v229, v[20:23] offset:36864
	s_waitcnt lgkmcnt(2)
	v_mfma_f32_16x16x32_bf16 v[144:147], v[168:171], v[188:191], v[144:147]
	v_mfma_f32_16x16x32_bf16 v[128:131], v[172:175], v[188:191], v[128:131]
	v_mfma_f32_16x16x32_bf16 v[100:103], v[180:183], v[188:191], v[100:103]
	v_mfma_f32_16x16x32_bf16 v[68:71], v[184:187], v[188:191], v[68:71]
	ds_read_b128 v[188:191], v152 offset:16896
	ds_write_b128 v229, v[16:19] offset:36960
	global_load_dwordx4 v[20:23], v154, s[98:99]
	global_load_dwordx4 v[16:19], v154, s[98:99] offset:64
	s_waitcnt lgkmcnt(3)
	v_mfma_f32_16x16x32_bf16 v[140:143], v[168:171], v[176:179], v[140:143]
	v_mfma_f32_16x16x32_bf16 v[120:123], v[172:175], v[176:179], v[120:123]
	v_mfma_f32_16x16x32_bf16 v[88:91], v[180:183], v[176:179], v[88:91]
	v_mfma_f32_16x16x32_bf16 v[44:47], v[184:187], v[176:179], v[44:47]
	ds_read_b128 v[176:179], v152 offset:18432
	ds_write_b128 v230, v[36:39] offset:49152
	global_load_dwordx4 v[36:39], v156, s[100:101] offset:2048
	s_waitcnt lgkmcnt(3)
	v_mfma_f32_16x16x32_bf16 v[132:135], v[168:171], v[188:191], v[132:135]
	v_mfma_f32_16x16x32_bf16 v[108:111], v[172:175], v[188:191], v[108:111]
	v_mfma_f32_16x16x32_bf16 v[76:79], v[180:183], v[188:191], v[76:79]
	v_mfma_f32_16x16x32_bf16 v[40:43], v[184:187], v[188:191], v[40:43]
	ds_read_b128 v[188:191], v152 offset:19968
	ds_write_b128 v230, v[32:35] offset:49248
	global_load_dwordx4 v[32:35], v156, s[100:101] offset:2112
	s_waitcnt lgkmcnt(3)
	v_mfma_f32_16x16x32_bf16 v[124:127], v[168:171], v[176:179], v[124:127]
	v_mfma_f32_16x16x32_bf16 v[96:99], v[172:175], v[176:179], v[96:99]
	v_mfma_f32_16x16x32_bf16 v[64:67], v[180:183], v[176:179], v[64:67]
	v_mfma_f32_16x16x32_bf16 v[12:15], v[184:187], v[176:179], v[12:15]
	ds_read_b128 v[176:179], v152 offset:21504
	ds_write_b128 v230, v[28:31] offset:49344
	global_load_dwordx4 v[28:31], v156, s[100:101] offset:2176
	s_waitcnt lgkmcnt(3)
	v_mfma_f32_16x16x32_bf16 v[116:119], v[168:171], v[188:191], v[116:119]
	v_mfma_f32_16x16x32_bf16 v[84:87], v[172:175], v[188:191], v[84:87]
	v_mfma_f32_16x16x32_bf16 v[56:59], v[180:183], v[188:191], v[56:59]
	v_mfma_f32_16x16x32_bf16 v[8:11], v[184:187], v[188:191], v[8:11]
	ds_read_b128 v[188:191], v152 offset:23040
	ds_write_b128 v230, v[24:27] offset:49440
	global_load_dwordx4 v[24:27], v156, s[100:101] offset:2240
	s_waitcnt lgkmcnt(3)
	v_mfma_f32_16x16x32_bf16 v[104:107], v[168:171], v[176:179], v[104:107]
	v_mfma_f32_16x16x32_bf16 v[72:75], v[172:175], v[176:179], v[72:75]
	v_mfma_f32_16x16x32_bf16 v[52:55], v[180:183], v[176:179], v[52:55]
	v_mfma_f32_16x16x32_bf16 v[4:7], v[184:187], v[176:179], v[4:7]
	s_add_u32 s98, s98, s18
	s_addc_u32 s99, s99, s19
	s_add_u32 s100, s100, s10
	s_addc_u32 s101, s101, s11
	s_waitcnt lgkmcnt(1)
	v_mfma_f32_16x16x32_bf16 v[92:95], v[168:171], v[188:191], v[92:95]
	v_mfma_f32_16x16x32_bf16 v[60:63], v[172:175], v[188:191], v[60:63]
	v_mfma_f32_16x16x32_bf16 v[48:51], v[180:183], v[188:191], v[48:51]
	v_mfma_f32_16x16x32_bf16 v[0:3], v[184:187], v[188:191], v[0:3]
	s_setprio 0
	s_waitcnt lgkmcnt(0)
	s_barrier
; DI f32x4 mfma16(bf16x8 a, bf16x8 b, f32x4 c) { return __builtin_amdgcn_mfma_f32_16x16x32_bf16(a, b, c, 0, 0, 0); }
; template <int NI, class XL, class EP>
; DI void gemm_tile(const u16* __restrict__ W, int ldw, int f0, int t0, int K, XL xl, EP ep, unsigned char* smem) {
;     ...
;   for (int it = 0; it < nk; ++it) {
;     const u16* Ws = S0 + (it & 1) * BUF; const u16* Xs = Ws + 128 * LST;
;     __builtin_amdgcn_s_setprio(1);
;     bf16x8 a[4];
; #pragma unroll
;     for (int mi = 0; mi < 4; ++mi) a[mi] = *(const bf16x8*)(Ws + (wf * 64 + mi * 16 + lr) * LST + lq * 8);
; #pragma unroll
;     for (int ni = 0; ni < NI; ++ni) {
;       const bf16x8 b = *(const bf16x8*)(Xs + (wt * (NI * 16) + ni * 16 + lr) * LST + lq * 8);
; #pragma unroll
;       for (int mi = 0; mi < 4; ++mi) acc[mi][ni] = mfma16(a[mi], b, acc[mi][ni]);
;     }
;     __builtin_amdgcn_sched_group_barrier(0x100, 6, 0);
; #pragma unroll
;     for (int ni = 0; ni < NI; ++ni) { __builtin_amdgcn_sched_group_barrier(0x008, 4, 0); if (ni + 2 < NI) __builtin_amdgcn_sched_group_barrier(0x100, 1, 0); }
;     __builtin_amdgcn_s_setprio(0);
;     if (it + 1 < nk) lstore((it + 1) & 1);
;     if (it + 2 < nk) gload(it + 2);
;     __syncthreads();
;   }
	s_setprio 1
	ds_read_b128 v[168:171], v228 offset:36864
	ds_read_b128 v[172:175], v228 offset:38400
	ds_read_b128 v[180:183], v228 offset:39936
	ds_read_b128 v[184:187], v228 offset:41472
	ds_read_b128 v[176:179], v152 offset:49152
	ds_read_b128 v[188:191], v152 offset:50688
	s_waitcnt lgkmcnt(1)
	v_mfma_f32_16x16x32_bf16 v[148:151], v[168:171], v[176:179], v[148:151]
	v_mfma_f32_16x16x32_bf16 v[136:139], v[172:175], v[176:179], v[136:139]
	v_mfma_f32_16x16x32_bf16 v[112:115], v[180:183], v[176:179], v[112:115]
	v_mfma_f32_16x16x32_bf16 v[80:83], v[184:187], v[176:179], v[80:83]
	ds_read_b128 v[176:179], v152 offset:52224
	s_waitcnt vmcnt(6)
	ds_write_b128 v229, v[200:203] offset:0
	s_waitcnt lgkmcnt(2)
	v_mfma_f32_16x16x32_bf16 v[144:147], v[168:171], v[188:191], v[144:147]
	v_mfma_f32_16x16x32_bf16 v[128:131], v[172:175], v[188:191], v[128:131]
	v_mfma_f32_16x16x32_bf16 v[100:103], v[180:183], v[188:191], v[100:103]
	v_mfma_f32_16x16x32_bf16 v[68:71], v[184:187], v[188:191], v[68:71]
	ds_read_b128 v[188:191], v152 offset:53760
	ds_write_b128 v229, v[204:207] offset:96
	s_waitcnt lgkmcnt(3)
	v_mfma_f32_16x16x32_bf16 v[140:143], v[168:171], v[176:179], v[140:143]
	v_mfma_f32_16x16x32_bf16 v[120:123], v[172:175], v[176:179], v[120:123]
	v_mfma_f32_16x16x32_bf16 v[88:91], v[180:183], v[176:179], v[88:91]
	v_mfma_f32_16x16x32_bf16 v[44:47], v[184:187], v[176:179], v[44:47]
	ds_read_b128 v[176:179], v152 offset:55296
	ds_write_b128 v230, v[208:211] offset:12288
	s_waitcnt lgkmcnt(3)
	v_mfma_f32_16x16x32_bf16 v[132:135], v[168:171], v[188:191], v[132:135]
	v_mfma_f32_16x16x32_bf16 v[108:111], v[172:175], v[188:191], v[108:111]
	v_mfma_f32_16x16x32_bf16 v[76:79], v[180:183], v[188:191], v[76:79]
	v_mfma_f32_16x16x32_bf16 v[40:43], v[184:187], v[188:191], v[40:43]
	ds_read_b128 v[188:191], v152 offset:56832
	ds_write_b128 v230, v[212:215] offset:12384
	s_waitcnt lgkmcnt(3)
	v_mfma_f32_16x16x32_bf16 v[124:127], v[168:171], v[176:179], v[124:127]
	v_mfma_f32_16x16x32_bf16 v[96:99], v[172:175], v[176:179], v[96:99]
	v_mfma_f32_16x16x32_bf16 v[64:67], v[180:183], v[176:179], v[64:67]
	v_mfma_f32_16x16x32_bf16 v[12:15], v[184:187], v[176:179], v[12:15]
	ds_read_b128 v[176:179], v152 offset:58368
	ds_write_b128 v230, v[220:223] offset:12480
	s_waitcnt lgkmcnt(3)
	v_mfma_f32_16x16x32_bf16 v[116:119], v[168:171], v[188:191], v[116:119]
	v_mfma_f32_16x16x32_bf16 v[84:87], v[172:175], v[188:191], v[84:87]
	v_mfma_f32_16x16x32_bf16 v[56:59], v[180:183], v[188:191], v[56:59]
	v_mfma_f32_16x16x32_bf16 v[8:11], v[184:187], v[188:191], v[8:11]
	ds_read_b128 v[188:191], v152 offset:59904
	ds_write_b128 v230, v[224:227] offset:12576
	s_waitcnt lgkmcnt(3)
	v_mfma_f32_16x16x32_bf16 v[104:107], v[168:171], v[176:179], v[104:107]
	v_mfma_f32_16x16x32_bf16 v[72:75], v[172:175], v[176:179], v[72:75]
	v_mfma_f32_16x16x32_bf16 v[52:55], v[180:183], v[176:179], v[52:55]
	v_mfma_f32_16x16x32_bf16 v[4:7], v[184:187], v[176:179], v[4:7]
	s_add_i32 s36, s36, 2
	s_waitcnt lgkmcnt(1)
	v_mfma_f32_16x16x32_bf16 v[92:95], v[168:171], v[188:191], v[92:95]
	v_mfma_f32_16x16x32_bf16 v[60:63], v[172:175], v[188:191], v[60:63]
	v_mfma_f32_16x16x32_bf16 v[48:51], v[180:183], v[188:191], v[48:51]
	v_mfma_f32_16x16x32_bf16 v[0:3], v[184:187], v[188:191], v[0:3]
	s_setprio 0
	s_waitcnt lgkmcnt(0)
	s_barrier
	s_setprio 1
	v_lshl_add_u32 v152, v167, 1, v164
	ds_read_b128 v[154:157], v152
	v_lshl_add_u32 v161, v165, 1, v164
	ds_read_b128 v[164:167], v152 offset:1536
	ds_read_b128 v[172:175], v152 offset:3072
	ds_read_b128 v[176:179], v152 offset:4608
	ds_read_b128 v[168:171], v161 offset:12288
	ds_read_b128 v[180:183], v161 offset:13824
	s_waitcnt lgkmcnt(1)
	v_mfma_f32_16x16x32_bf16 v[148:151], v[154:157], v[168:171], v[148:151]
	v_mfma_f32_16x16x32_bf16 v[136:139], v[164:167], v[168:171], v[136:139]
	v_mfma_f32_16x16x32_bf16 v[112:115], v[172:175], v[168:171], v[112:115]
	v_mfma_f32_16x16x32_bf16 v[80:83], v[176:179], v[168:171], v[80:83]
	ds_read_b128 v[168:171], v161 offset:15360
	s_waitcnt lgkmcnt(1)
	v_mfma_f32_16x16x32_bf16 v[144:147], v[154:157], v[180:183], v[144:147]
	v_mfma_f32_16x16x32_bf16 v[128:131], v[164:167], v[180:183], v[128:131]
	v_mfma_f32_16x16x32_bf16 v[100:103], v[172:175], v[180:183], v[100:103]
	v_mfma_f32_16x16x32_bf16 v[68:71], v[176:179], v[180:183], v[68:71]
	ds_read_b128 v[180:183], v161 offset:16896
	s_waitcnt lgkmcnt(1)
	v_mfma_f32_16x16x32_bf16 v[140:143], v[154:157], v[168:171], v[140:143]
	v_mfma_f32_16x16x32_bf16 v[120:123], v[164:167], v[168:171], v[120:123]
	v_mfma_f32_16x16x32_bf16 v[184:187], v[172:175], v[168:171], v[88:91]
	v_mfma_f32_16x16x32_bf16 v[44:47], v[176:179], v[168:171], v[44:47]
	s_nop 1
	ds_read_b128 v[88:91], v161 offset:18432
	s_waitcnt lgkmcnt(1)
	v_mfma_f32_16x16x32_bf16 v[132:135], v[154:157], v[180:183], v[132:135]
	v_mfma_f32_16x16x32_bf16 v[168:171], v[164:167], v[180:183], v[108:111]
	v_mfma_f32_16x16x32_bf16 v[188:191], v[172:175], v[180:183], v[76:79]
	v_mfma_f32_16x16x32_bf16 v[180:183], v[176:179], v[180:183], v[40:43]
	s_nop 2
	ds_read_b128 v[40:43], v161 offset:19968
	s_waitcnt lgkmcnt(1)
	v_mfma_f32_16x16x32_bf16 v[124:127], v[154:157], v[88:91], v[124:127]
	v_mfma_f32_16x16x32_bf16 v[192:195], v[164:167], v[88:91], v[96:99]
	v_mfma_f32_16x16x32_bf16 v[196:199], v[172:175], v[88:91], v[64:67]
	v_mfma_f32_16x16x32_bf16 v[200:203], v[176:179], v[88:91], v[12:15]
	s_nop 2
	ds_read_b128 v[12:15], v161 offset:21504
	s_waitcnt lgkmcnt(1)
	v_mfma_f32_16x16x32_bf16 v[116:119], v[154:157], v[40:43], v[116:119]
	v_mfma_f32_16x16x32_bf16 v[204:207], v[164:167], v[40:43], v[84:87]
	v_mfma_f32_16x16x32_bf16 v[56:59], v[172:175], v[40:43], v[56:59]
	v_mfma_f32_16x16x32_bf16 v[208:211], v[176:179], v[40:43], v[8:11]
	s_nop 2
	ds_read_b128 v[8:11], v161 offset:23040
	s_waitcnt lgkmcnt(1)
	v_mfma_f32_16x16x32_bf16 v[212:215], v[154:157], v[12:15], v[104:107]
	v_mfma_f32_16x16x32_bf16 v[72:75], v[164:167], v[12:15], v[72:75]
	v_mfma_f32_16x16x32_bf16 v[220:223], v[172:175], v[12:15], v[52:55]
	v_mfma_f32_16x16x32_bf16 v[224:227], v[176:179], v[12:15], v[4:7]
	s_waitcnt lgkmcnt(0)
	v_mfma_f32_16x16x32_bf16 v[154:157], v[154:157], v[8:11], v[92:95]
	v_mfma_f32_16x16x32_bf16 v[60:63], v[164:167], v[8:11], v[60:63]
	v_mfma_f32_16x16x32_bf16 v[164:167], v[172:175], v[8:11], v[48:51]
	v_mfma_f32_16x16x32_bf16 v[172:175], v[176:179], v[8:11], v[0:3]
	s_setprio 0
	s_waitcnt vmcnt(5)
	ds_write_b128 v162, v[20:23] offset:36864
	s_waitcnt vmcnt(4)
	ds_write_b128 v162, v[16:19] offset:36960
	s_waitcnt vmcnt(3)
	ds_write_b128 v163, v[36:39] offset:49152
	s_waitcnt vmcnt(2)
	ds_write_b128 v163, v[32:35] offset:49248
	s_waitcnt vmcnt(1)
	ds_write_b128 v163, v[28:31] offset:49344
	s_waitcnt vmcnt(0)
	ds_write_b128 v163, v[24:27] offset:49440
	s_waitcnt lgkmcnt(0)
	s_barrier
; DI void store4(u16* dst, f32x4 v) { uint2 w; w.x = cvtpk(v[0], v[1]); w.y = cvtpk(v[2], v[3]); *(uint2*)dst = w; }
; DI f32x4 mfma16(bf16x8 a, bf16x8 b, f32x4 c) { return __builtin_amdgcn_mfma_f32_16x16x32_bf16(a, b, c, 0, 0, 0); }
; template <int NI, class XL, class EP>
; DI void gemm_tile(const u16* __restrict__ W, int ldw, int f0, int t0, int K, XL xl, EP ep, unsigned char* smem) {
;     ...
; #pragma unroll
;     for (int mi = 0; mi < 4; ++mi) a[mi] = *(const bf16x8*)(Ws + (wf * 64 + mi * 16 + lr) * LST + lq * 8);
; #pragma unroll
;     for (int ni = 0; ni < NI; ++ni) {
;       const bf16x8 b = *(const bf16x8*)(Xs + (wt * (NI * 16) + ni * 16 + lr) * LST + lq * 8);
; #pragma unroll
;       for (int mi = 0; mi < 4; ++mi) acc[mi][ni] = mfma16(a[mi], b, acc[mi][ni]);
;     }
; DI void phase6(const Params& p, const Sched& sched, unsigned char* smem) {
;     ...
;       const int b = tb >> 11;
;       __syncthreads();
; #pragma unroll
;       for (int mi = 0; mi < 4; ++mi) {
;         const int f = fb + mi * 16 + lq * 4; const float4 gm = *(const float4*)(mod + (size_t)b * 6144 + 2048 + f);
; #pragma unroll
;         for (int ni = 0; ni < 8; ++ni) {
;           const f32x4 o = {gm.x * acc[mi][ni][0], gm.y * acc[mi][ni][1], gm.z * acc[mi][ni][2], gm.w * acc[mi][ni][3]};
;           store4(Ls + (wt * 128 + ni * 16 + lr) * EST + wf * 64 + mi * 16 + lq * 4, o);
;         }
;       }
	s_lshl_b32 s34, s34, 7
	s_setprio 1
	ds_read_b128 v[28:31], v152 offset:36864
	ds_read_b128 v[176:179], v152 offset:38400
	ds_read_b128 v[228:231], v152 offset:39936
	ds_read_b128 v[232:235], v152 offset:41472
	ds_read_b128 v[0:3], v161 offset:49152
	ds_read_b128 v[4:7], v161 offset:50688
	s_waitcnt lgkmcnt(1)
	v_mfma_f32_16x16x32_bf16 v[88:91], v[28:31], v[0:3], v[148:151]
	v_mfma_f32_16x16x32_bf16 v[64:67], v[176:179], v[0:3], v[136:139]
	v_mfma_f32_16x16x32_bf16 v[32:35], v[228:231], v[0:3], v[112:115]
	v_mfma_f32_16x16x32_bf16 v[0:3], v[232:235], v[0:3], v[80:83]
	ds_read_b128 v[8:11], v161 offset:52224
	s_waitcnt lgkmcnt(1)
	v_mfma_f32_16x16x32_bf16 v[96:99], v[28:31], v[4:7], v[144:147]
	v_mfma_f32_16x16x32_bf16 v[76:79], v[176:179], v[4:7], v[128:131]
	v_mfma_f32_16x16x32_bf16 v[36:39], v[228:231], v[4:7], v[100:103]
	v_mfma_f32_16x16x32_bf16 v[4:7], v[232:235], v[4:7], v[68:71]
	ds_read_b128 v[12:15], v161 offset:53760
	s_waitcnt lgkmcnt(1)
	v_mfma_f32_16x16x32_bf16 v[104:107], v[28:31], v[8:11], v[140:143]
	v_mfma_f32_16x16x32_bf16 v[84:87], v[176:179], v[8:11], v[120:123]
	v_mfma_f32_16x16x32_bf16 v[40:43], v[228:231], v[8:11], v[184:187]
	v_mfma_f32_16x16x32_bf16 v[8:11], v[232:235], v[8:11], v[44:47]
	ds_read_b128 v[16:19], v161 offset:55296
	s_waitcnt lgkmcnt(1)
	v_mfma_f32_16x16x32_bf16 v[108:111], v[28:31], v[12:15], v[132:135]
	v_mfma_f32_16x16x32_bf16 v[92:95], v[176:179], v[12:15], v[168:171]
	v_mfma_f32_16x16x32_bf16 v[44:47], v[228:231], v[12:15], v[188:191]
	v_mfma_f32_16x16x32_bf16 v[12:15], v[232:235], v[12:15], v[180:183]
	ds_read_b128 v[20:23], v161 offset:56832
	s_waitcnt lgkmcnt(1)
	v_mfma_f32_16x16x32_bf16 v[112:115], v[28:31], v[16:19], v[124:127]
	v_mfma_f32_16x16x32_bf16 v[100:103], v[176:179], v[16:19], v[192:195]
	v_mfma_f32_16x16x32_bf16 v[48:51], v[228:231], v[16:19], v[196:199]
	v_mfma_f32_16x16x32_bf16 v[16:19], v[232:235], v[16:19], v[200:203]
	ds_read_b128 v[24:27], v161 offset:58368
	s_waitcnt lgkmcnt(1)
	v_mfma_f32_16x16x32_bf16 v[116:119], v[28:31], v[20:23], v[116:119]
	v_mfma_f32_16x16x32_bf16 v[68:71], v[176:179], v[20:23], v[204:207]
	v_mfma_f32_16x16x32_bf16 v[52:55], v[228:231], v[20:23], v[56:59]
	v_mfma_f32_16x16x32_bf16 v[20:23], v[232:235], v[20:23], v[208:211]
	ds_read_b128 v[128:131], v161 offset:59904
	s_waitcnt lgkmcnt(1)
	v_mfma_f32_16x16x32_bf16 v[120:123], v[28:31], v[24:27], v[212:215]
	v_mfma_f32_16x16x32_bf16 v[80:83], v[176:179], v[24:27], v[72:75]
	v_mfma_f32_16x16x32_bf16 v[56:59], v[228:231], v[24:27], v[220:223]
	v_mfma_f32_16x16x32_bf16 v[24:27], v[232:235], v[24:27], v[224:227]
	s_waitcnt lgkmcnt(0)
	v_mfma_f32_16x16x32_bf16 v[124:127], v[28:31], v[128:131], v[154:157]
	v_mfma_f32_16x16x32_bf16 v[72:75], v[176:179], v[128:131], v[60:63]
	v_mfma_f32_16x16x32_bf16 v[60:63], v[228:231], v[128:131], v[164:167]
	v_mfma_f32_16x16x32_bf16 v[28:31], v[232:235], v[128:131], v[172:175]
	s_setprio 0
	s_ashr_i32 s35, s35, 3
	v_add_u32_e32 v128, s34, v160
	s_mul_hi_i32 s37, s35, 0x6000
	s_mulk_i32 s35, 0x6000
	v_lshl_or_b32 v128, v158, 2, v128
	s_add_u32 s36, s72, s35
	s_addc_u32 s37, s73, s37
	v_ashrrev_i32_e32 v129, 31, v128
	v_lshl_add_u64 v[128:129], v[128:129], 2, s[36:37]
	v_add_co_u32_e32 v140, vcc, s26, v128
	v_mul_u32_u24_e32 v138, 0x88, v159
	s_nop 0
	v_addc_co_u32_e32 v141, vcc, 0, v129, vcc
	v_lshlrev_b32_e32 v136, 1, v160
	v_lshlrev_b32_e32 v137, 3, v158
	v_lshlrev_b32_e32 v138, 1, v138
	s_barrier
	s_barrier
	global_load_dwordx4 v[128:131], v[140:141], off
	global_load_dwordx4 v[132:135], v[140:141], off offset:64
	v_add3_u32 v144, v136, v137, v138
	global_load_dwordx4 v[136:139], v[140:141], off offset:128
	v_add_u32_e32 v145, 0x1000, v144
	global_load_dwordx4 v[140:143], v[140:141], off offset:192
	v_add_u32_e32 v146, 0x2000, v144
	v_add_u32_e32 v147, 0x3000, v144
	v_add_u32_e32 v148, 0x4000, v144
	s_add_i32 s31, s31, s78
	s_add_i32 s30, s30, s78
	s_cmp_gt_i32 s31, 63
	s_waitcnt vmcnt(3)
	v_pk_mul_f32 v[88:89], v[88:89], v[128:129]
	v_pk_mul_f32 v[90:91], v[90:91], v[130:131]
	v_pk_mul_f32 v[96:97], v[96:97], v[128:129]
	s_waitcnt vmcnt(1)
	v_pk_mul_f32 v[32:33], v[32:33], v[136:137]
	v_pk_mul_f32 v[34:35], v[34:35], v[138:139]
	s_waitcnt vmcnt(0)
	v_pk_mul_f32 v[0:1], v[0:1], v[140:141]
	v_pk_mul_f32 v[2:3], v[2:3], v[142:143]
	v_cvt_pk_bf16_f32 v32, v32, v33
	v_cvt_pk_bf16_f32 v33, v34, v35
	v_cvt_pk_bf16_f32 v0, v0, v1
	v_cvt_pk_bf16_f32 v1, v2, v3
	v_pk_mul_f32 v[34:35], v[36:37], v[136:137]
	v_pk_mul_f32 v[36:37], v[38:39], v[138:139]
	ds_write2_b64 v144, v[32:33], v[0:1] offset0:8 offset1:12
	v_pk_mul_f32 v[0:1], v[4:5], v[140:141]
	v_pk_mul_f32 v[2:3], v[6:7], v[142:143]
	v_cvt_pk_bf16_f32 v34, v34, v35
	v_cvt_pk_bf16_f32 v35, v36, v37
	v_cvt_pk_bf16_f32 v0, v0, v1
	v_cvt_pk_bf16_f32 v1, v2, v3
	v_pk_mul_f32 v[36:37], v[40:41], v[136:137]
	v_pk_mul_f32 v[38:39], v[42:43], v[138:139]
	ds_write2_b64 v145, v[34:35], v[0:1] offset0:40 offset1:44
	v_pk_mul_f32 v[0:1], v[8:9], v[140:141]
	v_pk_mul_f32 v[2:3], v[10:11], v[142:143]
	v_cvt_pk_bf16_f32 v36, v36, v37
	v_cvt_pk_bf16_f32 v37, v38, v39
	v_cvt_pk_bf16_f32 v0, v0, v1
	v_cvt_pk_bf16_f32 v1, v2, v3
	v_pk_mul_f32 v[38:39], v[44:45], v[136:137]
	v_pk_mul_f32 v[40:41], v[46:47], v[138:139]
	ds_write2_b64 v146, v[36:37], v[0:1] offset0:72 offset1:76
	v_pk_mul_f32 v[0:1], v[12:13], v[140:141]
	v_pk_mul_f32 v[2:3], v[14:15], v[142:143]
	v_cvt_pk_bf16_f32 v38, v38, v39
	v_cvt_pk_bf16_f32 v39, v40, v41
	v_cvt_pk_bf16_f32 v0, v0, v1
	v_cvt_pk_bf16_f32 v1, v2, v3
	v_pk_mul_f32 v[98:99], v[98:99], v[130:131]
	v_pk_mul_f32 v[64:65], v[64:65], v[132:133]
	v_pk_mul_f32 v[66:67], v[66:67], v[134:135]
; DI void store4(u16* dst, f32x4 v) { uint2 w; w.x = cvtpk(v[0], v[1]); w.y = cvtpk(v[2], v[3]); *(uint2*)dst = w; }
; DI void phase6(const Params& p, const Sched& sched, unsigned char* smem) {
;     ...
; #pragma unroll
;       for (int mi = 0; mi < 4; ++mi) {
;         const int f = fb + mi * 16 + lq * 4; const float4 gm = *(const float4*)(mod + (size_t)b * 6144 + 2048 + f);
; #pragma unroll
;         for (int ni = 0; ni < 8; ++ni) {
;           const f32x4 o = {gm.x * acc[mi][ni][0], gm.y * acc[mi][ni][1], gm.z * acc[mi][ni][2], gm.w * acc[mi][ni][3]};
;           store4(Ls + (wt * 128 + ni * 16 + lr) * EST + wf * 64 + mi * 16 + lq * 4, o);
;         }
;       }
;       __syncthreads();
	v_pk_mul_f32 v[76:77], v[76:77], v[132:133]
	v_pk_mul_f32 v[78:79], v[78:79], v[134:135]
	v_pk_mul_f32 v[40:41], v[48:49], v[136:137]
	v_pk_mul_f32 v[42:43], v[50:51], v[138:139]
	ds_write2_b64 v147, v[38:39], v[0:1] offset0:104 offset1:108
	v_pk_mul_f32 v[0:1], v[16:17], v[140:141]
	v_pk_mul_f32 v[2:3], v[18:19], v[142:143]
	v_cvt_pk_bf16_f32 v88, v88, v89
	v_cvt_pk_bf16_f32 v89, v90, v91
	v_cvt_pk_bf16_f32 v90, v96, v97
	v_cvt_pk_bf16_f32 v91, v98, v99
	v_cvt_pk_bf16_f32 v64, v64, v65
	v_cvt_pk_bf16_f32 v65, v66, v67
	v_cvt_pk_bf16_f32 v66, v76, v77
	v_cvt_pk_bf16_f32 v67, v78, v79
	v_cvt_pk_bf16_f32 v40, v40, v41
	v_cvt_pk_bf16_f32 v41, v42, v43
	v_cvt_pk_bf16_f32 v0, v0, v1
	v_cvt_pk_bf16_f32 v1, v2, v3
	v_pk_mul_f32 v[106:107], v[106:107], v[130:131]
	v_pk_mul_f32 v[116:117], v[116:117], v[128:129]
	v_pk_mul_f32 v[118:119], v[118:119], v[130:131]
	ds_write2_b64 v144, v[88:89], v[64:65] offset1:4
	ds_write2_b64 v145, v[90:91], v[66:67] offset0:32 offset1:36
	v_pk_mul_f32 v[64:65], v[68:69], v[132:133]
	v_pk_mul_f32 v[66:67], v[70:71], v[134:135]
	v_pk_mul_f32 v[42:43], v[52:53], v[136:137]
	v_pk_mul_f32 v[44:45], v[54:55], v[138:139]
	ds_write2_b64 v148, v[40:41], v[0:1] offset0:136 offset1:140
	v_pk_mul_f32 v[0:1], v[20:21], v[140:141]
	v_pk_mul_f32 v[2:3], v[22:23], v[142:143]
	v_cvt_pk_bf16_f32 v97, v106, v107
	v_cvt_pk_bf16_f32 v106, v116, v117
	v_cvt_pk_bf16_f32 v107, v118, v119
	v_cvt_pk_bf16_f32 v64, v64, v65
	v_cvt_pk_bf16_f32 v65, v66, v67
	v_add_u32_e32 v68, 0x5000, v144
	v_cvt_pk_bf16_f32 v42, v42, v43
	v_cvt_pk_bf16_f32 v43, v44, v45
	v_cvt_pk_bf16_f32 v0, v0, v1
	v_cvt_pk_bf16_f32 v1, v2, v3
	v_pk_mul_f32 v[108:109], v[108:109], v[128:129]
	v_pk_mul_f32 v[120:121], v[120:121], v[128:129]
	v_pk_mul_f32 v[122:123], v[122:123], v[130:131]
	ds_write2_b64 v68, v[106:107], v[64:65] offset0:160 offset1:164
	v_pk_mul_f32 v[64:65], v[80:81], v[132:133]
	v_pk_mul_f32 v[66:67], v[82:83], v[134:135]
	v_pk_mul_f32 v[44:45], v[56:57], v[136:137]
	v_pk_mul_f32 v[46:47], v[58:59], v[138:139]
	ds_write2_b64 v68, v[42:43], v[0:1] offset0:168 offset1:172
	v_pk_mul_f32 v[0:1], v[24:25], v[140:141]
	v_pk_mul_f32 v[2:3], v[26:27], v[142:143]
	v_cvt_pk_bf16_f32 v98, v108, v109
	v_cvt_pk_bf16_f32 v108, v120, v121
	v_cvt_pk_bf16_f32 v109, v122, v123
	v_cvt_pk_bf16_f32 v64, v64, v65
	v_cvt_pk_bf16_f32 v65, v66, v67
	v_add_u32_e32 v69, 0x6000, v144
	v_cvt_pk_bf16_f32 v44, v44, v45
	v_cvt_pk_bf16_f32 v45, v46, v47
	v_cvt_pk_bf16_f32 v0, v0, v1
	v_cvt_pk_bf16_f32 v1, v2, v3
	v_pk_mul_f32 v[104:105], v[104:105], v[128:129]
	v_pk_mul_f32 v[110:111], v[110:111], v[130:131]
	v_pk_mul_f32 v[112:113], v[112:113], v[128:129]
	v_pk_mul_f32 v[114:115], v[114:115], v[130:131]
	v_pk_mul_f32 v[124:125], v[124:125], v[128:129]
	v_pk_mul_f32 v[126:127], v[126:127], v[130:131]
	v_pk_mul_f32 v[84:85], v[84:85], v[132:133]
	v_pk_mul_f32 v[86:87], v[86:87], v[134:135]
	v_pk_mul_f32 v[92:93], v[92:93], v[132:133]
	v_pk_mul_f32 v[94:95], v[94:95], v[134:135]
	v_pk_mul_f32 v[100:101], v[100:101], v[132:133]
	v_pk_mul_f32 v[102:103], v[102:103], v[134:135]
	ds_write2_b64 v69, v[108:109], v[64:65] offset0:192 offset1:196
	v_pk_mul_f32 v[64:65], v[72:73], v[132:133]
	v_pk_mul_f32 v[66:67], v[74:75], v[134:135]
	v_pk_mul_f32 v[46:47], v[60:61], v[136:137]
	v_pk_mul_f32 v[48:49], v[62:63], v[138:139]
	ds_write2_b64 v69, v[44:45], v[0:1] offset0:200 offset1:204
	v_pk_mul_f32 v[0:1], v[28:29], v[140:141]
	v_pk_mul_f32 v[2:3], v[30:31], v[142:143]
	v_cvt_pk_bf16_f32 v96, v104, v105
	v_cvt_pk_bf16_f32 v99, v110, v111
	v_cvt_pk_bf16_f32 v104, v112, v113
	v_cvt_pk_bf16_f32 v105, v114, v115
	v_cvt_pk_bf16_f32 v110, v124, v125
	v_cvt_pk_bf16_f32 v111, v126, v127
	v_cvt_pk_bf16_f32 v76, v84, v85
	v_cvt_pk_bf16_f32 v77, v86, v87
	v_cvt_pk_bf16_f32 v78, v92, v93
	v_cvt_pk_bf16_f32 v79, v94, v95
	v_cvt_pk_bf16_f32 v84, v100, v101
	v_cvt_pk_bf16_f32 v85, v102, v103
	v_cvt_pk_bf16_f32 v64, v64, v65
	v_cvt_pk_bf16_f32 v65, v66, v67
	v_add_u32_e32 v66, 0x7000, v144
	v_cvt_pk_bf16_f32 v46, v46, v47
	v_cvt_pk_bf16_f32 v47, v48, v49
	v_cvt_pk_bf16_f32 v0, v0, v1
	v_cvt_pk_bf16_f32 v1, v2, v3
	v_mov_b32_e32 v2, v218
	ds_write2_b64 v146, v[96:97], v[76:77] offset0:64 offset1:68
	ds_write2_b64 v147, v[98:99], v[78:79] offset0:96 offset1:100
	ds_write2_b64 v148, v[104:105], v[84:85] offset0:128 offset1:132
	ds_write2_b64 v66, v[110:111], v[64:65] offset0:224 offset1:228
	ds_write2_b64 v66, v[46:47], v[0:1] offset0:232 offset1:236
	s_waitcnt lgkmcnt(0)
	s_barrier
; DI int tidx() { int t = __builtin_amdgcn_workitem_id_x(); asm volatile("" : "+v"(t)); return t; }
; DI unsigned cvtpk(float lo, float hi) { const f32x2_ v = {lo, hi}; return __builtin_bit_cast(unsigned, __builtin_convertvector(v, bf16x2_)); }
; DI float bflo(unsigned w) { return __uint_as_float(w << 16); }
; DI float bfhi(unsigned w) { return __uint_as_float(w & 0xffff0000u); }
; DI void phase6(const Params& p, const Sched& sched, unsigned char* smem) {
;     ...
;       const int tid = tidx();
; #pragma unroll
;       for (int i = 0; i < 16; ++i) {
;         const int c = tid + 256 * i, row = c >> 4, ch = (c & 15) * 8;
;         const size_t gi = (size_t)(tm * 256 + row) * 1024 + tn * 128 + ch;
;         const u32x4 sv = *(const u32x4*)(Ls + row * EST + ch);
;         const f32x4 x0 = *(const f32x4*)(p.x + gi), x1 = *(const f32x4*)(p.x + gi + 4);
;         u32x4 w;
;         w.x = cvtpk(x0[0] + bflo(sv.x), x0[1] + bfhi(sv.x)); w.y = cvtpk(x0[2] + bflo(sv.y), x0[3] + bfhi(sv.y));
;         w.z = cvtpk(x1[0] + bflo(sv.z), x1[1] + bfhi(sv.z)); w.w = cvtpk(x1[2] + bflo(sv.w), x1[3] + bfhi(sv.w));
;         *(u32x4*)(x1b + gi) = w;
;       }
	s_nop 0
	v_ashrrev_i32_e32 v3, 4, v2
	v_add_u32_e32 v4, s33, v3
	v_lshlrev_b32_e32 v0, 3, v2
	v_ashrrev_i32_e32 v5, 31, v4
	v_and_b32_e32 v1, 0x78, v0
	v_lshlrev_b64 v[16:17], 10, v[4:5]
	v_or3_b32 v16, v16, s34, v1
	v_lshl_add_u64 v[8:9], v[16:17], 2, s[76:77]
	global_load_dwordx4 v[4:7], v[8:9], off
	v_lshlrev_b32_e32 v0, 1, v1
	global_load_dwordx4 v[8:11], v[8:9], off offset:16
	v_mad_u64_u32 v[12:13], s[36:37], v3, s27, v[0:1]
	ds_read_b128 v[12:15], v12
	v_add_u32_e32 v3, 0x100, v2
	v_ashrrev_i32_e32 v3, 4, v3
	s_waitcnt lgkmcnt(0)
	v_lshlrev_b32_e32 v18, 16, v12
	v_and_b32_e32 v19, 0xffff0000, v12
	v_lshlrev_b32_e32 v12, 16, v13
	v_and_b32_e32 v13, 0xffff0000, v13
	s_waitcnt vmcnt(1)
	v_pk_add_f32 v[4:5], v[4:5], v[18:19]
	v_pk_add_f32 v[6:7], v[6:7], v[12:13]
	v_cvt_pk_bf16_f32 v4, v4, v5
	v_cvt_pk_bf16_f32 v5, v6, v7
	v_lshlrev_b32_e32 v6, 16, v14
	v_and_b32_e32 v7, 0xffff0000, v14
	s_waitcnt vmcnt(0)
	v_pk_add_f32 v[6:7], v[8:9], v[6:7]
	v_lshlrev_b32_e32 v8, 16, v15
	v_and_b32_e32 v9, 0xffff0000, v15
	v_pk_add_f32 v[8:9], v[10:11], v[8:9]
	v_cvt_pk_bf16_f32 v6, v6, v7
	v_cvt_pk_bf16_f32 v7, v8, v9
	v_lshl_add_u64 v[8:9], v[16:17], 1, s[12:13]
	global_store_dwordx4 v[8:9], v[4:7], off
	v_add_u32_e32 v12, 0x200, v2
	v_ashrrev_i32_e32 v26, 4, v12
	v_add_u32_e32 v4, s33, v3
	v_ashrrev_i32_e32 v5, 31, v4
	v_lshlrev_b64 v[16:17], 10, v[4:5]
	v_or3_b32 v16, v16, s34, v1
	v_lshl_add_u64 v[8:9], v[16:17], 2, s[76:77]
	global_load_dwordx4 v[4:7], v[8:9], off
	v_mad_u64_u32 v[12:13], s[36:37], v3, s27, v[0:1]
	global_load_dwordx4 v[8:11], v[8:9], off offset:16
	ds_read_b128 v[12:15], v12
	v_add_u32_e32 v18, s33, v26
	v_ashrrev_i32_e32 v19, 31, v18
	v_lshlrev_b64 v[18:19], 10, v[18:19]
	v_or3_b32 v18, v18, s34, v1
	s_waitcnt lgkmcnt(0)
	v_lshlrev_b32_e32 v22, 16, v12
	v_and_b32_e32 v23, 0xffff0000, v12
	v_lshlrev_b32_e32 v12, 16, v13
	v_and_b32_e32 v13, 0xffff0000, v13
	v_lshlrev_b32_e32 v24, 16, v14
	v_and_b32_e32 v25, 0xffff0000, v14
	v_lshlrev_b32_e32 v14, 16, v15
	v_and_b32_e32 v15, 0xffff0000, v15
	v_lshl_add_u64 v[16:17], v[16:17], 1, s[12:13]
	v_lshl_add_u64 v[20:21], v[18:19], 2, s[76:77]
	v_add_u32_e32 v3, 0x300, v2
	v_ashrrev_i32_e32 v3, 4, v3
	v_lshl_add_u64 v[18:19], v[18:19], 1, s[12:13]
	s_waitcnt vmcnt(1)
	v_pk_add_f32 v[4:5], v[4:5], v[22:23]
	v_pk_add_f32 v[6:7], v[6:7], v[12:13]
	v_cvt_pk_bf16_f32 v4, v4, v5
	s_waitcnt vmcnt(0)
	v_pk_add_f32 v[8:9], v[8:9], v[24:25]
	v_pk_add_f32 v[10:11], v[10:11], v[14:15]
	v_cvt_pk_bf16_f32 v5, v6, v7
	v_cvt_pk_bf16_f32 v6, v8, v9
	v_cvt_pk_bf16_f32 v7, v10, v11
	global_store_dwordx4 v[16:17], v[4:7], off
	global_load_dwordx4 v[4:7], v[20:21], off
	v_mad_u64_u32 v[12:13], s[36:37], v26, s27, v[0:1]
	global_load_dwordx4 v[8:11], v[20:21], off offset:16
	ds_read_b128 v[12:15], v12
	v_add_u32_e32 v16, s33, v3
	v_ashrrev_i32_e32 v17, 31, v16
	v_lshlrev_b64 v[16:17], 10, v[16:17]
	v_or3_b32 v16, v16, s34, v1
	s_waitcnt lgkmcnt(0)
	v_lshlrev_b32_e32 v22, 16, v12
	v_and_b32_e32 v23, 0xffff0000, v12
	v_lshlrev_b32_e32 v12, 16, v13
	v_and_b32_e32 v13, 0xffff0000, v13
	v_lshlrev_b32_e32 v24, 16, v14
	v_and_b32_e32 v25, 0xffff0000, v14
	v_lshlrev_b32_e32 v14, 16, v15
	v_and_b32_e32 v15, 0xffff0000, v15
	v_lshl_add_u64 v[20:21], v[16:17], 2, s[76:77]
	v_lshl_add_u64 v[16:17], v[16:17], 1, s[12:13]
	s_waitcnt vmcnt(1)
	v_pk_add_f32 v[4:5], v[4:5], v[22:23]
	v_pk_add_f32 v[6:7], v[6:7], v[12:13]
	v_cvt_pk_bf16_f32 v4, v4, v5
	s_waitcnt vmcnt(0)
	v_pk_add_f32 v[8:9], v[8:9], v[24:25]
	v_pk_add_f32 v[10:11], v[10:11], v[14:15]
	v_cvt_pk_bf16_f32 v5, v6, v7
	v_cvt_pk_bf16_f32 v6, v8, v9
	v_cvt_pk_bf16_f32 v7, v10, v11
	global_store_dwordx4 v[18:19], v[4:7], off
	global_load_dwordx4 v[4:7], v[20:21], off
	v_add_u32_e32 v12, 0x400, v2
	global_load_dwordx4 v[8:11], v[20:21], off offset:16
	v_ashrrev_i32_e32 v26, 4, v12
	v_mad_u64_u32 v[12:13], s[36:37], v3, s27, v[0:1]
	ds_read_b128 v[12:15], v12
	v_add_u32_e32 v18, s33, v26
	v_ashrrev_i32_e32 v19, 31, v18
	v_lshlrev_b64 v[18:19], 10, v[18:19]
	v_or3_b32 v18, v18, s34, v1
	s_waitcnt lgkmcnt(0)
	v_lshlrev_b32_e32 v22, 16, v12
	v_and_b32_e32 v23, 0xffff0000, v12
	v_lshlrev_b32_e32 v12, 16, v13
	v_and_b32_e32 v13, 0xffff0000, v13
	v_lshlrev_b32_e32 v24, 16, v14
	v_and_b32_e32 v25, 0xffff0000, v14
	v_lshlrev_b32_e32 v14, 16, v15
	v_and_b32_e32 v15, 0xffff0000, v15
	v_lshl_add_u64 v[20:21], v[18:19], 2, s[76:77]
	v_add_u32_e32 v3, 0x500, v2
	v_ashrrev_i32_e32 v3, 4, v3
	v_lshl_add_u64 v[18:19], v[18:19], 1, s[12:13]
	s_waitcnt vmcnt(1)
	v_pk_add_f32 v[4:5], v[4:5], v[22:23]
	v_pk_add_f32 v[6:7], v[6:7], v[12:13]
	s_waitcnt vmcnt(0)
	v_pk_add_f32 v[8:9], v[8:9], v[24:25]
	v_pk_add_f32 v[10:11], v[10:11], v[14:15]
	v_cvt_pk_bf16_f32 v4, v4, v5
	v_cvt_pk_bf16_f32 v5, v6, v7
	v_cvt_pk_bf16_f32 v6, v8, v9
	v_cvt_pk_bf16_f32 v7, v10, v11
	global_store_dwordx4 v[16:17], v[4:7], off
	global_load_dwordx4 v[4:7], v[20:21], off
	v_mad_u64_u32 v[12:13], s[36:37], v26, s27, v[0:1]
	global_load_dwordx4 v[8:11], v[20:21], off offset:16
	ds_read_b128 v[12:15], v12
	v_add_u32_e32 v16, s33, v3
	v_ashrrev_i32_e32 v17, 31, v16
	v_lshlrev_b64 v[16:17], 10, v[16:17]
	v_or3_b32 v16, v16, s34, v1
	s_waitcnt lgkmcnt(0)
	v_lshlrev_b32_e32 v22, 16, v12
	v_and_b32_e32 v23, 0xffff0000, v12
	v_lshlrev_b32_e32 v12, 16, v13
	v_and_b32_e32 v13, 0xffff0000, v13
	v_lshlrev_b32_e32 v24, 16, v14
	v_and_b32_e32 v25, 0xffff0000, v14
	v_lshlrev_b32_e32 v14, 16, v15
	v_and_b32_e32 v15, 0xffff0000, v15
	v_lshl_add_u64 v[20:21], v[16:17], 2, s[76:77]
	v_lshl_add_u64 v[16:17], v[16:17], 1, s[12:13]
	s_waitcnt vmcnt(1)
	v_pk_add_f32 v[4:5], v[4:5], v[22:23]
	v_pk_add_f32 v[6:7], v[6:7], v[12:13]
	v_cvt_pk_bf16_f32 v4, v4, v5
	s_waitcnt vmcnt(0)
; DI int tidx() { int t = __builtin_amdgcn_workitem_id_x(); asm volatile("" : "+v"(t)); return t; }
; DI unsigned cvtpk(float lo, float hi) { const f32x2_ v = {lo, hi}; return __builtin_bit_cast(unsigned, __builtin_convertvector(v, bf16x2_)); }
; DI float bflo(unsigned w) { return __uint_as_float(w << 16); }
; DI float bfhi(unsigned w) { return __uint_as_float(w & 0xffff0000u); }
; DI void phase6(const Params& p, const Sched& sched, unsigned char* smem) {
;     ...
;       const int tid = tidx();
; #pragma unroll
;       for (int i = 0; i < 16; ++i) {
;         const int c = tid + 256 * i, row = c >> 4, ch = (c & 15) * 8;
;         const size_t gi = (size_t)(tm * 256 + row) * 1024 + tn * 128 + ch;
;         const u32x4 sv = *(const u32x4*)(Ls + row * EST + ch);
;         const f32x4 x0 = *(const f32x4*)(p.x + gi), x1 = *(const f32x4*)(p.x + gi + 4);
;         u32x4 w;
;         w.x = cvtpk(x0[0] + bflo(sv.x), x0[1] + bfhi(sv.x)); w.y = cvtpk(x0[2] + bflo(sv.y), x0[3] + bfhi(sv.y));
;         w.z = cvtpk(x1[0] + bflo(sv.z), x1[1] + bfhi(sv.z)); w.w = cvtpk(x1[2] + bflo(sv.w), x1[3] + bfhi(sv.w));
;         *(u32x4*)(x1b + gi) = w;
;       }
	v_pk_add_f32 v[8:9], v[8:9], v[24:25]
	v_pk_add_f32 v[10:11], v[10:11], v[14:15]
	v_cvt_pk_bf16_f32 v5, v6, v7
	v_cvt_pk_bf16_f32 v6, v8, v9
	v_cvt_pk_bf16_f32 v7, v10, v11
	global_store_dwordx4 v[18:19], v[4:7], off
	global_load_dwordx4 v[4:7], v[20:21], off
	v_add_u32_e32 v12, 0x600, v2
	global_load_dwordx4 v[8:11], v[20:21], off offset:16
	v_ashrrev_i32_e32 v26, 4, v12
	v_mad_u64_u32 v[12:13], s[36:37], v3, s27, v[0:1]
	ds_read_b128 v[12:15], v12
	v_add_u32_e32 v18, s33, v26
	v_ashrrev_i32_e32 v19, 31, v18
	v_lshlrev_b64 v[18:19], 10, v[18:19]
	v_or3_b32 v18, v18, s34, v1
	s_waitcnt lgkmcnt(0)
	v_lshlrev_b32_e32 v22, 16, v12
	v_and_b32_e32 v23, 0xffff0000, v12
	v_lshlrev_b32_e32 v12, 16, v13
	v_and_b32_e32 v13, 0xffff0000, v13
	v_lshlrev_b32_e32 v24, 16, v14
	v_and_b32_e32 v25, 0xffff0000, v14
	v_lshlrev_b32_e32 v14, 16, v15
	v_and_b32_e32 v15, 0xffff0000, v15
	v_lshl_add_u64 v[20:21], v[18:19], 2, s[76:77]
	v_add_u32_e32 v3, 0x700, v2
	v_ashrrev_i32_e32 v3, 4, v3
	v_lshl_add_u64 v[18:19], v[18:19], 1, s[12:13]
	s_waitcnt vmcnt(1)
	v_pk_add_f32 v[4:5], v[4:5], v[22:23]
	v_pk_add_f32 v[6:7], v[6:7], v[12:13]
	s_waitcnt vmcnt(0)
	v_pk_add_f32 v[8:9], v[8:9], v[24:25]
	v_pk_add_f32 v[10:11], v[10:11], v[14:15]
	v_cvt_pk_bf16_f32 v4, v4, v5
	v_cvt_pk_bf16_f32 v5, v6, v7
	v_cvt_pk_bf16_f32 v6, v8, v9
	v_cvt_pk_bf16_f32 v7, v10, v11
	global_store_dwordx4 v[16:17], v[4:7], off
	global_load_dwordx4 v[4:7], v[20:21], off
	v_mad_u64_u32 v[12:13], s[36:37], v26, s27, v[0:1]
	global_load_dwordx4 v[8:11], v[20:21], off offset:16
	ds_read_b128 v[12:15], v12
	v_add_u32_e32 v16, s33, v3
	v_ashrrev_i32_e32 v17, 31, v16
	v_lshlrev_b64 v[16:17], 10, v[16:17]
	v_or3_b32 v16, v16, s34, v1
	s_waitcnt lgkmcnt(0)
	v_lshlrev_b32_e32 v22, 16, v12
	v_and_b32_e32 v23, 0xffff0000, v12
	v_lshlrev_b32_e32 v12, 16, v13
	v_and_b32_e32 v13, 0xffff0000, v13
	v_lshlrev_b32_e32 v24, 16, v14
	v_and_b32_e32 v25, 0xffff0000, v14
	v_lshlrev_b32_e32 v14, 16, v15
	v_and_b32_e32 v15, 0xffff0000, v15
	v_lshl_add_u64 v[20:21], v[16:17], 2, s[76:77]
	v_lshl_add_u64 v[16:17], v[16:17], 1, s[12:13]
	s_waitcnt vmcnt(1)
	v_pk_add_f32 v[4:5], v[4:5], v[22:23]
	v_pk_add_f32 v[6:7], v[6:7], v[12:13]
	v_cvt_pk_bf16_f32 v4, v4, v5
	s_waitcnt vmcnt(0)
	v_pk_add_f32 v[8:9], v[8:9], v[24:25]
	v_pk_add_f32 v[10:11], v[10:11], v[14:15]
	v_cvt_pk_bf16_f32 v5, v6, v7
	v_cvt_pk_bf16_f32 v6, v8, v9
	v_cvt_pk_bf16_f32 v7, v10, v11
	global_store_dwordx4 v[18:19], v[4:7], off
	global_load_dwordx4 v[4:7], v[20:21], off
	v_add_u32_e32 v12, 0x800, v2
	global_load_dwordx4 v[8:11], v[20:21], off offset:16
	v_ashrrev_i32_e32 v26, 4, v12
	v_mad_u64_u32 v[12:13], s[36:37], v3, s27, v[0:1]
	ds_read_b128 v[12:15], v12
	v_add_u32_e32 v18, s33, v26
	v_ashrrev_i32_e32 v19, 31, v18
	v_lshlrev_b64 v[18:19], 10, v[18:19]
	v_or3_b32 v18, v18, s34, v1
	s_waitcnt lgkmcnt(0)
	v_lshlrev_b32_e32 v22, 16, v12
	v_and_b32_e32 v23, 0xffff0000, v12
	v_lshlrev_b32_e32 v12, 16, v13
	v_and_b32_e32 v13, 0xffff0000, v13
	v_lshlrev_b32_e32 v24, 16, v14
	v_and_b32_e32 v25, 0xffff0000, v14
	v_lshlrev_b32_e32 v14, 16, v15
	v_and_b32_e32 v15, 0xffff0000, v15
	v_lshl_add_u64 v[20:21], v[18:19], 2, s[76:77]
	v_add_u32_e32 v3, 0x900, v2
	v_ashrrev_i32_e32 v3, 4, v3
	v_lshl_add_u64 v[18:19], v[18:19], 1, s[12:13]
	s_waitcnt vmcnt(1)
	v_pk_add_f32 v[4:5], v[4:5], v[22:23]
	v_pk_add_f32 v[6:7], v[6:7], v[12:13]
	s_waitcnt vmcnt(0)
	v_pk_add_f32 v[8:9], v[8:9], v[24:25]
	v_pk_add_f32 v[10:11], v[10:11], v[14:15]
	v_cvt_pk_bf16_f32 v4, v4, v5
	v_cvt_pk_bf16_f32 v5, v6, v7
	v_cvt_pk_bf16_f32 v6, v8, v9
	v_cvt_pk_bf16_f32 v7, v10, v11
	global_store_dwordx4 v[16:17], v[4:7], off
	global_load_dwordx4 v[4:7], v[20:21], off
	v_mad_u64_u32 v[12:13], s[36:37], v26, s27, v[0:1]
	global_load_dwordx4 v[8:11], v[20:21], off offset:16
	ds_read_b128 v[12:15], v12
	v_add_u32_e32 v16, s33, v3
	v_ashrrev_i32_e32 v17, 31, v16
	v_lshlrev_b64 v[16:17], 10, v[16:17]
	v_or3_b32 v16, v16, s34, v1
	s_waitcnt lgkmcnt(0)
	v_lshlrev_b32_e32 v22, 16, v12
	v_and_b32_e32 v23, 0xffff0000, v12
	v_lshlrev_b32_e32 v12, 16, v13
	v_and_b32_e32 v13, 0xffff0000, v13
	v_lshlrev_b32_e32 v24, 16, v14
	v_and_b32_e32 v25, 0xffff0000, v14
	v_lshlrev_b32_e32 v14, 16, v15
	v_and_b32_e32 v15, 0xffff0000, v15
	v_lshl_add_u64 v[20:21], v[16:17], 2, s[76:77]
	v_lshl_add_u64 v[16:17], v[16:17], 1, s[12:13]
	s_waitcnt vmcnt(1)
	v_pk_add_f32 v[4:5], v[4:5], v[22:23]
	v_pk_add_f32 v[6:7], v[6:7], v[12:13]
	v_cvt_pk_bf16_f32 v4, v4, v5
	s_waitcnt vmcnt(0)
	v_pk_add_f32 v[8:9], v[8:9], v[24:25]
	v_pk_add_f32 v[10:11], v[10:11], v[14:15]
	v_cvt_pk_bf16_f32 v5, v6, v7
	v_cvt_pk_bf16_f32 v6, v8, v9
	v_cvt_pk_bf16_f32 v7, v10, v11
	global_store_dwordx4 v[18:19], v[4:7], off
	global_load_dwordx4 v[4:7], v[20:21], off
	v_add_u32_e32 v12, 0xa00, v2
	global_load_dwordx4 v[8:11], v[20:21], off offset:16
	v_ashrrev_i32_e32 v26, 4, v12
	v_mad_u64_u32 v[12:13], s[36:37], v3, s27, v[0:1]
	ds_read_b128 v[12:15], v12
	v_add_u32_e32 v18, s33, v26
	v_ashrrev_i32_e32 v19, 31, v18
	v_lshlrev_b64 v[18:19], 10, v[18:19]
	v_or3_b32 v18, v18, s34, v1
	s_waitcnt lgkmcnt(0)
	v_lshlrev_b32_e32 v22, 16, v12
	v_and_b32_e32 v23, 0xffff0000, v12
	v_lshlrev_b32_e32 v12, 16, v13
	v_and_b32_e32 v13, 0xffff0000, v13
	v_lshlrev_b32_e32 v24, 16, v14
	v_and_b32_e32 v25, 0xffff0000, v14
	v_lshlrev_b32_e32 v14, 16, v15
	v_and_b32_e32 v15, 0xffff0000, v15
	v_lshl_add_u64 v[20:21], v[18:19], 2, s[76:77]
	v_add_u32_e32 v3, 0xb00, v2
	v_ashrrev_i32_e32 v3, 4, v3
	v_lshl_add_u64 v[18:19], v[18:19], 1, s[12:13]
	s_waitcnt vmcnt(1)
	v_pk_add_f32 v[4:5], v[4:5], v[22:23]
	v_pk_add_f32 v[6:7], v[6:7], v[12:13]
	s_waitcnt vmcnt(0)
; DI int tidx() { int t = __builtin_amdgcn_workitem_id_x(); asm volatile("" : "+v"(t)); return t; }
; DI unsigned cvtpk(float lo, float hi) { const f32x2_ v = {lo, hi}; return __builtin_bit_cast(unsigned, __builtin_convertvector(v, bf16x2_)); }
; DI float bflo(unsigned w) { return __uint_as_float(w << 16); }
; DI float bfhi(unsigned w) { return __uint_as_float(w & 0xffff0000u); }
; DI void phase6(const Params& p, const Sched& sched, unsigned char* smem) {
;     ...
;       const int tid = tidx();
; #pragma unroll
;       for (int i = 0; i < 16; ++i) {
;         const int c = tid + 256 * i, row = c >> 4, ch = (c & 15) * 8;
;         const size_t gi = (size_t)(tm * 256 + row) * 1024 + tn * 128 + ch;
;         const u32x4 sv = *(const u32x4*)(Ls + row * EST + ch);
;         const f32x4 x0 = *(const f32x4*)(p.x + gi), x1 = *(const f32x4*)(p.x + gi + 4);
;         u32x4 w;
;         w.x = cvtpk(x0[0] + bflo(sv.x), x0[1] + bfhi(sv.x)); w.y = cvtpk(x0[2] + bflo(sv.y), x0[3] + bfhi(sv.y));
;         w.z = cvtpk(x1[0] + bflo(sv.z), x1[1] + bfhi(sv.z)); w.w = cvtpk(x1[2] + bflo(sv.w), x1[3] + bfhi(sv.w));
;         *(u32x4*)(x1b + gi) = w;
;       }
	v_pk_add_f32 v[8:9], v[8:9], v[24:25]
	v_pk_add_f32 v[10:11], v[10:11], v[14:15]
	v_cvt_pk_bf16_f32 v4, v4, v5
	v_cvt_pk_bf16_f32 v5, v6, v7
	v_cvt_pk_bf16_f32 v6, v8, v9
	v_cvt_pk_bf16_f32 v7, v10, v11
	global_store_dwordx4 v[16:17], v[4:7], off
	global_load_dwordx4 v[4:7], v[20:21], off
	v_mad_u64_u32 v[12:13], s[36:37], v26, s27, v[0:1]
	global_load_dwordx4 v[8:11], v[20:21], off offset:16
	ds_read_b128 v[12:15], v12
	v_add_u32_e32 v16, s33, v3
	v_ashrrev_i32_e32 v17, 31, v16
	v_lshlrev_b64 v[16:17], 10, v[16:17]
	v_or3_b32 v16, v16, s34, v1
	s_waitcnt lgkmcnt(0)
	v_lshlrev_b32_e32 v22, 16, v12
	v_and_b32_e32 v23, 0xffff0000, v12
	v_lshlrev_b32_e32 v12, 16, v13
	v_and_b32_e32 v13, 0xffff0000, v13
	v_lshlrev_b32_e32 v24, 16, v14
	v_and_b32_e32 v25, 0xffff0000, v14
	v_lshlrev_b32_e32 v14, 16, v15
	v_and_b32_e32 v15, 0xffff0000, v15
	v_lshl_add_u64 v[20:21], v[16:17], 2, s[76:77]
	v_lshl_add_u64 v[16:17], v[16:17], 1, s[12:13]
	s_waitcnt vmcnt(1)
	v_pk_add_f32 v[4:5], v[4:5], v[22:23]
	v_pk_add_f32 v[6:7], v[6:7], v[12:13]
	v_cvt_pk_bf16_f32 v4, v4, v5
	s_waitcnt vmcnt(0)
	v_pk_add_f32 v[8:9], v[8:9], v[24:25]
	v_pk_add_f32 v[10:11], v[10:11], v[14:15]
	v_cvt_pk_bf16_f32 v5, v6, v7
	v_cvt_pk_bf16_f32 v6, v8, v9
	v_cvt_pk_bf16_f32 v7, v10, v11
	global_store_dwordx4 v[18:19], v[4:7], off
	global_load_dwordx4 v[4:7], v[20:21], off
	v_add_u32_e32 v12, 0xc00, v2
	global_load_dwordx4 v[8:11], v[20:21], off offset:16
	v_ashrrev_i32_e32 v26, 4, v12
	v_mad_u64_u32 v[12:13], s[36:37], v3, s27, v[0:1]
	ds_read_b128 v[12:15], v12
	v_add_u32_e32 v18, s33, v26
	v_ashrrev_i32_e32 v19, 31, v18
	v_lshlrev_b64 v[18:19], 10, v[18:19]
	v_or3_b32 v18, v18, s34, v1
	s_waitcnt lgkmcnt(0)
	v_lshlrev_b32_e32 v22, 16, v12
	v_and_b32_e32 v23, 0xffff0000, v12
	v_lshlrev_b32_e32 v12, 16, v13
	v_and_b32_e32 v13, 0xffff0000, v13
	v_lshlrev_b32_e32 v24, 16, v14
	v_and_b32_e32 v25, 0xffff0000, v14
	v_lshlrev_b32_e32 v14, 16, v15
	v_and_b32_e32 v15, 0xffff0000, v15
	v_lshl_add_u64 v[20:21], v[18:19], 2, s[76:77]
	v_add_u32_e32 v3, 0xd00, v2
	v_ashrrev_i32_e32 v3, 4, v3
	v_lshl_add_u64 v[18:19], v[18:19], 1, s[12:13]
	s_waitcnt vmcnt(1)
	v_pk_add_f32 v[4:5], v[4:5], v[22:23]
	v_pk_add_f32 v[6:7], v[6:7], v[12:13]
	s_waitcnt vmcnt(0)
	v_pk_add_f32 v[8:9], v[8:9], v[24:25]
	v_pk_add_f32 v[10:11], v[10:11], v[14:15]
	v_cvt_pk_bf16_f32 v4, v4, v5
	v_cvt_pk_bf16_f32 v5, v6, v7
	v_cvt_pk_bf16_f32 v6, v8, v9
	v_cvt_pk_bf16_f32 v7, v10, v11
	global_store_dwordx4 v[16:17], v[4:7], off
	global_load_dwordx4 v[4:7], v[20:21], off
	v_mad_u64_u32 v[12:13], s[36:37], v26, s27, v[0:1]
	global_load_dwordx4 v[8:11], v[20:21], off offset:16
	ds_read_b128 v[12:15], v12
	v_add_u32_e32 v16, s33, v3
	v_ashrrev_i32_e32 v17, 31, v16
	v_lshlrev_b64 v[16:17], 10, v[16:17]
	v_or3_b32 v16, v16, s34, v1
	s_waitcnt lgkmcnt(0)
	v_lshlrev_b32_e32 v22, 16, v12
	v_and_b32_e32 v23, 0xffff0000, v12
	v_lshlrev_b32_e32 v12, 16, v13
	v_and_b32_e32 v13, 0xffff0000, v13
	v_lshlrev_b32_e32 v24, 16, v14
	v_and_b32_e32 v25, 0xffff0000, v14
	v_lshlrev_b32_e32 v14, 16, v15
	v_and_b32_e32 v15, 0xffff0000, v15
	v_lshl_add_u64 v[20:21], v[16:17], 2, s[76:77]
	v_lshl_add_u64 v[16:17], v[16:17], 1, s[12:13]
	s_waitcnt vmcnt(1)
	v_pk_add_f32 v[4:5], v[4:5], v[22:23]
	v_pk_add_f32 v[6:7], v[6:7], v[12:13]
	v_cvt_pk_bf16_f32 v4, v4, v5
	s_waitcnt vmcnt(0)
	v_pk_add_f32 v[8:9], v[8:9], v[24:25]
	v_pk_add_f32 v[10:11], v[10:11], v[14:15]
	v_cvt_pk_bf16_f32 v5, v6, v7
	v_cvt_pk_bf16_f32 v6, v8, v9
	v_cvt_pk_bf16_f32 v7, v10, v11
	global_store_dwordx4 v[18:19], v[4:7], off
	global_load_dwordx4 v[4:7], v[20:21], off
	v_add_u32_e32 v12, 0xe00, v2
	global_load_dwordx4 v[8:11], v[20:21], off offset:16
	v_ashrrev_i32_e32 v26, 4, v12
	v_mad_u64_u32 v[12:13], s[36:37], v3, s27, v[0:1]
	ds_read_b128 v[12:15], v12
	v_add_u32_e32 v18, s33, v26
	v_ashrrev_i32_e32 v19, 31, v18
	v_lshlrev_b64 v[18:19], 10, v[18:19]
	v_or3_b32 v18, v18, s34, v1
	s_waitcnt lgkmcnt(0)
	v_lshlrev_b32_e32 v22, 16, v12
	v_and_b32_e32 v23, 0xffff0000, v12
	v_lshlrev_b32_e32 v12, 16, v13
	v_and_b32_e32 v13, 0xffff0000, v13
	v_lshlrev_b32_e32 v24, 16, v14
	v_and_b32_e32 v25, 0xffff0000, v14
	v_lshlrev_b32_e32 v14, 16, v15
	v_and_b32_e32 v15, 0xffff0000, v15
	v_lshl_add_u64 v[20:21], v[18:19], 2, s[76:77]
	v_add_u32_e32 v2, 0xf00, v2
	v_lshl_add_u64 v[18:19], v[18:19], 1, s[12:13]
	s_waitcnt vmcnt(1)
	v_pk_add_f32 v[4:5], v[4:5], v[22:23]
	v_pk_add_f32 v[6:7], v[6:7], v[12:13]
	s_waitcnt vmcnt(0)
	v_pk_add_f32 v[8:9], v[8:9], v[24:25]
	v_pk_add_f32 v[10:11], v[10:11], v[14:15]
	v_cvt_pk_bf16_f32 v4, v4, v5
	v_cvt_pk_bf16_f32 v5, v6, v7
	v_cvt_pk_bf16_f32 v6, v8, v9
	v_cvt_pk_bf16_f32 v7, v10, v11
	global_store_dwordx4 v[16:17], v[4:7], off
	global_load_dwordx4 v[4:7], v[20:21], off
	v_mad_u64_u32 v[12:13], s[36:37], v26, s27, v[0:1]
	global_load_dwordx4 v[8:11], v[20:21], off offset:16
	ds_read_b128 v[12:15], v12
	v_ashrrev_i32_e32 v24, 4, v2
	v_add_u32_e32 v2, s33, v24
	v_ashrrev_i32_e32 v3, 31, v2
	v_lshlrev_b64 v[16:17], 10, v[2:3]
	s_waitcnt lgkmcnt(0)
	v_lshlrev_b32_e32 v2, 16, v12
	v_and_b32_e32 v3, 0xffff0000, v12
	v_lshlrev_b32_e32 v12, 16, v13
	v_and_b32_e32 v13, 0xffff0000, v13
	v_lshlrev_b32_e32 v22, 16, v14
	v_and_b32_e32 v23, 0xffff0000, v14
	v_lshlrev_b32_e32 v14, 16, v15
	v_and_b32_e32 v15, 0xffff0000, v15
	v_or3_b32 v16, v16, s34, v1
	v_lshl_add_u64 v[20:21], v[16:17], 2, s[76:77]
	v_mad_u64_u32 v[0:1], s[34:35], v24, s27, v[0:1]
	s_waitcnt vmcnt(1)
	v_pk_add_f32 v[2:3], v[4:5], v[2:3]
	v_pk_add_f32 v[4:5], v[6:7], v[12:13]
	v_cvt_pk_bf16_f32 v2, v2, v3
	s_waitcnt vmcnt(0)
	v_pk_add_f32 v[6:7], v[8:9], v[22:23]
	v_pk_add_f32 v[8:9], v[10:11], v[14:15]
	v_cvt_pk_bf16_f32 v3, v4, v5
	v_cvt_pk_bf16_f32 v4, v6, v7
	v_cvt_pk_bf16_f32 v5, v8, v9
	global_store_dwordx4 v[18:19], v[2:5], off
	global_load_dwordx4 v[2:5], v[20:21], off
	ds_read_b128 v[10:13], v0
	global_load_dwordx4 v[6:9], v[20:21], off offset:16
	v_lshl_add_u64 v[14:15], v[16:17], 1, s[12:13]
	s_waitcnt lgkmcnt(0)
	v_lshlrev_b32_e32 v0, 16, v10
	v_and_b32_e32 v1, 0xffff0000, v10
	v_lshlrev_b32_e32 v10, 16, v11
	v_and_b32_e32 v11, 0xffff0000, v11
	v_lshlrev_b32_e32 v16, 16, v12
	v_and_b32_e32 v17, 0xffff0000, v12
	v_lshlrev_b32_e32 v12, 16, v13
	v_and_b32_e32 v13, 0xffff0000, v13
	s_waitcnt vmcnt(1)
	v_pk_add_f32 v[0:1], v[2:3], v[0:1]
	v_pk_add_f32 v[2:3], v[4:5], v[10:11]
	s_waitcnt vmcnt(0)
	v_pk_add_f32 v[4:5], v[6:7], v[16:17]
	v_pk_add_f32 v[6:7], v[8:9], v[12:13]
	v_cvt_pk_bf16_f32 v0, v0, v1
	v_cvt_pk_bf16_f32 v1, v2, v3
	v_cvt_pk_bf16_f32 v2, v4, v5
	v_cvt_pk_bf16_f32 v3, v6, v7
	global_store_dwordx4 v[14:15], v[0:3], off
	s_cbranch_scc0 .LBB0_811
	s_branch .LBB0_808

; DI int tidx() { int t = __builtin_amdgcn_workitem_id_x(); asm volatile("" : "+v"(t)); return t; }
;   DI unsigned rowoff(int r, int sch) const { const int g = r & 3, bc = r >> 2, b = bc / NCMP, c = bc - b * NCMP; return (unsigned)(b * Sn + c * 16) * 512u + g * 64 + sch; }
; template <int NI, class XL, class EP>
; DI void gemm_tile(const u16* __restrict__ W, int ldw, int f0, int t0, int K, XL xl, EP ep, unsigned char* smem) {
;     ...
;   const int tid = tidx(), lane = tid & 63, wave = tid >> 6;
;   const int wf = wave >> 1, wt = wave & 1, lr = lane & 15, lq = lane >> 4;
;   const int srow = tid >> 2, sch = (tid & 3) * 8;
;   f32x4 acc[4][NI];
; #pragma unroll
;   for (int i = 0; i < 4; ++i)
; #pragma unroll
;     for (int j = 0; j < NI; ++j) acc[i][j] = (f32x4){0.f, 0.f, 0.f, 0.f};
;   u32x4 wr[2], xr[XR];
;   const unsigned wbyte = ((unsigned)(f0 + srow * 2) * 32u + sch) * 2u;
;   const unsigned xbyte = xl.rowoff(t0 + srow * XR, sch) * 2u;
;   const int xrs = xl.rstride();
;   const int nk = K >> 5;
;   auto gload = [&](int it) {
;     const int k = it * 32;
;     const char* wb = (const char*)(W + (size_t)(k >> 5) * ldw * 32);
;     const char* xb = (const char*)xl.kbase(k);
; #pragma unroll
;     for (int i = 0; i < 2; ++i) wr[i] = *(const u32x4*)(wb + wbyte + i * 64);
; #pragma unroll
;     for (int i = 0; i < XR; ++i) xr[i] = *(const u32x4*)(xb + xbyte + i * xrs);
;   };
;   auto lstore = [&](int buf) {
;     u16* Ws = S0 + buf * BUF; u16* Xs = Ws + 128 * LST;
; #pragma unroll
;     for (int i = 0; i < 2; ++i) *(u32x4*)(Ws + (srow * 2 + i) * LST + sch) = wr[i];
; #pragma unroll
;     for (int i = 0; i < XR; ++i) *(u32x4*)(Xs + (srow * XR + i) * LST + sch) = xr[i];
;   };
;   gload(0);
;   __syncthreads();
;   lstore(0);
;   __syncthreads();
;   if (nk > 1) gload(1);
.LBB0_944:
	s_ashr_i32 s4, s55, 2
	v_mov_b32_e32 v48, v218
	s_add_i32 s30, s4, s51
	s_and_b32 s4, s55, 3
	s_or_b32 s56, s4, s52
	v_ashrrev_i32_e32 v49, 2, v48
	v_lshlrev_b32_e32 v0, 3, v48
	v_lshlrev_b32_e32 v51, 6, v49
	v_and_b32_e32 v50, 24, v0
	v_lshl_add_u32 v0, s56, 12, v51
	v_or_b32_e32 v0, v0, v50
	v_lshlrev_b32_e32 v54, 1, v0
	v_lshlrev_b32_e32 v0, 6, v48
	v_and_b32_e32 v0, 0xffffff00, v0
	v_lshl_add_u32 v0, s30, 14, v0
	v_lshlrev_b32_e32 v171, 1, v50
	v_readlane_b32 s4, v245, 25
	v_or_b32_e32 v152, v0, v171
	v_readlane_b32 s5, v245, 26
	global_load_dwordx4 v[16:19], v54, s[60:61]
	global_load_dwordx4 v[20:23], v54, s[60:61] offset:64
	s_nop 2
	global_load_dwordx4 v[24:27], v152, s[4:5]
	global_load_dwordx4 v[28:31], v152, s[4:5] offset:64
	global_load_dwordx4 v[32:35], v152, s[4:5] offset:128
	global_load_dwordx4 v[36:39], v152, s[4:5] offset:192
	v_mul_lo_u32 v174, v49, s37
	v_or_b32_e32 v170, v174, v171
	v_add_u32_e32 v169, v170, v174
	s_barrier
	s_and_b32 s5, s54, 3
	s_add_i32 s5, s53, s5
	v_bfe_u32 v168, v48, 4, 2
	v_ashrrev_i32_e32 v155, 7, v48
	v_and_b32_e32 v55, 15, v48
	v_lshlrev_b32_e32 v48, 1, v48
	v_and_or_b32 v154, v48, s44, v55
	v_lshl_add_u32 v48, s5, 12, v51
	v_mov_b32_e32 v0, 0
	v_lshl_or_b32 v49, v155, 6, v55
	v_or_b32_e32 v48, v48, v50
	s_mov_b32 s4, 1
	v_mov_b32_e32 v157, v153
	v_mov_b32_e32 v1, v0
	v_mov_b32_e32 v2, v0
	v_mov_b32_e32 v3, v0
	v_mov_b32_e32 v4, v0
	v_mov_b32_e32 v5, v0
	v_mov_b32_e32 v6, v0
	v_mov_b32_e32 v7, v0
	v_mov_b32_e32 v8, v0
	v_mov_b32_e32 v9, v0
	v_mov_b32_e32 v10, v0
	v_mov_b32_e32 v11, v0
	v_mov_b32_e32 v12, v0
	v_mov_b32_e32 v13, v0
	v_mov_b32_e32 v14, v0
	v_mov_b32_e32 v15, v0
	v_mov_b32_e32 v40, v0
	v_mov_b32_e32 v41, v0
	v_mov_b32_e32 v42, v0
	v_mov_b32_e32 v43, v0
	v_mov_b32_e32 v44, v0
	v_mov_b32_e32 v45, v0
	v_mov_b32_e32 v46, v0
	v_mov_b32_e32 v47, v0
	v_mov_b32_e32 v52, v0
	v_mov_b32_e32 v53, v0
	v_lshlrev_b32_e32 v172, 4, v168
	v_mul_lo_u32 v175, v49, 48
	v_mul_u32_u24_e32 v173, 48, v154
	v_lshlrev_b32_e32 v156, 1, v48
	v_mov_b64_e32 v[158:159], v[152:153]
	v_mov_b32_e32 v55, v0
	v_mov_b32_e32 v80, v0
	v_mov_b32_e32 v81, v0
	v_mov_b32_e32 v82, v0
	v_mov_b32_e32 v83, v0
	v_mov_b32_e32 v48, v0
	v_mov_b32_e32 v49, v0
	v_mov_b32_e32 v50, v0
	v_mov_b32_e32 v51, v0
	v_mov_b32_e32 v56, v0
	v_mov_b32_e32 v57, v0
	v_mov_b32_e32 v58, v0
	v_mov_b32_e32 v59, v0
	v_mov_b32_e32 v60, v0
	v_mov_b32_e32 v61, v0
	v_mov_b32_e32 v62, v0
	v_mov_b32_e32 v63, v0
	v_mov_b32_e32 v68, v0
	s_waitcnt vmcnt(5)
	ds_write_b128 v170, v[16:19]
	s_waitcnt vmcnt(4)
	ds_write_b128 v170, v[20:23] offset:96
	s_waitcnt vmcnt(3)
	ds_write_b128 v169, v[24:27] offset:12288
	s_waitcnt vmcnt(2)
	ds_write_b128 v169, v[28:31] offset:12384
	s_waitcnt vmcnt(1)
	ds_write_b128 v169, v[32:35] offset:12480
	s_waitcnt vmcnt(0)
	ds_write_b128 v169, v[36:39] offset:12576
	s_waitcnt lgkmcnt(0)
	s_barrier
	global_load_dwordx4 v[20:23], v54, s[20:21]
	global_load_dwordx4 v[16:19], v54, s[20:21] offset:64
	global_load_dwordx4 v[36:39], v152, s[18:19]
	global_load_dwordx4 v[32:35], v152, s[18:19] offset:64
	global_load_dwordx4 v[28:31], v152, s[18:19] offset:128
	global_load_dwordx4 v[24:27], v152, s[18:19] offset:192
	s_add_u32 s98, s42, s45
	s_addc_u32 s99, s43, 0
	s_add_u32 s100, s42, s46
	s_addc_u32 s101, s43, 0
	global_load_dwordx4 v[200:203], v156, s[98:99]
	global_load_dwordx4 v[204:207], v156, s[98:99] offset:64
	global_load_dwordx4 v[208:211], v158, s[100:101] offset:2048
	global_load_dwordx4 v[212:215], v158, s[100:101] offset:2112
	global_load_dwordx4 v[220:223], v158, s[100:101] offset:2176
	global_load_dwordx4 v[224:227], v158, s[100:101] offset:2240
	s_add_u32 s98, s98, s28
	s_addc_u32 s99, s99, s29
	s_add_u32 s100, s100, s26
	s_addc_u32 s101, s101, s27
	v_mov_b32_e32 v54, v0
	v_mov_b32_e32 v69, v0
	v_mov_b32_e32 v70, v0
	v_mov_b32_e32 v71, v0
	v_mov_b32_e32 v76, v0
	v_mov_b32_e32 v77, v0
	v_mov_b32_e32 v78, v0
	v_mov_b32_e32 v79, v0
	v_mov_b32_e32 v88, v0
	v_mov_b32_e32 v89, v0
	v_mov_b32_e32 v90, v0
	v_mov_b32_e32 v91, v0
	v_mov_b32_e32 v100, v0
	v_mov_b32_e32 v101, v0
	v_mov_b32_e32 v102, v0
	v_mov_b32_e32 v103, v0
	v_mov_b32_e32 v112, v0
	v_mov_b32_e32 v113, v0
	v_mov_b32_e32 v114, v0
	v_mov_b32_e32 v115, v0
	v_mov_b32_e32 v64, v0
	v_mov_b32_e32 v65, v0
	v_mov_b32_e32 v66, v0
	v_mov_b32_e32 v67, v0
	v_mov_b32_e32 v72, v0
	v_mov_b32_e32 v73, v0
	v_mov_b32_e32 v74, v0
	v_mov_b32_e32 v75, v0
	v_mov_b32_e32 v84, v0
	v_mov_b32_e32 v85, v0
	v_mov_b32_e32 v86, v0
	v_mov_b32_e32 v87, v0
	v_mov_b32_e32 v96, v0
	v_mov_b32_e32 v97, v0
	v_mov_b32_e32 v98, v0
	v_mov_b32_e32 v99, v0
	v_mov_b32_e32 v108, v0
	v_mov_b32_e32 v109, v0
	v_mov_b32_e32 v110, v0
	v_mov_b32_e32 v111, v0
	v_mov_b32_e32 v120, v0
	v_mov_b32_e32 v121, v0
	v_mov_b32_e32 v122, v0
	v_mov_b32_e32 v123, v0
	v_mov_b32_e32 v128, v0
	v_mov_b32_e32 v129, v0
	v_mov_b32_e32 v130, v0
	v_mov_b32_e32 v131, v0
	v_mov_b32_e32 v136, v0
	v_mov_b32_e32 v137, v0
	v_mov_b32_e32 v138, v0
	v_mov_b32_e32 v139, v0
	v_mov_b32_e32 v92, v0
	v_mov_b32_e32 v93, v0
	v_mov_b32_e32 v94, v0
	v_mov_b32_e32 v95, v0
	v_mov_b32_e32 v104, v0
	v_mov_b32_e32 v105, v0
	v_mov_b32_e32 v106, v0
	v_mov_b32_e32 v107, v0
	v_mov_b32_e32 v116, v0
	v_mov_b32_e32 v117, v0
	v_mov_b32_e32 v118, v0
	v_mov_b32_e32 v119, v0
	v_mov_b32_e32 v124, v0
	v_mov_b32_e32 v125, v0
	v_mov_b32_e32 v126, v0
	v_mov_b32_e32 v127, v0
	v_mov_b32_e32 v132, v0
	v_mov_b32_e32 v133, v0
	v_mov_b32_e32 v134, v0
	v_mov_b32_e32 v135, v0
	v_mov_b32_e32 v140, v0
	v_mov_b32_e32 v141, v0
	v_mov_b32_e32 v142, v0
	v_mov_b32_e32 v143, v0
	v_mov_b32_e32 v144, v0
	v_mov_b32_e32 v145, v0
	v_mov_b32_e32 v146, v0
	v_mov_b32_e32 v147, v0
	v_mov_b32_e32 v148, v0
	v_mov_b32_e32 v149, v0
	v_mov_b32_e32 v150, v0
	v_mov_b32_e32 v151, v0
	v_lshl_add_u32 v228, v175, 1, v172
	v_lshl_add_u32 v152, v173, 1, v172
	v_add_u32_e32 v229, v174, v171
	v_add_u32_e32 v230, v229, v174
; DI f32x4 mfma16(bf16x8 a, bf16x8 b, f32x4 c) { return __builtin_amdgcn_mfma_f32_16x16x32_bf16(a, b, c, 0, 0, 0); }
; template <int NI, class XL, class EP>
; DI void gemm_tile(const u16* __restrict__ W, int ldw, int f0, int t0, int K, XL xl, EP ep, unsigned char* smem) {
;     ...
;   for (int it = 0; it < nk; ++it) {
;     const u16* Ws = S0 + (it & 1) * BUF; const u16* Xs = Ws + 128 * LST;
;     __builtin_amdgcn_s_setprio(1);
;     bf16x8 a[4];
; #pragma unroll
;     for (int mi = 0; mi < 4; ++mi) a[mi] = *(const bf16x8*)(Ws + (wf * 64 + mi * 16 + lr) * LST + lq * 8);
; #pragma unroll
;     for (int ni = 0; ni < NI; ++ni) {
;       const bf16x8 b = *(const bf16x8*)(Xs + (wt * (NI * 16) + ni * 16 + lr) * LST + lq * 8);
; #pragma unroll
;       for (int mi = 0; mi < 4; ++mi) acc[mi][ni] = mfma16(a[mi], b, acc[mi][ni]);
;     }
;     __builtin_amdgcn_sched_group_barrier(0x100, 6, 0);
; #pragma unroll
;     for (int ni = 0; ni < NI; ++ni) { __builtin_amdgcn_sched_group_barrier(0x008, 4, 0); if (ni + 2 < NI) __builtin_amdgcn_sched_group_barrier(0x100, 1, 0); }
;     __builtin_amdgcn_s_setprio(0);
;     if (it + 1 < nk) lstore((it + 1) & 1);
;     if (it + 2 < nk) gload(it + 2);
;     __syncthreads();
.LBB0_945:
	s_setprio 1
	ds_read_b128 v[176:179], v228 offset:0
	ds_read_b128 v[180:183], v228 offset:1536
	ds_read_b128 v[188:191], v228 offset:3072
	ds_read_b128 v[192:195], v228 offset:4608
	ds_read_b128 v[184:187], v152 offset:12288
	ds_read_b128 v[196:199], v152 offset:13824
	s_waitcnt lgkmcnt(1)
	v_mfma_f32_16x16x32_bf16 v[148:151], v[176:179], v[184:187], v[148:151]
	v_mfma_f32_16x16x32_bf16 v[136:139], v[180:183], v[184:187], v[136:139]
	v_mfma_f32_16x16x32_bf16 v[112:115], v[188:191], v[184:187], v[112:115]
	v_mfma_f32_16x16x32_bf16 v[80:83], v[192:195], v[184:187], v[80:83]
	ds_read_b128 v[184:187], v152 offset:15360
	s_waitcnt vmcnt(6)
	ds_write_b128 v229, v[20:23] offset:36864
	s_waitcnt lgkmcnt(2)
	v_mfma_f32_16x16x32_bf16 v[144:147], v[176:179], v[196:199], v[144:147]
	v_mfma_f32_16x16x32_bf16 v[128:131], v[180:183], v[196:199], v[128:131]
	v_mfma_f32_16x16x32_bf16 v[100:103], v[188:191], v[196:199], v[100:103]
	v_mfma_f32_16x16x32_bf16 v[52:55], v[192:195], v[196:199], v[52:55]
	ds_read_b128 v[196:199], v152 offset:16896
	ds_write_b128 v229, v[16:19] offset:36960
	global_load_dwordx4 v[20:23], v156, s[98:99]
	global_load_dwordx4 v[16:19], v156, s[98:99] offset:64
	s_waitcnt lgkmcnt(3)
	v_mfma_f32_16x16x32_bf16 v[140:143], v[176:179], v[184:187], v[140:143]
	v_mfma_f32_16x16x32_bf16 v[120:123], v[180:183], v[184:187], v[120:123]
	v_mfma_f32_16x16x32_bf16 v[88:91], v[188:191], v[184:187], v[88:91]
	v_mfma_f32_16x16x32_bf16 v[44:47], v[192:195], v[184:187], v[44:47]
	ds_read_b128 v[184:187], v152 offset:18432
	ds_write_b128 v230, v[36:39] offset:49152
	global_load_dwordx4 v[36:39], v158, s[100:101] offset:2048
	s_waitcnt lgkmcnt(3)
	v_mfma_f32_16x16x32_bf16 v[132:135], v[176:179], v[196:199], v[132:135]
	v_mfma_f32_16x16x32_bf16 v[108:111], v[180:183], v[196:199], v[108:111]
	v_mfma_f32_16x16x32_bf16 v[76:79], v[188:191], v[196:199], v[76:79]
	v_mfma_f32_16x16x32_bf16 v[40:43], v[192:195], v[196:199], v[40:43]
	ds_read_b128 v[196:199], v152 offset:19968
	ds_write_b128 v230, v[32:35] offset:49248
	global_load_dwordx4 v[32:35], v158, s[100:101] offset:2112
	s_waitcnt lgkmcnt(3)
	v_mfma_f32_16x16x32_bf16 v[124:127], v[176:179], v[184:187], v[124:127]
	v_mfma_f32_16x16x32_bf16 v[96:99], v[180:183], v[184:187], v[96:99]
	v_mfma_f32_16x16x32_bf16 v[68:71], v[188:191], v[184:187], v[68:71]
	v_mfma_f32_16x16x32_bf16 v[12:15], v[192:195], v[184:187], v[12:15]
	ds_read_b128 v[184:187], v152 offset:21504
	ds_write_b128 v230, v[28:31] offset:49344
	global_load_dwordx4 v[28:31], v158, s[100:101] offset:2176
	s_waitcnt lgkmcnt(3)
	v_mfma_f32_16x16x32_bf16 v[116:119], v[176:179], v[196:199], v[116:119]
	v_mfma_f32_16x16x32_bf16 v[84:87], v[180:183], v[196:199], v[84:87]
	v_mfma_f32_16x16x32_bf16 v[60:63], v[188:191], v[196:199], v[60:63]
	v_mfma_f32_16x16x32_bf16 v[8:11], v[192:195], v[196:199], v[8:11]
	ds_read_b128 v[196:199], v152 offset:23040
	ds_write_b128 v230, v[24:27] offset:49440
	global_load_dwordx4 v[24:27], v158, s[100:101] offset:2240
	s_waitcnt lgkmcnt(3)
	v_mfma_f32_16x16x32_bf16 v[104:107], v[176:179], v[184:187], v[104:107]
	v_mfma_f32_16x16x32_bf16 v[72:75], v[180:183], v[184:187], v[72:75]
	v_mfma_f32_16x16x32_bf16 v[56:59], v[188:191], v[184:187], v[56:59]
	v_mfma_f32_16x16x32_bf16 v[4:7], v[192:195], v[184:187], v[4:7]
	s_add_u32 s98, s98, s28
	s_addc_u32 s99, s99, s29
	s_add_u32 s100, s100, s26
	s_addc_u32 s101, s101, s27
	s_waitcnt lgkmcnt(1)
	v_mfma_f32_16x16x32_bf16 v[92:95], v[176:179], v[196:199], v[92:95]
	v_mfma_f32_16x16x32_bf16 v[64:67], v[180:183], v[196:199], v[64:67]
	v_mfma_f32_16x16x32_bf16 v[48:51], v[188:191], v[196:199], v[48:51]
	v_mfma_f32_16x16x32_bf16 v[0:3], v[192:195], v[196:199], v[0:3]
	s_setprio 0
	s_waitcnt lgkmcnt(0)
	s_barrier
	s_setprio 1
	ds_read_b128 v[176:179], v228 offset:36864
	ds_read_b128 v[180:183], v228 offset:38400
	ds_read_b128 v[188:191], v228 offset:39936
	ds_read_b128 v[192:195], v228 offset:41472
	ds_read_b128 v[184:187], v152 offset:49152
	ds_read_b128 v[196:199], v152 offset:50688
	s_waitcnt lgkmcnt(1)
	v_mfma_f32_16x16x32_bf16 v[148:151], v[176:179], v[184:187], v[148:151]
	v_mfma_f32_16x16x32_bf16 v[136:139], v[180:183], v[184:187], v[136:139]
	v_mfma_f32_16x16x32_bf16 v[112:115], v[188:191], v[184:187], v[112:115]
	v_mfma_f32_16x16x32_bf16 v[80:83], v[192:195], v[184:187], v[80:83]
	ds_read_b128 v[184:187], v152 offset:52224
	s_waitcnt vmcnt(6)
	ds_write_b128 v229, v[200:203] offset:0
	s_waitcnt lgkmcnt(2)
	v_mfma_f32_16x16x32_bf16 v[144:147], v[176:179], v[196:199], v[144:147]
	v_mfma_f32_16x16x32_bf16 v[128:131], v[180:183], v[196:199], v[128:131]
	v_mfma_f32_16x16x32_bf16 v[100:103], v[188:191], v[196:199], v[100:103]
	v_mfma_f32_16x16x32_bf16 v[52:55], v[192:195], v[196:199], v[52:55]
	ds_read_b128 v[196:199], v152 offset:53760
	ds_write_b128 v229, v[204:207] offset:96
	global_load_dwordx4 v[200:203], v156, s[98:99]
	global_load_dwordx4 v[204:207], v156, s[98:99] offset:64
	s_waitcnt lgkmcnt(3)
	v_mfma_f32_16x16x32_bf16 v[140:143], v[176:179], v[184:187], v[140:143]
	v_mfma_f32_16x16x32_bf16 v[120:123], v[180:183], v[184:187], v[120:123]
	v_mfma_f32_16x16x32_bf16 v[88:91], v[188:191], v[184:187], v[88:91]
	v_mfma_f32_16x16x32_bf16 v[44:47], v[192:195], v[184:187], v[44:47]
	ds_read_b128 v[184:187], v152 offset:55296
	ds_write_b128 v230, v[208:211] offset:12288
	global_load_dwordx4 v[208:211], v158, s[100:101] offset:2048
	s_waitcnt lgkmcnt(3)
; DI f32x4 mfma16(bf16x8 a, bf16x8 b, f32x4 c) { return __builtin_amdgcn_mfma_f32_16x16x32_bf16(a, b, c, 0, 0, 0); }
; template <int NI, class XL, class EP>
; DI void gemm_tile(const u16* __restrict__ W, int ldw, int f0, int t0, int K, XL xl, EP ep, unsigned char* smem) {
;     ...
;   for (int it = 0; it < nk; ++it) {
;     const u16* Ws = S0 + (it & 1) * BUF; const u16* Xs = Ws + 128 * LST;
;     __builtin_amdgcn_s_setprio(1);
;     bf16x8 a[4];
; #pragma unroll
;     for (int mi = 0; mi < 4; ++mi) a[mi] = *(const bf16x8*)(Ws + (wf * 64 + mi * 16 + lr) * LST + lq * 8);
; #pragma unroll
;     for (int ni = 0; ni < NI; ++ni) {
;       const bf16x8 b = *(const bf16x8*)(Xs + (wt * (NI * 16) + ni * 16 + lr) * LST + lq * 8);
; #pragma unroll
;       for (int mi = 0; mi < 4; ++mi) acc[mi][ni] = mfma16(a[mi], b, acc[mi][ni]);
;     }
;     __builtin_amdgcn_sched_group_barrier(0x100, 6, 0);
; #pragma unroll
;     for (int ni = 0; ni < NI; ++ni) { __builtin_amdgcn_sched_group_barrier(0x008, 4, 0); if (ni + 2 < NI) __builtin_amdgcn_sched_group_barrier(0x100, 1, 0); }
;     __builtin_amdgcn_s_setprio(0);
;     if (it + 1 < nk) lstore((it + 1) & 1);
;     if (it + 2 < nk) gload(it + 2);
;     __syncthreads();
	v_mfma_f32_16x16x32_bf16 v[132:135], v[176:179], v[196:199], v[132:135]
	v_mfma_f32_16x16x32_bf16 v[108:111], v[180:183], v[196:199], v[108:111]
	v_mfma_f32_16x16x32_bf16 v[76:79], v[188:191], v[196:199], v[76:79]
	v_mfma_f32_16x16x32_bf16 v[40:43], v[192:195], v[196:199], v[40:43]
	ds_read_b128 v[196:199], v152 offset:56832
	ds_write_b128 v230, v[212:215] offset:12384
	global_load_dwordx4 v[212:215], v158, s[100:101] offset:2112
	s_waitcnt lgkmcnt(3)
	v_mfma_f32_16x16x32_bf16 v[124:127], v[176:179], v[184:187], v[124:127]
	v_mfma_f32_16x16x32_bf16 v[96:99], v[180:183], v[184:187], v[96:99]
	v_mfma_f32_16x16x32_bf16 v[68:71], v[188:191], v[184:187], v[68:71]
	v_mfma_f32_16x16x32_bf16 v[12:15], v[192:195], v[184:187], v[12:15]
	ds_read_b128 v[184:187], v152 offset:58368
	ds_write_b128 v230, v[220:223] offset:12480
	global_load_dwordx4 v[220:223], v158, s[100:101] offset:2176
	s_waitcnt lgkmcnt(3)
	v_mfma_f32_16x16x32_bf16 v[116:119], v[176:179], v[196:199], v[116:119]
	v_mfma_f32_16x16x32_bf16 v[84:87], v[180:183], v[196:199], v[84:87]
	v_mfma_f32_16x16x32_bf16 v[60:63], v[188:191], v[196:199], v[60:63]
	v_mfma_f32_16x16x32_bf16 v[8:11], v[192:195], v[196:199], v[8:11]
	ds_read_b128 v[196:199], v152 offset:59904
	ds_write_b128 v230, v[224:227] offset:12576
	global_load_dwordx4 v[224:227], v158, s[100:101] offset:2240
	s_waitcnt lgkmcnt(3)
	v_mfma_f32_16x16x32_bf16 v[104:107], v[176:179], v[184:187], v[104:107]
	v_mfma_f32_16x16x32_bf16 v[72:75], v[180:183], v[184:187], v[72:75]
	v_mfma_f32_16x16x32_bf16 v[56:59], v[188:191], v[184:187], v[56:59]
	v_mfma_f32_16x16x32_bf16 v[4:7], v[192:195], v[184:187], v[4:7]
	s_add_u32 s98, s98, s28
	s_addc_u32 s99, s99, s29
	s_add_u32 s100, s100, s26
	s_addc_u32 s101, s101, s27
	s_add_i32 s4, s4, 2
	s_waitcnt lgkmcnt(1)
	v_mfma_f32_16x16x32_bf16 v[92:95], v[176:179], v[196:199], v[92:95]
	v_mfma_f32_16x16x32_bf16 v[64:67], v[180:183], v[196:199], v[64:67]
	v_mfma_f32_16x16x32_bf16 v[48:51], v[188:191], v[196:199], v[48:51]
	v_mfma_f32_16x16x32_bf16 v[0:3], v[192:195], v[196:199], v[0:3]
	s_setprio 0
	s_cmp_eq_u32 s4, 29
	s_waitcnt lgkmcnt(0)
	s_barrier
	s_cbranch_scc0 .LBB0_945
	s_setprio 1
	ds_read_b128 v[176:179], v228 offset:0
	ds_read_b128 v[180:183], v228 offset:1536
	ds_read_b128 v[188:191], v228 offset:3072
	ds_read_b128 v[192:195], v228 offset:4608
	ds_read_b128 v[184:187], v152 offset:12288
	ds_read_b128 v[196:199], v152 offset:13824
	s_waitcnt lgkmcnt(1)
	v_mfma_f32_16x16x32_bf16 v[148:151], v[176:179], v[184:187], v[148:151]
	v_mfma_f32_16x16x32_bf16 v[136:139], v[180:183], v[184:187], v[136:139]
	v_mfma_f32_16x16x32_bf16 v[112:115], v[188:191], v[184:187], v[112:115]
	v_mfma_f32_16x16x32_bf16 v[80:83], v[192:195], v[184:187], v[80:83]
	ds_read_b128 v[184:187], v152 offset:15360
	s_waitcnt vmcnt(6)
	ds_write_b128 v229, v[20:23] offset:36864
	s_waitcnt lgkmcnt(2)
	v_mfma_f32_16x16x32_bf16 v[144:147], v[176:179], v[196:199], v[144:147]
	v_mfma_f32_16x16x32_bf16 v[128:131], v[180:183], v[196:199], v[128:131]
	v_mfma_f32_16x16x32_bf16 v[100:103], v[188:191], v[196:199], v[100:103]
	v_mfma_f32_16x16x32_bf16 v[52:55], v[192:195], v[196:199], v[52:55]
	ds_read_b128 v[196:199], v152 offset:16896
	ds_write_b128 v229, v[16:19] offset:36960
	global_load_dwordx4 v[20:23], v156, s[98:99]
	global_load_dwordx4 v[16:19], v156, s[98:99] offset:64
	s_waitcnt lgkmcnt(3)
	v_mfma_f32_16x16x32_bf16 v[140:143], v[176:179], v[184:187], v[140:143]
	v_mfma_f32_16x16x32_bf16 v[120:123], v[180:183], v[184:187], v[120:123]
	v_mfma_f32_16x16x32_bf16 v[88:91], v[188:191], v[184:187], v[88:91]
	v_mfma_f32_16x16x32_bf16 v[44:47], v[192:195], v[184:187], v[44:47]
	ds_read_b128 v[184:187], v152 offset:18432
	ds_write_b128 v230, v[36:39] offset:49152
	global_load_dwordx4 v[36:39], v158, s[100:101] offset:2048
	s_waitcnt lgkmcnt(3)
	v_mfma_f32_16x16x32_bf16 v[132:135], v[176:179], v[196:199], v[132:135]
	v_mfma_f32_16x16x32_bf16 v[108:111], v[180:183], v[196:199], v[108:111]
	v_mfma_f32_16x16x32_bf16 v[76:79], v[188:191], v[196:199], v[76:79]
	v_mfma_f32_16x16x32_bf16 v[40:43], v[192:195], v[196:199], v[40:43]
	ds_read_b128 v[196:199], v152 offset:19968
	ds_write_b128 v230, v[32:35] offset:49248
	global_load_dwordx4 v[32:35], v158, s[100:101] offset:2112
	s_waitcnt lgkmcnt(3)
	v_mfma_f32_16x16x32_bf16 v[124:127], v[176:179], v[184:187], v[124:127]
	v_mfma_f32_16x16x32_bf16 v[96:99], v[180:183], v[184:187], v[96:99]
	v_mfma_f32_16x16x32_bf16 v[68:71], v[188:191], v[184:187], v[68:71]
	v_mfma_f32_16x16x32_bf16 v[12:15], v[192:195], v[184:187], v[12:15]
	ds_read_b128 v[184:187], v152 offset:21504
	ds_write_b128 v230, v[28:31] offset:49344
	global_load_dwordx4 v[28:31], v158, s[100:101] offset:2176
	s_waitcnt lgkmcnt(3)
	v_mfma_f32_16x16x32_bf16 v[116:119], v[176:179], v[196:199], v[116:119]
	v_mfma_f32_16x16x32_bf16 v[84:87], v[180:183], v[196:199], v[84:87]
	v_mfma_f32_16x16x32_bf16 v[60:63], v[188:191], v[196:199], v[60:63]
	v_mfma_f32_16x16x32_bf16 v[8:11], v[192:195], v[196:199], v[8:11]
	ds_read_b128 v[196:199], v152 offset:23040
	ds_write_b128 v230, v[24:27] offset:49440
	global_load_dwordx4 v[24:27], v158, s[100:101] offset:2240
	s_waitcnt lgkmcnt(3)
	v_mfma_f32_16x16x32_bf16 v[104:107], v[176:179], v[184:187], v[104:107]
	v_mfma_f32_16x16x32_bf16 v[72:75], v[180:183], v[184:187], v[72:75]
	v_mfma_f32_16x16x32_bf16 v[56:59], v[188:191], v[184:187], v[56:59]
	v_mfma_f32_16x16x32_bf16 v[4:7], v[192:195], v[184:187], v[4:7]
	s_add_u32 s98, s98, s28
	s_addc_u32 s99, s99, s29
	s_add_u32 s100, s100, s26
	s_addc_u32 s101, s101, s27
	s_waitcnt lgkmcnt(1)
	v_mfma_f32_16x16x32_bf16 v[92:95], v[176:179], v[196:199], v[92:95]
	v_mfma_f32_16x16x32_bf16 v[64:67], v[180:183], v[196:199], v[64:67]
	v_mfma_f32_16x16x32_bf16 v[48:51], v[188:191], v[196:199], v[48:51]
	v_mfma_f32_16x16x32_bf16 v[0:3], v[192:195], v[196:199], v[0:3]
	s_setprio 0
	s_waitcnt lgkmcnt(0)
	s_barrier
; DI f32x4 mfma16(bf16x8 a, bf16x8 b, f32x4 c) { return __builtin_amdgcn_mfma_f32_16x16x32_bf16(a, b, c, 0, 0, 0); }
; template <int NI, class XL, class EP>
; DI void gemm_tile(const u16* __restrict__ W, int ldw, int f0, int t0, int K, XL xl, EP ep, unsigned char* smem) {
;     ...
;   for (int it = 0; it < nk; ++it) {
;     const u16* Ws = S0 + (it & 1) * BUF; const u16* Xs = Ws + 128 * LST;
;     __builtin_amdgcn_s_setprio(1);
;     bf16x8 a[4];
; #pragma unroll
;     for (int mi = 0; mi < 4; ++mi) a[mi] = *(const bf16x8*)(Ws + (wf * 64 + mi * 16 + lr) * LST + lq * 8);
; #pragma unroll
;     for (int ni = 0; ni < NI; ++ni) {
;       const bf16x8 b = *(const bf16x8*)(Xs + (wt * (NI * 16) + ni * 16 + lr) * LST + lq * 8);
; #pragma unroll
;       for (int mi = 0; mi < 4; ++mi) acc[mi][ni] = mfma16(a[mi], b, acc[mi][ni]);
;     }
;     __builtin_amdgcn_sched_group_barrier(0x100, 6, 0);
; #pragma unroll
;     for (int ni = 0; ni < NI; ++ni) { __builtin_amdgcn_sched_group_barrier(0x008, 4, 0); if (ni + 2 < NI) __builtin_amdgcn_sched_group_barrier(0x100, 1, 0); }
;     __builtin_amdgcn_s_setprio(0);
;     if (it + 1 < nk) lstore((it + 1) & 1);
;     if (it + 2 < nk) gload(it + 2);
;     __syncthreads();
;   }
	s_setprio 1
	ds_read_b128 v[176:179], v228 offset:36864
	ds_read_b128 v[180:183], v228 offset:38400
	ds_read_b128 v[188:191], v228 offset:39936
	ds_read_b128 v[192:195], v228 offset:41472
	ds_read_b128 v[184:187], v152 offset:49152
	ds_read_b128 v[196:199], v152 offset:50688
	s_waitcnt lgkmcnt(1)
	v_mfma_f32_16x16x32_bf16 v[148:151], v[176:179], v[184:187], v[148:151]
	v_mfma_f32_16x16x32_bf16 v[136:139], v[180:183], v[184:187], v[136:139]
	v_mfma_f32_16x16x32_bf16 v[112:115], v[188:191], v[184:187], v[112:115]
	v_mfma_f32_16x16x32_bf16 v[80:83], v[192:195], v[184:187], v[80:83]
	ds_read_b128 v[184:187], v152 offset:52224
	s_waitcnt vmcnt(6)
	ds_write_b128 v229, v[200:203] offset:0
	s_waitcnt lgkmcnt(2)
	v_mfma_f32_16x16x32_bf16 v[144:147], v[176:179], v[196:199], v[144:147]
	v_mfma_f32_16x16x32_bf16 v[128:131], v[180:183], v[196:199], v[128:131]
	v_mfma_f32_16x16x32_bf16 v[100:103], v[188:191], v[196:199], v[100:103]
	v_mfma_f32_16x16x32_bf16 v[52:55], v[192:195], v[196:199], v[52:55]
	ds_read_b128 v[196:199], v152 offset:53760
	ds_write_b128 v229, v[204:207] offset:96
	s_waitcnt lgkmcnt(3)
	v_mfma_f32_16x16x32_bf16 v[140:143], v[176:179], v[184:187], v[140:143]
	v_mfma_f32_16x16x32_bf16 v[120:123], v[180:183], v[184:187], v[120:123]
	v_mfma_f32_16x16x32_bf16 v[88:91], v[188:191], v[184:187], v[88:91]
	v_mfma_f32_16x16x32_bf16 v[44:47], v[192:195], v[184:187], v[44:47]
	ds_read_b128 v[184:187], v152 offset:55296
	ds_write_b128 v230, v[208:211] offset:12288
	s_waitcnt lgkmcnt(3)
	v_mfma_f32_16x16x32_bf16 v[132:135], v[176:179], v[196:199], v[132:135]
	v_mfma_f32_16x16x32_bf16 v[108:111], v[180:183], v[196:199], v[108:111]
	v_mfma_f32_16x16x32_bf16 v[76:79], v[188:191], v[196:199], v[76:79]
	v_mfma_f32_16x16x32_bf16 v[40:43], v[192:195], v[196:199], v[40:43]
	ds_read_b128 v[196:199], v152 offset:56832
	ds_write_b128 v230, v[212:215] offset:12384
	s_waitcnt lgkmcnt(3)
	v_mfma_f32_16x16x32_bf16 v[124:127], v[176:179], v[184:187], v[124:127]
	v_mfma_f32_16x16x32_bf16 v[96:99], v[180:183], v[184:187], v[96:99]
	v_mfma_f32_16x16x32_bf16 v[68:71], v[188:191], v[184:187], v[68:71]
	v_mfma_f32_16x16x32_bf16 v[12:15], v[192:195], v[184:187], v[12:15]
	ds_read_b128 v[184:187], v152 offset:58368
	ds_write_b128 v230, v[220:223] offset:12480
	s_waitcnt lgkmcnt(3)
	v_mfma_f32_16x16x32_bf16 v[116:119], v[176:179], v[196:199], v[116:119]
	v_mfma_f32_16x16x32_bf16 v[84:87], v[180:183], v[196:199], v[84:87]
	v_mfma_f32_16x16x32_bf16 v[60:63], v[188:191], v[196:199], v[60:63]
	v_mfma_f32_16x16x32_bf16 v[8:11], v[192:195], v[196:199], v[8:11]
	ds_read_b128 v[196:199], v152 offset:59904
	ds_write_b128 v230, v[224:227] offset:12576
	s_waitcnt lgkmcnt(3)
	v_mfma_f32_16x16x32_bf16 v[104:107], v[176:179], v[184:187], v[104:107]
	v_mfma_f32_16x16x32_bf16 v[72:75], v[180:183], v[184:187], v[72:75]
	v_mfma_f32_16x16x32_bf16 v[56:59], v[188:191], v[184:187], v[56:59]
	v_mfma_f32_16x16x32_bf16 v[4:7], v[192:195], v[184:187], v[4:7]
	s_add_i32 s4, s4, 2
	s_waitcnt lgkmcnt(1)
	v_mfma_f32_16x16x32_bf16 v[92:95], v[176:179], v[196:199], v[92:95]
	v_mfma_f32_16x16x32_bf16 v[64:67], v[180:183], v[196:199], v[64:67]
	v_mfma_f32_16x16x32_bf16 v[48:51], v[188:191], v[196:199], v[48:51]
	v_mfma_f32_16x16x32_bf16 v[0:3], v[192:195], v[196:199], v[0:3]
	s_setprio 0
	s_waitcnt lgkmcnt(0)
	s_barrier
	s_setprio 1
	v_lshl_add_u32 v152, v175, 1, v172
	ds_read_b128 v[156:159], v152
	v_lshl_add_u32 v171, v173, 1, v172
	ds_read_b128 v[172:175], v152 offset:1536
	ds_read_b128 v[180:183], v152 offset:3072
	ds_read_b128 v[184:187], v152 offset:4608
	ds_read_b128 v[176:179], v171 offset:12288
	ds_read_b128 v[188:191], v171 offset:13824
	s_waitcnt lgkmcnt(1)
	v_mfma_f32_16x16x32_bf16 v[148:151], v[156:159], v[176:179], v[148:151]
	v_mfma_f32_16x16x32_bf16 v[136:139], v[172:175], v[176:179], v[136:139]
	v_mfma_f32_16x16x32_bf16 v[112:115], v[180:183], v[176:179], v[112:115]
	v_mfma_f32_16x16x32_bf16 v[80:83], v[184:187], v[176:179], v[80:83]
	ds_read_b128 v[176:179], v171 offset:15360
	s_waitcnt lgkmcnt(1)
	v_mfma_f32_16x16x32_bf16 v[144:147], v[156:159], v[188:191], v[144:147]
	v_mfma_f32_16x16x32_bf16 v[128:131], v[172:175], v[188:191], v[128:131]
	v_mfma_f32_16x16x32_bf16 v[100:103], v[180:183], v[188:191], v[100:103]
	v_mfma_f32_16x16x32_bf16 v[188:191], v[184:187], v[188:191], v[52:55]
	s_nop 2
	ds_read_b128 v[52:55], v171 offset:16896
	s_waitcnt lgkmcnt(1)
	v_mfma_f32_16x16x32_bf16 v[192:195], v[156:159], v[176:179], v[140:143]
	v_mfma_f32_16x16x32_bf16 v[120:123], v[172:175], v[176:179], v[120:123]
	v_mfma_f32_16x16x32_bf16 v[88:91], v[180:183], v[176:179], v[88:91]
	v_mfma_f32_16x16x32_bf16 v[176:179], v[184:187], v[176:179], v[44:47]
	s_nop 2
	ds_read_b128 v[44:47], v171 offset:18432
	s_waitcnt lgkmcnt(1)
	v_mfma_f32_16x16x32_bf16 v[196:199], v[156:159], v[52:55], v[132:135]
	v_mfma_f32_16x16x32_bf16 v[108:111], v[172:175], v[52:55], v[108:111]
	v_mfma_f32_16x16x32_bf16 v[76:79], v[180:183], v[52:55], v[76:79]
	v_mfma_f32_16x16x32_bf16 v[200:203], v[184:187], v[52:55], v[40:43]
	s_nop 2
	ds_read_b128 v[40:43], v171 offset:19968
	s_waitcnt lgkmcnt(1)
	v_mfma_f32_16x16x32_bf16 v[204:207], v[156:159], v[44:47], v[124:127]
	v_mfma_f32_16x16x32_bf16 v[96:99], v[172:175], v[44:47], v[96:99]
	v_mfma_f32_16x16x32_bf16 v[68:71], v[180:183], v[44:47], v[68:71]
	v_mfma_f32_16x16x32_bf16 v[12:15], v[184:187], v[44:47], v[12:15]
	ds_read_b128 v[44:47], v171 offset:21504
	s_waitcnt lgkmcnt(1)
	v_mfma_f32_16x16x32_bf16 v[208:211], v[156:159], v[40:43], v[116:119]
	v_mfma_f32_16x16x32_bf16 v[84:87], v[172:175], v[40:43], v[84:87]
	v_mfma_f32_16x16x32_bf16 v[212:215], v[180:183], v[40:43], v[60:63]
	v_mfma_f32_16x16x32_bf16 v[8:11], v[184:187], v[40:43], v[8:11]
	ds_read_b128 v[40:43], v171 offset:23040
	s_waitcnt lgkmcnt(1)
	v_mfma_f32_16x16x32_bf16 v[220:223], v[156:159], v[44:47], v[104:107]
	v_mfma_f32_16x16x32_bf16 v[72:75], v[172:175], v[44:47], v[72:75]
	v_mfma_f32_16x16x32_bf16 v[224:227], v[180:183], v[44:47], v[56:59]
	v_mfma_f32_16x16x32_bf16 v[4:7], v[184:187], v[44:47], v[4:7]
	s_waitcnt lgkmcnt(0)
	v_mfma_f32_16x16x32_bf16 v[156:159], v[156:159], v[40:43], v[92:95]
	v_mfma_f32_16x16x32_bf16 v[172:175], v[172:175], v[40:43], v[64:67]
	v_mfma_f32_16x16x32_bf16 v[180:183], v[180:183], v[40:43], v[48:51]
	v_mfma_f32_16x16x32_bf16 v[184:187], v[184:187], v[40:43], v[0:3]
	s_setprio 0
	s_waitcnt vmcnt(5)
	ds_write_b128 v170, v[20:23] offset:36864
	s_waitcnt vmcnt(4)
	ds_write_b128 v170, v[16:19] offset:36960
	s_waitcnt vmcnt(3)
	ds_write_b128 v169, v[36:39] offset:49152
	s_waitcnt vmcnt(2)
	ds_write_b128 v169, v[32:35] offset:49248
	s_waitcnt vmcnt(1)
	ds_write_b128 v169, v[28:31] offset:49344
	s_waitcnt vmcnt(0)
	ds_write_b128 v169, v[24:27] offset:49440
	s_waitcnt lgkmcnt(0)
	s_barrier
; DI float sigmoidf_(float x) { return 1.0f / (1.0f + __expf(-x)); }
; DI void store4(u16* dst, f32x4 v) { uint2 w; w.x = cvtpk(v[0], v[1]); w.y = cvtpk(v[2], v[3]); *(uint2*)dst = w; }
; DI f32x4 mfma16(bf16x8 a, bf16x8 b, f32x4 c) { return __builtin_amdgcn_mfma_f32_16x16x32_bf16(a, b, c, 0, 0, 0); }
; template <int NI, class XL, class EP>
; DI void gemm_tile(const u16* __restrict__ W, int ldw, int f0, int t0, int K, XL xl, EP ep, unsigned char* smem) {
;     ...
; #pragma unroll
;     for (int mi = 0; mi < 4; ++mi) a[mi] = *(const bf16x8*)(Ws + (wf * 64 + mi * 16 + lr) * LST + lq * 8);
; #pragma unroll
;     for (int ni = 0; ni < NI; ++ni) {
;       const bf16x8 b = *(const bf16x8*)(Xs + (wt * (NI * 16) + ni * 16 + lr) * LST + lq * 8);
; #pragma unroll
;       for (int mi = 0; mi < 4; ++mi) acc[mi][ni] = mfma16(a[mi], b, acc[mi][ni]);
;     }
; DI void phase8(const Params& p, const Sched& sched, unsigned char* smem) {
;     ...
;       for (int h2 = 0; h2 < 2; ++h2) {
;         const int fl = wf * 16 + lq * 4, fc = (2 * wf + h2) * 16 + lq * 4, F = tn * 64 + fc;
;         __syncthreads();
; #pragma unroll
;         for (int ni = 0; ni < 8; ++ni) *(f32x4*)(gl + (wt * 128 + ni * 16 + lr) * 36 + fl) = acc[2 * h2][ni];
;         __syncthreads();
;         const float4 w0 = *(const float4*)(p.conv_w + F), w1 = *(const float4*)(p.conv_w + FF + F), w2 = *(const float4*)(p.conv_w + 2 * FF + F), cb = *(const float4*)(p.conv_b + F);
; #pragma unroll
;         for (int ni = 0; ni < 8; ++ni) {
;           const int row = wt * 128 + ni * 16 + lr;
;           const f32x4 gv = acc[2 * h2][ni], uv = acc[2 * h2 + 1][ni];
;           if (row >= 2) {
;             const f32x4 g1 = *(const f32x4*)(gl + (row - 1) * 36 + fl), g2 = *(const f32x4*)(gl + (row - 2) * 36 + fl);
;             f32x4 o;
;             o[0] = cb.x + w0.x * g2[0] + w1.x * g1[0] + w2.x * gv[0];
;             o[1] = cb.y + w0.y * g2[1] + w1.y * g1[1] + w2.y * gv[1];
;             o[2] = cb.z + w0.z * g2[2] + w1.z * g1[2] + w2.z * gv[2];
;             o[3] = cb.w + w0.w * g2[3] + w1.w * g1[3] + w2.w * gv[3];
; #pragma unroll
;             for (int j = 0; j < 4; ++j) o[j] = o[j] * sigmoidf_(o[j]) * uv[j];
;             store4(Ls + row * 72 + fc, o);
;           } else {
;             *(f32x4*)(gside + ((size_t)tm * 4 + row) * FF + F) = gv;
;             *(f32x4*)(uside + ((size_t)tm * 2 + row) * FF + F) = uv;
;           }
	s_setprio 1
	ds_read_b128 v[0:3], v152 offset:36864
	ds_read_b128 v[228:231], v152 offset:38400
	ds_read_b128 v[232:235], v152 offset:39936
	ds_read_b128 v[236:239], v152 offset:41472
	ds_read_b128 v[16:19], v171 offset:49152
	ds_read_b128 v[20:23], v171 offset:50688
	s_waitcnt lgkmcnt(1)
	v_mfma_f32_16x16x32_bf16 v[140:143], v[0:3], v[16:19], v[148:151]
	v_mfma_f32_16x16x32_bf16 v[136:139], v[228:231], v[16:19], v[136:139]
	v_mfma_f32_16x16x32_bf16 v[60:63], v[232:235], v[16:19], v[112:115]
	v_mfma_f32_16x16x32_bf16 v[56:59], v[236:239], v[16:19], v[80:83]
	ds_read_b128 v[16:19], v171 offset:52224
	s_waitcnt lgkmcnt(1)
	v_mfma_f32_16x16x32_bf16 v[132:135], v[0:3], v[20:23], v[144:147]
	v_mfma_f32_16x16x32_bf16 v[128:131], v[228:231], v[20:23], v[128:131]
	v_mfma_f32_16x16x32_bf16 v[52:55], v[232:235], v[20:23], v[100:103]
	v_mfma_f32_16x16x32_bf16 v[48:51], v[236:239], v[20:23], v[188:191]
	ds_read_b128 v[20:23], v171 offset:53760
	s_waitcnt lgkmcnt(1)
	v_mfma_f32_16x16x32_bf16 v[124:127], v[0:3], v[16:19], v[192:195]
	v_mfma_f32_16x16x32_bf16 v[120:123], v[228:231], v[16:19], v[120:123]
	v_mfma_f32_16x16x32_bf16 v[44:47], v[232:235], v[16:19], v[88:91]
	v_mfma_f32_16x16x32_bf16 v[40:43], v[236:239], v[16:19], v[176:179]
	ds_read_b128 v[16:19], v171 offset:55296
	s_waitcnt lgkmcnt(1)
	v_mfma_f32_16x16x32_bf16 v[116:119], v[0:3], v[20:23], v[196:199]
	v_mfma_f32_16x16x32_bf16 v[112:115], v[228:231], v[20:23], v[108:111]
	v_mfma_f32_16x16x32_bf16 v[36:39], v[232:235], v[20:23], v[76:79]
	v_mfma_f32_16x16x32_bf16 v[32:35], v[236:239], v[20:23], v[200:203]
	ds_read_b128 v[64:67], v171 offset:56832
	s_waitcnt lgkmcnt(1)
	v_mfma_f32_16x16x32_bf16 v[108:111], v[0:3], v[16:19], v[204:207]
	v_mfma_f32_16x16x32_bf16 v[104:107], v[228:231], v[16:19], v[96:99]
	v_mfma_f32_16x16x32_bf16 v[28:31], v[232:235], v[16:19], v[68:71]
	v_mfma_f32_16x16x32_bf16 v[24:27], v[236:239], v[16:19], v[12:15]
	s_nop 1
	ds_read_b128 v[68:71], v171 offset:58368
	s_waitcnt lgkmcnt(1)
	v_mfma_f32_16x16x32_bf16 v[100:103], v[0:3], v[64:67], v[208:211]
	v_mfma_f32_16x16x32_bf16 v[96:99], v[228:231], v[64:67], v[84:87]
	v_mfma_f32_16x16x32_bf16 v[20:23], v[232:235], v[64:67], v[212:215]
	v_mfma_f32_16x16x32_bf16 v[16:19], v[236:239], v[64:67], v[8:11]
	ds_read_b128 v[76:79], v171 offset:59904
	s_waitcnt lgkmcnt(1)
	v_mfma_f32_16x16x32_bf16 v[92:95], v[0:3], v[68:71], v[220:223]
	v_mfma_f32_16x16x32_bf16 v[72:75], v[228:231], v[68:71], v[72:75]
	v_mfma_f32_16x16x32_bf16 v[12:15], v[232:235], v[68:71], v[224:227]
	v_mfma_f32_16x16x32_bf16 v[8:11], v[236:239], v[68:71], v[4:7]
	s_waitcnt lgkmcnt(0)
	v_mfma_f32_16x16x32_bf16 v[64:67], v[0:3], v[76:79], v[156:159]
	v_mfma_f32_16x16x32_bf16 v[68:71], v[228:231], v[76:79], v[172:175]
	v_mfma_f32_16x16x32_bf16 v[0:3], v[232:235], v[76:79], v[180:183]
	v_mfma_f32_16x16x32_bf16 v[4:7], v[236:239], v[76:79], v[184:187]
	s_setprio 0
	v_lshlrev_b32_e32 v76, 2, v168
	v_lshl_or_b32 v152, v155, 4, v76
	v_lshl_or_b32 v156, v155, 5, v76
	v_lshlrev_b32_e32 v76, 2, v152
	v_mad_u32_u24 v77, v154, s47, v160
	v_add_u32_e32 v159, v77, v76
	v_mad_u32_u24 v77, v154, s47, v161
	v_add_u32_e32 v168, v77, v76
	v_mad_u32_u24 v77, v154, s47, v162
	s_lshl_b32 s57, s56, 6
	v_add_u32_e32 v169, v77, v76
	v_mad_u32_u24 v77, v154, s47, v163
	v_add_u32_e32 v170, v77, v76
	v_mad_u32_u24 v77, v154, s47, v164
	v_add_u32_e32 v144, s57, v156
	v_add_u32_e32 v171, v77, v76
	v_mad_u32_u24 v77, v154, s47, v165
	v_ashrrev_i32_e32 v145, 31, v144
	v_add_u32_e32 v172, v77, v76
	v_mad_u32_u24 v77, v154, s47, v166
	v_lshlrev_b64 v[146:147], 2, v[144:145]
	v_mad_u32_u24 v158, v154, s47, v76
	v_add_u32_e32 v173, v77, v76
	v_lshl_add_u64 v[148:149], s[68:69], 0, v[146:147]
	v_lshl_add_u64 v[76:77], s[22:23], 0, v[146:147]
	v_lshl_add_u64 v[78:79], s[24:25], 0, v[146:147]
	v_lshl_add_u64 v[150:151], s[70:71], 0, v[146:147]
	s_barrier
	s_barrier
	ds_write_b128 v158, v[140:143]
	ds_write_b128 v159, v[132:135]
	ds_write_b128 v168, v[124:127]
	ds_write_b128 v169, v[116:119]
	ds_write_b128 v170, v[108:111]
	ds_write_b128 v171, v[100:103]
	ds_write_b128 v172, v[92:95]
	ds_write_b128 v173, v[64:67]
	s_waitcnt lgkmcnt(0)
	s_barrier
	global_load_dwordx4 v[84:87], v[148:149], off
	global_load_dwordx4 v[80:83], v[76:77], off
	global_load_dwordx4 v[88:91], v[150:151], off
	v_cmp_gt_u32_e64 s[4:5], 2, v154
	global_load_dwordx4 v[76:79], v[78:79], off
	v_lshl_or_b32 v157, s30, 1, v154
	s_and_saveexec_b64 s[6:7], s[4:5]
	s_xor_b64 s[6:7], exec, s[6:7]
	s_cbranch_execz .LBB0_948
	s_ashr_i32 s31, s30, 31
	s_lshl_b64 s[34:35], s[30:31], 2
	v_or_b32_e32 v155, s34, v154
	v_mov_b64_e32 v[174:175], s[16:17]
	v_mad_u64_u32 v[174:175], s[58:59], v155, s48, v[174:175]
	v_mad_i32_i24 v175, s35, v167, v175
	v_lshl_add_u64 v[174:175], v[174:175], 0, v[146:147]
	global_store_dwordx4 v[174:175], v[140:143], off
	s_nop 1
	v_mov_b64_e32 v[140:141], s[10:11]
	v_mad_u64_u32 v[140:141], s[34:35], v157, s48, v[140:141]
	v_mad_i32_i24 v141, s31, v167, v141
	v_lshl_add_u64 v[140:141], v[140:141], 0, v[146:147]
	global_store_dwordx4 v[140:141], v[136:139], off

; DI int tidx() { int t = __builtin_amdgcn_workitem_id_x(); asm volatile("" : "+v"(t)); return t; }
;   DI unsigned rowoff(int r, int sch) const { const int g = r & 3, bc = r >> 2, b = bc / NCMP, c = bc - b * NCMP; return (unsigned)(b * Sn + c * 16) * 512u + g * 64 + sch; }
; template <int NI, class XL, class EP>
; DI void gemm_tile(const u16* __restrict__ W, int ldw, int f0, int t0, int K, XL xl, EP ep, unsigned char* smem) {
;     ...
;   const int tid = tidx(), lane = tid & 63, wave = tid >> 6;
;   const int wf = wave >> 1, wt = wave & 1, lr = lane & 15, lq = lane >> 4;
;   const int srow = tid >> 2, sch = (tid & 3) * 8;
;   f32x4 acc[4][NI];
; #pragma unroll
;   for (int i = 0; i < 4; ++i)
; #pragma unroll
;     for (int j = 0; j < NI; ++j) acc[i][j] = (f32x4){0.f, 0.f, 0.f, 0.f};
;   u32x4 wr[2], xr[XR];
;   const unsigned wbyte = ((unsigned)(f0 + srow * 2) * 32u + sch) * 2u;
;   const unsigned xbyte = xl.rowoff(t0 + srow * XR, sch) * 2u;
;   const int xrs = xl.rstride();
;   const int nk = K >> 5;
;   auto gload = [&](int it) {
;     const int k = it * 32;
;     const char* wb = (const char*)(W + (size_t)(k >> 5) * ldw * 32);
;     const char* xb = (const char*)xl.kbase(k);
; #pragma unroll
;     for (int i = 0; i < 2; ++i) wr[i] = *(const u32x4*)(wb + wbyte + i * 64);
; #pragma unroll
;     for (int i = 0; i < XR; ++i) xr[i] = *(const u32x4*)(xb + xbyte + i * xrs);
;   };
;   auto lstore = [&](int buf) {
;     u16* Ws = S0 + buf * BUF; u16* Xs = Ws + 128 * LST;
; #pragma unroll
;     for (int i = 0; i < 2; ++i) *(u32x4*)(Ws + (srow * 2 + i) * LST + sch) = wr[i];
; #pragma unroll
;     for (int i = 0; i < XR; ++i) *(u32x4*)(Xs + (srow * XR + i) * LST + sch) = xr[i];
;   };
;   gload(0);
;   __syncthreads();
;   lstore(0);
;   __syncthreads();
;   if (nk > 1) gload(1);
.LBB0_1094:
	v_mov_b32_e32 v46, v218
	s_and_b32 s30, s28, 7
	v_ashrrev_i32_e32 v47, 2, v46
	v_lshlrev_b32_e32 v0, 3, v46
	v_lshlrev_b32_e32 v49, 6, v47
	s_ashr_i32 s34, s28, 3
	v_and_b32_e32 v48, 24, v0
	v_lshl_add_u32 v0, s30, 12, v49
	s_add_i32 s31, s34, s26
	v_or_b32_e32 v0, v0, v48
	s_lshl_b32 s29, s31, 8
	v_lshlrev_b32_e32 v50, 1, v0
	v_and_b32_e32 v0, 0x3fffffc, v46
	v_add_u32_e32 v0, s29, v0
	v_lshlrev_b32_e32 v161, 1, v48
	v_lshl_or_b32 v51, v0, 6, v161
	global_load_dwordx4 v[16:19], v50, s[4:5]
	global_load_dwordx4 v[20:23], v50, s[4:5] offset:64
	global_load_dwordx4 v[24:27], v51, s[8:9]
	global_load_dwordx4 v[28:31], v51, s[8:9] offset:64
	global_load_dwordx4 v[32:35], v51, s[8:9] offset:128
	global_load_dwordx4 v[36:39], v51, s[8:9] offset:192
	v_mul_lo_u32 v166, v47, s20
	v_or_b32_e32 v162, v166, v161
	v_add_u32_e32 v163, v162, v166
	s_barrier
	v_bfe_u32 v158, v46, 4, 2
	v_and_b32_e32 v52, 15, v46
	v_ashrrev_i32_e32 v53, 1, v46
	v_lshlrev_b32_e32 v54, 1, v46
	v_lshlrev_b32_e32 v46, 6, v46
	s_and_b32 s35, s27, 7
	s_add_i32 s34, s18, s34
	v_and_b32_e32 v46, 0xffffff00, v46
	v_and_b32_e32 v160, 0xffffffc0, v53
	v_lshl_add_u32 v46, s34, 14, v46
	v_lshl_add_u32 v49, s35, 12, v49
	v_mov_b32_e32 v0, 0
	v_and_or_b32 v159, v54, s21, v52
	v_or_b32_e32 v47, v160, v52
	v_or_b32_e32 v152, v46, v161
	v_or_b32_e32 v46, v49, v48
	s_mov_b32 s33, 1
	v_mov_b32_e32 v155, v153
	v_mov_b32_e32 v1, v0
	v_mov_b32_e32 v2, v0
	v_mov_b32_e32 v3, v0
	v_mov_b32_e32 v4, v0
	v_mov_b32_e32 v5, v0
	v_mov_b32_e32 v6, v0
	v_mov_b32_e32 v7, v0
	v_mov_b32_e32 v8, v0
	v_mov_b32_e32 v9, v0
	v_mov_b32_e32 v10, v0
	v_mov_b32_e32 v11, v0
	v_mov_b32_e32 v12, v0
	v_mov_b32_e32 v13, v0
	v_mov_b32_e32 v14, v0
	v_mov_b32_e32 v15, v0
	v_mov_b32_e32 v40, v0
	v_mov_b32_e32 v41, v0
	v_mov_b32_e32 v42, v0
	v_mov_b32_e32 v43, v0
	v_mov_b32_e32 v44, v0
	v_mov_b32_e32 v45, v0
	v_lshlrev_b32_e32 v164, 4, v158
	v_mul_u32_u24_e32 v165, 48, v159
	v_mul_lo_u32 v167, v47, 48
	v_lshlrev_b32_e32 v154, 1, v46
	v_mov_b64_e32 v[156:157], v[152:153]
	v_mov_b32_e32 v46, v0
	v_mov_b32_e32 v47, v0
	v_mov_b32_e32 v68, v0
	v_mov_b32_e32 v69, v0
	v_mov_b32_e32 v70, v0
	v_mov_b32_e32 v71, v0
	v_mov_b32_e32 v80, v0
	v_mov_b32_e32 v81, v0
	v_mov_b32_e32 v82, v0
	v_mov_b32_e32 v83, v0
	v_mov_b32_e32 v48, v0
	v_mov_b32_e32 v49, v0
	v_mov_b32_e32 v52, v0
	v_mov_b32_e32 v53, v0
	v_mov_b32_e32 v54, v0
	v_mov_b32_e32 v55, v0
	v_mov_b32_e32 v56, v0
	v_mov_b32_e32 v57, v0
	v_mov_b32_e32 v58, v0
	s_waitcnt vmcnt(5)
	ds_write_b128 v162, v[16:19]
	s_waitcnt vmcnt(4)
	ds_write_b128 v162, v[20:23] offset:96
	s_waitcnt vmcnt(3)
	ds_write_b128 v163, v[24:27] offset:12288
	s_waitcnt vmcnt(2)
	ds_write_b128 v163, v[28:31] offset:12384
	s_waitcnt vmcnt(1)
	ds_write_b128 v163, v[32:35] offset:12480
	s_waitcnt vmcnt(0)
	ds_write_b128 v163, v[36:39] offset:12576
	s_waitcnt lgkmcnt(0)
	s_barrier
	global_load_dwordx4 v[20:23], v50, s[10:11]
	global_load_dwordx4 v[16:19], v50, s[10:11] offset:64
	global_load_dwordx4 v[36:39], v51, s[6:7]
	global_load_dwordx4 v[32:35], v51, s[6:7] offset:64
	global_load_dwordx4 v[28:31], v51, s[6:7] offset:128
	global_load_dwordx4 v[24:27], v51, s[6:7] offset:192
	s_add_u32 s98, s42, s22
	s_addc_u32 s99, s43, 0
	s_add_u32 s100, s42, s23
	s_addc_u32 s101, s43, 0
	global_load_dwordx4 v[200:203], v154, s[98:99]
	global_load_dwordx4 v[204:207], v154, s[98:99] offset:64
	global_load_dwordx4 v[208:211], v156, s[100:101] offset:2048
	global_load_dwordx4 v[212:215], v156, s[100:101] offset:2112
	global_load_dwordx4 v[220:223], v156, s[100:101] offset:2176
	global_load_dwordx4 v[224:227], v156, s[100:101] offset:2240
	s_add_u32 s98, s98, s16
	s_addc_u32 s99, s99, s17
	s_add_u32 s100, s100, s14
	s_addc_u32 s101, s101, s15
	v_mov_b32_e32 v50, v0
	v_mov_b32_e32 v51, v0
	v_mov_b32_e32 v59, v0
	v_mov_b32_e32 v64, v0
	v_mov_b32_e32 v65, v0
	v_mov_b32_e32 v66, v0
	v_mov_b32_e32 v67, v0
	v_mov_b32_e32 v76, v0
	v_mov_b32_e32 v77, v0
	v_mov_b32_e32 v78, v0
	v_mov_b32_e32 v79, v0
	v_mov_b32_e32 v88, v0
	v_mov_b32_e32 v89, v0
	v_mov_b32_e32 v90, v0
	v_mov_b32_e32 v91, v0
	v_mov_b32_e32 v100, v0
	v_mov_b32_e32 v101, v0
	v_mov_b32_e32 v102, v0
	v_mov_b32_e32 v103, v0
	v_mov_b32_e32 v112, v0
	v_mov_b32_e32 v113, v0
	v_mov_b32_e32 v114, v0
	v_mov_b32_e32 v115, v0
	v_mov_b32_e32 v60, v0
	v_mov_b32_e32 v61, v0
	v_mov_b32_e32 v62, v0
	v_mov_b32_e32 v63, v0
	v_mov_b32_e32 v72, v0
	v_mov_b32_e32 v73, v0
	v_mov_b32_e32 v74, v0
	v_mov_b32_e32 v75, v0
	v_mov_b32_e32 v84, v0
	v_mov_b32_e32 v85, v0
	v_mov_b32_e32 v86, v0
	v_mov_b32_e32 v87, v0
	v_mov_b32_e32 v96, v0
	v_mov_b32_e32 v97, v0
	v_mov_b32_e32 v98, v0
	v_mov_b32_e32 v99, v0
	v_mov_b32_e32 v108, v0
	v_mov_b32_e32 v109, v0
	v_mov_b32_e32 v110, v0
	v_mov_b32_e32 v111, v0
	v_mov_b32_e32 v120, v0
	v_mov_b32_e32 v121, v0
	v_mov_b32_e32 v122, v0
	v_mov_b32_e32 v123, v0
	v_mov_b32_e32 v128, v0
	v_mov_b32_e32 v129, v0
	v_mov_b32_e32 v130, v0
	v_mov_b32_e32 v131, v0
	v_mov_b32_e32 v136, v0
	v_mov_b32_e32 v137, v0
	v_mov_b32_e32 v138, v0
	v_mov_b32_e32 v139, v0
	v_mov_b32_e32 v92, v0
	v_mov_b32_e32 v93, v0
	v_mov_b32_e32 v94, v0
	v_mov_b32_e32 v95, v0
	v_mov_b32_e32 v104, v0
	v_mov_b32_e32 v105, v0
	v_mov_b32_e32 v106, v0
	v_mov_b32_e32 v107, v0
	v_mov_b32_e32 v116, v0
	v_mov_b32_e32 v117, v0
	v_mov_b32_e32 v118, v0
	v_mov_b32_e32 v119, v0
	v_mov_b32_e32 v124, v0
	v_mov_b32_e32 v125, v0
	v_mov_b32_e32 v126, v0
	v_mov_b32_e32 v127, v0
	v_mov_b32_e32 v132, v0
	v_mov_b32_e32 v133, v0
	v_mov_b32_e32 v134, v0
	v_mov_b32_e32 v135, v0
	v_mov_b32_e32 v140, v0
	v_mov_b32_e32 v141, v0
	v_mov_b32_e32 v142, v0
	v_mov_b32_e32 v143, v0
	v_mov_b32_e32 v144, v0
	v_mov_b32_e32 v145, v0
	v_mov_b32_e32 v146, v0
	v_mov_b32_e32 v147, v0
	v_mov_b32_e32 v148, v0
	v_mov_b32_e32 v149, v0
	v_mov_b32_e32 v150, v0
	v_mov_b32_e32 v151, v0
	v_lshl_add_u32 v228, v167, 1, v164
	v_lshl_add_u32 v152, v165, 1, v164
	v_add_u32_e32 v229, v166, v161
	v_add_u32_e32 v230, v229, v166
; DI f32x4 mfma16(bf16x8 a, bf16x8 b, f32x4 c) { return __builtin_amdgcn_mfma_f32_16x16x32_bf16(a, b, c, 0, 0, 0); }
; template <int NI, class XL, class EP>
; DI void gemm_tile(const u16* __restrict__ W, int ldw, int f0, int t0, int K, XL xl, EP ep, unsigned char* smem) {
;     ...
;   for (int it = 0; it < nk; ++it) {
;     const u16* Ws = S0 + (it & 1) * BUF; const u16* Xs = Ws + 128 * LST;
;     __builtin_amdgcn_s_setprio(1);
;     bf16x8 a[4];
; #pragma unroll
;     for (int mi = 0; mi < 4; ++mi) a[mi] = *(const bf16x8*)(Ws + (wf * 64 + mi * 16 + lr) * LST + lq * 8);
; #pragma unroll
;     for (int ni = 0; ni < NI; ++ni) {
;       const bf16x8 b = *(const bf16x8*)(Xs + (wt * (NI * 16) + ni * 16 + lr) * LST + lq * 8);
; #pragma unroll
;       for (int mi = 0; mi < 4; ++mi) acc[mi][ni] = mfma16(a[mi], b, acc[mi][ni]);
;     }
;     __builtin_amdgcn_sched_group_barrier(0x100, 6, 0);
; #pragma unroll
;     for (int ni = 0; ni < NI; ++ni) { __builtin_amdgcn_sched_group_barrier(0x008, 4, 0); if (ni + 2 < NI) __builtin_amdgcn_sched_group_barrier(0x100, 1, 0); }
;     __builtin_amdgcn_s_setprio(0);
;     if (it + 1 < nk) lstore((it + 1) & 1);
;     if (it + 2 < nk) gload(it + 2);
;     __syncthreads();
.LBB0_1095:
	s_setprio 1
	ds_read_b128 v[168:171], v228 offset:0
	ds_read_b128 v[172:175], v228 offset:1536
	ds_read_b128 v[180:183], v228 offset:3072
	ds_read_b128 v[184:187], v228 offset:4608
	ds_read_b128 v[176:179], v152 offset:12288
	ds_read_b128 v[188:191], v152 offset:13824
	s_waitcnt lgkmcnt(1)
	v_mfma_f32_16x16x32_bf16 v[148:151], v[168:171], v[176:179], v[148:151]
	v_mfma_f32_16x16x32_bf16 v[136:139], v[172:175], v[176:179], v[136:139]
	v_mfma_f32_16x16x32_bf16 v[112:115], v[180:183], v[176:179], v[112:115]
	v_mfma_f32_16x16x32_bf16 v[80:83], v[184:187], v[176:179], v[80:83]
	ds_read_b128 v[176:179], v152 offset:15360
	s_waitcnt vmcnt(6)
	ds_write_b128 v229, v[20:23] offset:36864
	s_waitcnt lgkmcnt(2)
	v_mfma_f32_16x16x32_bf16 v[144:147], v[168:171], v[188:191], v[144:147]
	v_mfma_f32_16x16x32_bf16 v[128:131], v[172:175], v[188:191], v[128:131]
	v_mfma_f32_16x16x32_bf16 v[100:103], v[180:183], v[188:191], v[100:103]
	v_mfma_f32_16x16x32_bf16 v[68:71], v[184:187], v[188:191], v[68:71]
	ds_read_b128 v[188:191], v152 offset:16896
	ds_write_b128 v229, v[16:19] offset:36960
	global_load_dwordx4 v[20:23], v154, s[98:99]
	global_load_dwordx4 v[16:19], v154, s[98:99] offset:64
	s_waitcnt lgkmcnt(3)
	v_mfma_f32_16x16x32_bf16 v[140:143], v[168:171], v[176:179], v[140:143]
	v_mfma_f32_16x16x32_bf16 v[120:123], v[172:175], v[176:179], v[120:123]
	v_mfma_f32_16x16x32_bf16 v[88:91], v[180:183], v[176:179], v[88:91]
	v_mfma_f32_16x16x32_bf16 v[44:47], v[184:187], v[176:179], v[44:47]
	ds_read_b128 v[176:179], v152 offset:18432
	ds_write_b128 v230, v[36:39] offset:49152
	global_load_dwordx4 v[36:39], v156, s[100:101] offset:2048
	s_waitcnt lgkmcnt(3)
	v_mfma_f32_16x16x32_bf16 v[132:135], v[168:171], v[188:191], v[132:135]
	v_mfma_f32_16x16x32_bf16 v[108:111], v[172:175], v[188:191], v[108:111]
	v_mfma_f32_16x16x32_bf16 v[76:79], v[180:183], v[188:191], v[76:79]
	v_mfma_f32_16x16x32_bf16 v[40:43], v[184:187], v[188:191], v[40:43]
	ds_read_b128 v[188:191], v152 offset:19968
	ds_write_b128 v230, v[32:35] offset:49248
	global_load_dwordx4 v[32:35], v156, s[100:101] offset:2112
	s_waitcnt lgkmcnt(3)
	v_mfma_f32_16x16x32_bf16 v[124:127], v[168:171], v[176:179], v[124:127]
	v_mfma_f32_16x16x32_bf16 v[96:99], v[172:175], v[176:179], v[96:99]
	v_mfma_f32_16x16x32_bf16 v[64:67], v[180:183], v[176:179], v[64:67]
	v_mfma_f32_16x16x32_bf16 v[12:15], v[184:187], v[176:179], v[12:15]
	ds_read_b128 v[176:179], v152 offset:21504
	ds_write_b128 v230, v[28:31] offset:49344
	global_load_dwordx4 v[28:31], v156, s[100:101] offset:2176
	s_waitcnt lgkmcnt(3)
	v_mfma_f32_16x16x32_bf16 v[116:119], v[168:171], v[188:191], v[116:119]
	v_mfma_f32_16x16x32_bf16 v[84:87], v[172:175], v[188:191], v[84:87]
	v_mfma_f32_16x16x32_bf16 v[56:59], v[180:183], v[188:191], v[56:59]
	v_mfma_f32_16x16x32_bf16 v[8:11], v[184:187], v[188:191], v[8:11]
	ds_read_b128 v[188:191], v152 offset:23040
	ds_write_b128 v230, v[24:27] offset:49440
	global_load_dwordx4 v[24:27], v156, s[100:101] offset:2240
	s_waitcnt lgkmcnt(3)
	v_mfma_f32_16x16x32_bf16 v[104:107], v[168:171], v[176:179], v[104:107]
	v_mfma_f32_16x16x32_bf16 v[72:75], v[172:175], v[176:179], v[72:75]
	v_mfma_f32_16x16x32_bf16 v[52:55], v[180:183], v[176:179], v[52:55]
	v_mfma_f32_16x16x32_bf16 v[4:7], v[184:187], v[176:179], v[4:7]
	s_add_u32 s98, s98, s16
	s_addc_u32 s99, s99, s17
	s_add_u32 s100, s100, s14
	s_addc_u32 s101, s101, s15
	s_waitcnt lgkmcnt(1)
	v_mfma_f32_16x16x32_bf16 v[92:95], v[168:171], v[188:191], v[92:95]
	v_mfma_f32_16x16x32_bf16 v[60:63], v[172:175], v[188:191], v[60:63]
	v_mfma_f32_16x16x32_bf16 v[48:51], v[180:183], v[188:191], v[48:51]
	v_mfma_f32_16x16x32_bf16 v[0:3], v[184:187], v[188:191], v[0:3]
	s_setprio 0
	s_waitcnt lgkmcnt(0)
	s_barrier
	s_setprio 1
	ds_read_b128 v[168:171], v228 offset:36864
	ds_read_b128 v[172:175], v228 offset:38400
	ds_read_b128 v[180:183], v228 offset:39936
	ds_read_b128 v[184:187], v228 offset:41472
	ds_read_b128 v[176:179], v152 offset:49152
	ds_read_b128 v[188:191], v152 offset:50688
	s_waitcnt lgkmcnt(1)
	v_mfma_f32_16x16x32_bf16 v[148:151], v[168:171], v[176:179], v[148:151]
	v_mfma_f32_16x16x32_bf16 v[136:139], v[172:175], v[176:179], v[136:139]
	v_mfma_f32_16x16x32_bf16 v[112:115], v[180:183], v[176:179], v[112:115]
	v_mfma_f32_16x16x32_bf16 v[80:83], v[184:187], v[176:179], v[80:83]
	ds_read_b128 v[176:179], v152 offset:52224
	s_waitcnt vmcnt(6)
	ds_write_b128 v229, v[200:203] offset:0
	s_waitcnt lgkmcnt(2)
	v_mfma_f32_16x16x32_bf16 v[144:147], v[168:171], v[188:191], v[144:147]
	v_mfma_f32_16x16x32_bf16 v[128:131], v[172:175], v[188:191], v[128:131]
	v_mfma_f32_16x16x32_bf16 v[100:103], v[180:183], v[188:191], v[100:103]
	v_mfma_f32_16x16x32_bf16 v[68:71], v[184:187], v[188:191], v[68:71]
	ds_read_b128 v[188:191], v152 offset:53760
	ds_write_b128 v229, v[204:207] offset:96
	global_load_dwordx4 v[200:203], v154, s[98:99]
	global_load_dwordx4 v[204:207], v154, s[98:99] offset:64
	s_waitcnt lgkmcnt(3)
	v_mfma_f32_16x16x32_bf16 v[140:143], v[168:171], v[176:179], v[140:143]
	v_mfma_f32_16x16x32_bf16 v[120:123], v[172:175], v[176:179], v[120:123]
	v_mfma_f32_16x16x32_bf16 v[88:91], v[180:183], v[176:179], v[88:91]
	v_mfma_f32_16x16x32_bf16 v[44:47], v[184:187], v[176:179], v[44:47]
	ds_read_b128 v[176:179], v152 offset:55296
	ds_write_b128 v230, v[208:211] offset:12288
	global_load_dwordx4 v[208:211], v156, s[100:101] offset:2048
	s_waitcnt lgkmcnt(3)
; DI f32x4 mfma16(bf16x8 a, bf16x8 b, f32x4 c) { return __builtin_amdgcn_mfma_f32_16x16x32_bf16(a, b, c, 0, 0, 0); }
; template <int NI, class XL, class EP>
; DI void gemm_tile(const u16* __restrict__ W, int ldw, int f0, int t0, int K, XL xl, EP ep, unsigned char* smem) {
;     ...
;   for (int it = 0; it < nk; ++it) {
;     const u16* Ws = S0 + (it & 1) * BUF; const u16* Xs = Ws + 128 * LST;
;     __builtin_amdgcn_s_setprio(1);
;     bf16x8 a[4];
; #pragma unroll
;     for (int mi = 0; mi < 4; ++mi) a[mi] = *(const bf16x8*)(Ws + (wf * 64 + mi * 16 + lr) * LST + lq * 8);
; #pragma unroll
;     for (int ni = 0; ni < NI; ++ni) {
;       const bf16x8 b = *(const bf16x8*)(Xs + (wt * (NI * 16) + ni * 16 + lr) * LST + lq * 8);
; #pragma unroll
;       for (int mi = 0; mi < 4; ++mi) acc[mi][ni] = mfma16(a[mi], b, acc[mi][ni]);
;     }
;     __builtin_amdgcn_sched_group_barrier(0x100, 6, 0);
; #pragma unroll
;     for (int ni = 0; ni < NI; ++ni) { __builtin_amdgcn_sched_group_barrier(0x008, 4, 0); if (ni + 2 < NI) __builtin_amdgcn_sched_group_barrier(0x100, 1, 0); }
;     __builtin_amdgcn_s_setprio(0);
;     if (it + 1 < nk) lstore((it + 1) & 1);
;     if (it + 2 < nk) gload(it + 2);
;     __syncthreads();
	v_mfma_f32_16x16x32_bf16 v[132:135], v[168:171], v[188:191], v[132:135]
	v_mfma_f32_16x16x32_bf16 v[108:111], v[172:175], v[188:191], v[108:111]
	v_mfma_f32_16x16x32_bf16 v[76:79], v[180:183], v[188:191], v[76:79]
	v_mfma_f32_16x16x32_bf16 v[40:43], v[184:187], v[188:191], v[40:43]
	ds_read_b128 v[188:191], v152 offset:56832
	ds_write_b128 v230, v[212:215] offset:12384
	global_load_dwordx4 v[212:215], v156, s[100:101] offset:2112
	s_waitcnt lgkmcnt(3)
	v_mfma_f32_16x16x32_bf16 v[124:127], v[168:171], v[176:179], v[124:127]
	v_mfma_f32_16x16x32_bf16 v[96:99], v[172:175], v[176:179], v[96:99]
	v_mfma_f32_16x16x32_bf16 v[64:67], v[180:183], v[176:179], v[64:67]
	v_mfma_f32_16x16x32_bf16 v[12:15], v[184:187], v[176:179], v[12:15]
	ds_read_b128 v[176:179], v152 offset:58368
	ds_write_b128 v230, v[220:223] offset:12480
	global_load_dwordx4 v[220:223], v156, s[100:101] offset:2176
	s_waitcnt lgkmcnt(3)
	v_mfma_f32_16x16x32_bf16 v[116:119], v[168:171], v[188:191], v[116:119]
	v_mfma_f32_16x16x32_bf16 v[84:87], v[172:175], v[188:191], v[84:87]
	v_mfma_f32_16x16x32_bf16 v[56:59], v[180:183], v[188:191], v[56:59]
	v_mfma_f32_16x16x32_bf16 v[8:11], v[184:187], v[188:191], v[8:11]
	ds_read_b128 v[188:191], v152 offset:59904
	ds_write_b128 v230, v[224:227] offset:12576
	global_load_dwordx4 v[224:227], v156, s[100:101] offset:2240
	s_waitcnt lgkmcnt(3)
	v_mfma_f32_16x16x32_bf16 v[104:107], v[168:171], v[176:179], v[104:107]
	v_mfma_f32_16x16x32_bf16 v[72:75], v[172:175], v[176:179], v[72:75]
	v_mfma_f32_16x16x32_bf16 v[52:55], v[180:183], v[176:179], v[52:55]
	v_mfma_f32_16x16x32_bf16 v[4:7], v[184:187], v[176:179], v[4:7]
	s_add_u32 s98, s98, s16
	s_addc_u32 s99, s99, s17
	s_add_u32 s100, s100, s14
	s_addc_u32 s101, s101, s15
	s_add_i32 s33, s33, 2
	s_waitcnt lgkmcnt(1)
	v_mfma_f32_16x16x32_bf16 v[92:95], v[168:171], v[188:191], v[92:95]
	v_mfma_f32_16x16x32_bf16 v[60:63], v[172:175], v[188:191], v[60:63]
	v_mfma_f32_16x16x32_bf16 v[48:51], v[180:183], v[188:191], v[48:51]
	v_mfma_f32_16x16x32_bf16 v[0:3], v[184:187], v[188:191], v[0:3]
	s_setprio 0
	s_cmpk_lg_i32 s33, 85
	s_waitcnt lgkmcnt(0)
	s_barrier
	s_cbranch_scc1 .LBB0_1095
	s_setprio 1
	ds_read_b128 v[168:171], v228 offset:0
	ds_read_b128 v[172:175], v228 offset:1536
	ds_read_b128 v[180:183], v228 offset:3072
	ds_read_b128 v[184:187], v228 offset:4608
	ds_read_b128 v[176:179], v152 offset:12288
	ds_read_b128 v[188:191], v152 offset:13824
	s_waitcnt lgkmcnt(1)
	v_mfma_f32_16x16x32_bf16 v[148:151], v[168:171], v[176:179], v[148:151]
	v_mfma_f32_16x16x32_bf16 v[136:139], v[172:175], v[176:179], v[136:139]
	v_mfma_f32_16x16x32_bf16 v[112:115], v[180:183], v[176:179], v[112:115]
	v_mfma_f32_16x16x32_bf16 v[80:83], v[184:187], v[176:179], v[80:83]
	ds_read_b128 v[176:179], v152 offset:15360
	s_waitcnt vmcnt(6)
	ds_write_b128 v229, v[20:23] offset:36864
	s_waitcnt lgkmcnt(2)
	v_mfma_f32_16x16x32_bf16 v[144:147], v[168:171], v[188:191], v[144:147]
	v_mfma_f32_16x16x32_bf16 v[128:131], v[172:175], v[188:191], v[128:131]
	v_mfma_f32_16x16x32_bf16 v[100:103], v[180:183], v[188:191], v[100:103]
	v_mfma_f32_16x16x32_bf16 v[68:71], v[184:187], v[188:191], v[68:71]
	ds_read_b128 v[188:191], v152 offset:16896
	ds_write_b128 v229, v[16:19] offset:36960
	global_load_dwordx4 v[20:23], v154, s[98:99]
	global_load_dwordx4 v[16:19], v154, s[98:99] offset:64
	s_waitcnt lgkmcnt(3)
	v_mfma_f32_16x16x32_bf16 v[140:143], v[168:171], v[176:179], v[140:143]
	v_mfma_f32_16x16x32_bf16 v[120:123], v[172:175], v[176:179], v[120:123]
	v_mfma_f32_16x16x32_bf16 v[88:91], v[180:183], v[176:179], v[88:91]
	v_mfma_f32_16x16x32_bf16 v[44:47], v[184:187], v[176:179], v[44:47]
	ds_read_b128 v[176:179], v152 offset:18432
	ds_write_b128 v230, v[36:39] offset:49152
	global_load_dwordx4 v[36:39], v156, s[100:101] offset:2048
	s_waitcnt lgkmcnt(3)
	v_mfma_f32_16x16x32_bf16 v[132:135], v[168:171], v[188:191], v[132:135]
	v_mfma_f32_16x16x32_bf16 v[108:111], v[172:175], v[188:191], v[108:111]
	v_mfma_f32_16x16x32_bf16 v[76:79], v[180:183], v[188:191], v[76:79]
	v_mfma_f32_16x16x32_bf16 v[40:43], v[184:187], v[188:191], v[40:43]
	ds_read_b128 v[188:191], v152 offset:19968
	ds_write_b128 v230, v[32:35] offset:49248
	global_load_dwordx4 v[32:35], v156, s[100:101] offset:2112
	s_waitcnt lgkmcnt(3)
	v_mfma_f32_16x16x32_bf16 v[124:127], v[168:171], v[176:179], v[124:127]
	v_mfma_f32_16x16x32_bf16 v[96:99], v[172:175], v[176:179], v[96:99]
	v_mfma_f32_16x16x32_bf16 v[64:67], v[180:183], v[176:179], v[64:67]
	v_mfma_f32_16x16x32_bf16 v[12:15], v[184:187], v[176:179], v[12:15]
	ds_read_b128 v[176:179], v152 offset:21504
	ds_write_b128 v230, v[28:31] offset:49344
	global_load_dwordx4 v[28:31], v156, s[100:101] offset:2176
	s_waitcnt lgkmcnt(3)
	v_mfma_f32_16x16x32_bf16 v[116:119], v[168:171], v[188:191], v[116:119]
	v_mfma_f32_16x16x32_bf16 v[84:87], v[172:175], v[188:191], v[84:87]
	v_mfma_f32_16x16x32_bf16 v[56:59], v[180:183], v[188:191], v[56:59]
	v_mfma_f32_16x16x32_bf16 v[8:11], v[184:187], v[188:191], v[8:11]
	ds_read_b128 v[188:191], v152 offset:23040
	ds_write_b128 v230, v[24:27] offset:49440
	global_load_dwordx4 v[24:27], v156, s[100:101] offset:2240
	s_waitcnt lgkmcnt(3)
	v_mfma_f32_16x16x32_bf16 v[104:107], v[168:171], v[176:179], v[104:107]
	v_mfma_f32_16x16x32_bf16 v[72:75], v[172:175], v[176:179], v[72:75]
	v_mfma_f32_16x16x32_bf16 v[52:55], v[180:183], v[176:179], v[52:55]
	v_mfma_f32_16x16x32_bf16 v[4:7], v[184:187], v[176:179], v[4:7]
	s_add_u32 s98, s98, s16
	s_addc_u32 s99, s99, s17
	s_add_u32 s100, s100, s14
	s_addc_u32 s101, s101, s15
	s_waitcnt lgkmcnt(1)
	v_mfma_f32_16x16x32_bf16 v[92:95], v[168:171], v[188:191], v[92:95]
	v_mfma_f32_16x16x32_bf16 v[60:63], v[172:175], v[188:191], v[60:63]
	v_mfma_f32_16x16x32_bf16 v[48:51], v[180:183], v[188:191], v[48:51]
	v_mfma_f32_16x16x32_bf16 v[0:3], v[184:187], v[188:191], v[0:3]
	s_setprio 0
	s_waitcnt lgkmcnt(0)
	s_barrier
; DI f32x4 mfma16(bf16x8 a, bf16x8 b, f32x4 c) { return __builtin_amdgcn_mfma_f32_16x16x32_bf16(a, b, c, 0, 0, 0); }
; template <int NI, class XL, class EP>
; DI void gemm_tile(const u16* __restrict__ W, int ldw, int f0, int t0, int K, XL xl, EP ep, unsigned char* smem) {
;     ...
;   for (int it = 0; it < nk; ++it) {
;     const u16* Ws = S0 + (it & 1) * BUF; const u16* Xs = Ws + 128 * LST;
;     __builtin_amdgcn_s_setprio(1);
;     bf16x8 a[4];
; #pragma unroll
;     for (int mi = 0; mi < 4; ++mi) a[mi] = *(const bf16x8*)(Ws + (wf * 64 + mi * 16 + lr) * LST + lq * 8);
; #pragma unroll
;     for (int ni = 0; ni < NI; ++ni) {
;       const bf16x8 b = *(const bf16x8*)(Xs + (wt * (NI * 16) + ni * 16 + lr) * LST + lq * 8);
; #pragma unroll
;       for (int mi = 0; mi < 4; ++mi) acc[mi][ni] = mfma16(a[mi], b, acc[mi][ni]);
;     }
;     __builtin_amdgcn_sched_group_barrier(0x100, 6, 0);
; #pragma unroll
;     for (int ni = 0; ni < NI; ++ni) { __builtin_amdgcn_sched_group_barrier(0x008, 4, 0); if (ni + 2 < NI) __builtin_amdgcn_sched_group_barrier(0x100, 1, 0); }
;     __builtin_amdgcn_s_setprio(0);
;     if (it + 1 < nk) lstore((it + 1) & 1);
;     if (it + 2 < nk) gload(it + 2);
;     __syncthreads();
;   }
	s_setprio 1
	ds_read_b128 v[168:171], v228 offset:36864
	ds_read_b128 v[172:175], v228 offset:38400
	ds_read_b128 v[180:183], v228 offset:39936
	ds_read_b128 v[184:187], v228 offset:41472
	ds_read_b128 v[176:179], v152 offset:49152
	ds_read_b128 v[188:191], v152 offset:50688
	s_waitcnt lgkmcnt(1)
	v_mfma_f32_16x16x32_bf16 v[148:151], v[168:171], v[176:179], v[148:151]
	v_mfma_f32_16x16x32_bf16 v[136:139], v[172:175], v[176:179], v[136:139]
	v_mfma_f32_16x16x32_bf16 v[112:115], v[180:183], v[176:179], v[112:115]
	v_mfma_f32_16x16x32_bf16 v[80:83], v[184:187], v[176:179], v[80:83]
	ds_read_b128 v[176:179], v152 offset:52224
	s_waitcnt vmcnt(6)
	ds_write_b128 v229, v[200:203] offset:0
	s_waitcnt lgkmcnt(2)
	v_mfma_f32_16x16x32_bf16 v[144:147], v[168:171], v[188:191], v[144:147]
	v_mfma_f32_16x16x32_bf16 v[128:131], v[172:175], v[188:191], v[128:131]
	v_mfma_f32_16x16x32_bf16 v[100:103], v[180:183], v[188:191], v[100:103]
	v_mfma_f32_16x16x32_bf16 v[68:71], v[184:187], v[188:191], v[68:71]
	ds_read_b128 v[188:191], v152 offset:53760
	ds_write_b128 v229, v[204:207] offset:96
	s_waitcnt lgkmcnt(3)
	v_mfma_f32_16x16x32_bf16 v[140:143], v[168:171], v[176:179], v[140:143]
	v_mfma_f32_16x16x32_bf16 v[120:123], v[172:175], v[176:179], v[120:123]
	v_mfma_f32_16x16x32_bf16 v[88:91], v[180:183], v[176:179], v[88:91]
	v_mfma_f32_16x16x32_bf16 v[44:47], v[184:187], v[176:179], v[44:47]
	ds_read_b128 v[176:179], v152 offset:55296
	ds_write_b128 v230, v[208:211] offset:12288
	s_waitcnt lgkmcnt(3)
	v_mfma_f32_16x16x32_bf16 v[132:135], v[168:171], v[188:191], v[132:135]
	v_mfma_f32_16x16x32_bf16 v[108:111], v[172:175], v[188:191], v[108:111]
	v_mfma_f32_16x16x32_bf16 v[76:79], v[180:183], v[188:191], v[76:79]
	v_mfma_f32_16x16x32_bf16 v[40:43], v[184:187], v[188:191], v[40:43]
	ds_read_b128 v[188:191], v152 offset:56832
	ds_write_b128 v230, v[212:215] offset:12384
	s_waitcnt lgkmcnt(3)
	v_mfma_f32_16x16x32_bf16 v[124:127], v[168:171], v[176:179], v[124:127]
	v_mfma_f32_16x16x32_bf16 v[96:99], v[172:175], v[176:179], v[96:99]
	v_mfma_f32_16x16x32_bf16 v[64:67], v[180:183], v[176:179], v[64:67]
	v_mfma_f32_16x16x32_bf16 v[12:15], v[184:187], v[176:179], v[12:15]
	ds_read_b128 v[176:179], v152 offset:58368
	ds_write_b128 v230, v[220:223] offset:12480
	s_waitcnt lgkmcnt(3)
	v_mfma_f32_16x16x32_bf16 v[116:119], v[168:171], v[188:191], v[116:119]
	v_mfma_f32_16x16x32_bf16 v[84:87], v[172:175], v[188:191], v[84:87]
	v_mfma_f32_16x16x32_bf16 v[56:59], v[180:183], v[188:191], v[56:59]
	v_mfma_f32_16x16x32_bf16 v[8:11], v[184:187], v[188:191], v[8:11]
	ds_read_b128 v[188:191], v152 offset:59904
	ds_write_b128 v230, v[224:227] offset:12576
	s_waitcnt lgkmcnt(3)
	v_mfma_f32_16x16x32_bf16 v[104:107], v[168:171], v[176:179], v[104:107]
	v_mfma_f32_16x16x32_bf16 v[72:75], v[172:175], v[176:179], v[72:75]
	v_mfma_f32_16x16x32_bf16 v[52:55], v[180:183], v[176:179], v[52:55]
	v_mfma_f32_16x16x32_bf16 v[4:7], v[184:187], v[176:179], v[4:7]
	s_add_i32 s33, s33, 2
	s_waitcnt lgkmcnt(1)
	v_mfma_f32_16x16x32_bf16 v[92:95], v[168:171], v[188:191], v[92:95]
	v_mfma_f32_16x16x32_bf16 v[60:63], v[172:175], v[188:191], v[60:63]
	v_mfma_f32_16x16x32_bf16 v[48:51], v[180:183], v[188:191], v[48:51]
	v_mfma_f32_16x16x32_bf16 v[0:3], v[184:187], v[188:191], v[0:3]
	s_setprio 0
	s_waitcnt lgkmcnt(0)
	s_barrier
	s_setprio 1
	v_lshl_add_u32 v152, v167, 1, v164
	ds_read_b128 v[154:157], v152
	v_lshl_add_u32 v161, v165, 1, v164
	ds_read_b128 v[164:167], v152 offset:1536
	ds_read_b128 v[172:175], v152 offset:3072
	ds_read_b128 v[176:179], v152 offset:4608
	ds_read_b128 v[168:171], v161 offset:12288
	ds_read_b128 v[180:183], v161 offset:13824
	s_waitcnt lgkmcnt(1)
	v_mfma_f32_16x16x32_bf16 v[148:151], v[154:157], v[168:171], v[148:151]
	v_mfma_f32_16x16x32_bf16 v[136:139], v[164:167], v[168:171], v[136:139]
	v_mfma_f32_16x16x32_bf16 v[112:115], v[172:175], v[168:171], v[112:115]
	v_mfma_f32_16x16x32_bf16 v[80:83], v[176:179], v[168:171], v[80:83]
	ds_read_b128 v[168:171], v161 offset:15360
	s_waitcnt lgkmcnt(1)
	v_mfma_f32_16x16x32_bf16 v[144:147], v[154:157], v[180:183], v[144:147]
	v_mfma_f32_16x16x32_bf16 v[128:131], v[164:167], v[180:183], v[128:131]
	v_mfma_f32_16x16x32_bf16 v[100:103], v[172:175], v[180:183], v[100:103]
	v_mfma_f32_16x16x32_bf16 v[68:71], v[176:179], v[180:183], v[68:71]
	ds_read_b128 v[180:183], v161 offset:16896
	s_waitcnt lgkmcnt(1)
	v_mfma_f32_16x16x32_bf16 v[140:143], v[154:157], v[168:171], v[140:143]
	v_mfma_f32_16x16x32_bf16 v[120:123], v[164:167], v[168:171], v[120:123]
	v_mfma_f32_16x16x32_bf16 v[184:187], v[172:175], v[168:171], v[88:91]
	v_mfma_f32_16x16x32_bf16 v[44:47], v[176:179], v[168:171], v[44:47]
	s_nop 1
	ds_read_b128 v[88:91], v161 offset:18432
	s_waitcnt lgkmcnt(1)
	v_mfma_f32_16x16x32_bf16 v[132:135], v[154:157], v[180:183], v[132:135]
	v_mfma_f32_16x16x32_bf16 v[168:171], v[164:167], v[180:183], v[108:111]
	v_mfma_f32_16x16x32_bf16 v[188:191], v[172:175], v[180:183], v[76:79]
	v_mfma_f32_16x16x32_bf16 v[180:183], v[176:179], v[180:183], v[40:43]
	s_nop 2
	ds_read_b128 v[40:43], v161 offset:19968
	s_waitcnt lgkmcnt(1)
	v_mfma_f32_16x16x32_bf16 v[124:127], v[154:157], v[88:91], v[124:127]
	v_mfma_f32_16x16x32_bf16 v[192:195], v[164:167], v[88:91], v[96:99]
	v_mfma_f32_16x16x32_bf16 v[196:199], v[172:175], v[88:91], v[64:67]
	v_mfma_f32_16x16x32_bf16 v[200:203], v[176:179], v[88:91], v[12:15]
	s_nop 2
	ds_read_b128 v[12:15], v161 offset:21504
	s_waitcnt lgkmcnt(1)
	v_mfma_f32_16x16x32_bf16 v[116:119], v[154:157], v[40:43], v[116:119]
	v_mfma_f32_16x16x32_bf16 v[204:207], v[164:167], v[40:43], v[84:87]
	v_mfma_f32_16x16x32_bf16 v[56:59], v[172:175], v[40:43], v[56:59]
	v_mfma_f32_16x16x32_bf16 v[208:211], v[176:179], v[40:43], v[8:11]
	s_nop 2
	ds_read_b128 v[8:11], v161 offset:23040
	s_waitcnt lgkmcnt(1)
	v_mfma_f32_16x16x32_bf16 v[212:215], v[154:157], v[12:15], v[104:107]
	v_mfma_f32_16x16x32_bf16 v[72:75], v[164:167], v[12:15], v[72:75]
	v_mfma_f32_16x16x32_bf16 v[220:223], v[172:175], v[12:15], v[52:55]
	v_mfma_f32_16x16x32_bf16 v[224:227], v[176:179], v[12:15], v[4:7]
	s_waitcnt lgkmcnt(0)
	v_mfma_f32_16x16x32_bf16 v[154:157], v[154:157], v[8:11], v[92:95]
	v_mfma_f32_16x16x32_bf16 v[60:63], v[164:167], v[8:11], v[60:63]
	v_mfma_f32_16x16x32_bf16 v[164:167], v[172:175], v[8:11], v[48:51]
	v_mfma_f32_16x16x32_bf16 v[172:175], v[176:179], v[8:11], v[0:3]
	s_setprio 0
	s_waitcnt vmcnt(5)
	ds_write_b128 v162, v[20:23] offset:36864
	s_waitcnt vmcnt(4)
	ds_write_b128 v162, v[16:19] offset:36960
	s_waitcnt vmcnt(3)
	ds_write_b128 v163, v[36:39] offset:49152
	s_waitcnt vmcnt(2)
	ds_write_b128 v163, v[32:35] offset:49248
	s_waitcnt vmcnt(1)
	ds_write_b128 v163, v[28:31] offset:49344
	s_waitcnt vmcnt(0)
	ds_write_b128 v163, v[24:27] offset:49440
	s_waitcnt lgkmcnt(0)
	s_barrier
; DI void store4(u16* dst, f32x4 v) { uint2 w; w.x = cvtpk(v[0], v[1]); w.y = cvtpk(v[2], v[3]); *(uint2*)dst = w; }
; DI f32x4 mfma16(bf16x8 a, bf16x8 b, f32x4 c) { return __builtin_amdgcn_mfma_f32_16x16x32_bf16(a, b, c, 0, 0, 0); }
; template <int NI, class XL, class EP>
; DI void gemm_tile(const u16* __restrict__ W, int ldw, int f0, int t0, int K, XL xl, EP ep, unsigned char* smem) {
;     ...
; #pragma unroll
;     for (int mi = 0; mi < 4; ++mi) a[mi] = *(const bf16x8*)(Ws + (wf * 64 + mi * 16 + lr) * LST + lq * 8);
; #pragma unroll
;     for (int ni = 0; ni < NI; ++ni) {
;       const bf16x8 b = *(const bf16x8*)(Xs + (wt * (NI * 16) + ni * 16 + lr) * LST + lq * 8);
; #pragma unroll
;       for (int mi = 0; mi < 4; ++mi) acc[mi][ni] = mfma16(a[mi], b, acc[mi][ni]);
;     }
; DI void phase9(const Params& p, const Sched& sched, unsigned char* smem) {
;     ...
;       constexpr int EST = 136;
;       u16* Ls = (u16*)smem;
;       const int b = tb >> 11;
;       __syncthreads();
; #pragma unroll
;       for (int mi = 0; mi < 4; ++mi) {
;         const int f = fb + mi * 16 + lq * 4; const float4 gm = *(const float4*)(mod + (size_t)b * 6144 + 5120 + f);
; #pragma unroll
;         for (int ni = 0; ni < 8; ++ni) {
;           const f32x4 o = {gm.x * acc[mi][ni][0], gm.y * acc[mi][ni][1], gm.z * acc[mi][ni][2], gm.w * acc[mi][ni][3]};
;           store4(Ls + (wt * 128 + ni * 16 + lr) * EST + wf * 64 + mi * 16 + lq * 4, o);
;         }
;       }
	s_lshl_b32 s30, s30, 7
	s_setprio 1
	ds_read_b128 v[28:31], v152 offset:36864
	ds_read_b128 v[176:179], v152 offset:38400
	ds_read_b128 v[228:231], v152 offset:39936
	ds_read_b128 v[232:235], v152 offset:41472
	ds_read_b128 v[0:3], v161 offset:49152
	ds_read_b128 v[4:7], v161 offset:50688
	s_waitcnt lgkmcnt(1)
	v_mfma_f32_16x16x32_bf16 v[88:91], v[28:31], v[0:3], v[148:151]
	v_mfma_f32_16x16x32_bf16 v[64:67], v[176:179], v[0:3], v[136:139]
	v_mfma_f32_16x16x32_bf16 v[32:35], v[228:231], v[0:3], v[112:115]
	v_mfma_f32_16x16x32_bf16 v[0:3], v[232:235], v[0:3], v[80:83]
	ds_read_b128 v[8:11], v161 offset:52224
	s_waitcnt lgkmcnt(1)
	v_mfma_f32_16x16x32_bf16 v[96:99], v[28:31], v[4:7], v[144:147]
	v_mfma_f32_16x16x32_bf16 v[76:79], v[176:179], v[4:7], v[128:131]
	v_mfma_f32_16x16x32_bf16 v[36:39], v[228:231], v[4:7], v[100:103]
	v_mfma_f32_16x16x32_bf16 v[4:7], v[232:235], v[4:7], v[68:71]
	ds_read_b128 v[12:15], v161 offset:53760
	s_waitcnt lgkmcnt(1)
	v_mfma_f32_16x16x32_bf16 v[104:107], v[28:31], v[8:11], v[140:143]
	v_mfma_f32_16x16x32_bf16 v[84:87], v[176:179], v[8:11], v[120:123]
	v_mfma_f32_16x16x32_bf16 v[40:43], v[228:231], v[8:11], v[184:187]
	v_mfma_f32_16x16x32_bf16 v[8:11], v[232:235], v[8:11], v[44:47]
	ds_read_b128 v[16:19], v161 offset:55296
	s_waitcnt lgkmcnt(1)
	v_mfma_f32_16x16x32_bf16 v[108:111], v[28:31], v[12:15], v[132:135]
	v_mfma_f32_16x16x32_bf16 v[92:95], v[176:179], v[12:15], v[168:171]
	v_mfma_f32_16x16x32_bf16 v[44:47], v[228:231], v[12:15], v[188:191]
	v_mfma_f32_16x16x32_bf16 v[12:15], v[232:235], v[12:15], v[180:183]
	ds_read_b128 v[20:23], v161 offset:56832
	s_waitcnt lgkmcnt(1)
	v_mfma_f32_16x16x32_bf16 v[112:115], v[28:31], v[16:19], v[124:127]
	v_mfma_f32_16x16x32_bf16 v[100:103], v[176:179], v[16:19], v[192:195]
	v_mfma_f32_16x16x32_bf16 v[48:51], v[228:231], v[16:19], v[196:199]
	v_mfma_f32_16x16x32_bf16 v[16:19], v[232:235], v[16:19], v[200:203]
	ds_read_b128 v[24:27], v161 offset:58368
	s_waitcnt lgkmcnt(1)
	v_mfma_f32_16x16x32_bf16 v[116:119], v[28:31], v[20:23], v[116:119]
	v_mfma_f32_16x16x32_bf16 v[68:71], v[176:179], v[20:23], v[204:207]
	v_mfma_f32_16x16x32_bf16 v[52:55], v[228:231], v[20:23], v[56:59]
	v_mfma_f32_16x16x32_bf16 v[20:23], v[232:235], v[20:23], v[208:211]
	ds_read_b128 v[128:131], v161 offset:59904
	s_waitcnt lgkmcnt(1)
	v_mfma_f32_16x16x32_bf16 v[120:123], v[28:31], v[24:27], v[212:215]
	v_mfma_f32_16x16x32_bf16 v[80:83], v[176:179], v[24:27], v[72:75]
	v_mfma_f32_16x16x32_bf16 v[56:59], v[228:231], v[24:27], v[220:223]
	v_mfma_f32_16x16x32_bf16 v[24:27], v[232:235], v[24:27], v[224:227]
	s_waitcnt lgkmcnt(0)
	v_mfma_f32_16x16x32_bf16 v[124:127], v[28:31], v[128:131], v[154:157]
	v_mfma_f32_16x16x32_bf16 v[72:75], v[176:179], v[128:131], v[60:63]
	v_mfma_f32_16x16x32_bf16 v[60:63], v[228:231], v[128:131], v[164:167]
	v_mfma_f32_16x16x32_bf16 v[28:31], v[232:235], v[128:131], v[172:175]
	s_setprio 0
	s_ashr_i32 s31, s31, 3
	v_add_u32_e32 v128, s30, v160
	s_mul_hi_i32 s33, s31, 0x6000
	s_mulk_i32 s31, 0x6000
	v_lshl_or_b32 v128, v158, 2, v128
	s_add_u32 s34, s72, s31
	s_addc_u32 s35, s73, s33
	v_ashrrev_i32_e32 v129, 31, v128
	v_lshl_add_u64 v[128:129], v[128:129], 2, s[34:35]
	v_add_co_u32_e32 v140, vcc, s24, v128
	v_mul_u32_u24_e32 v138, 0x88, v159
	s_nop 0
	v_addc_co_u32_e32 v141, vcc, 0, v129, vcc
	v_lshlrev_b32_e32 v136, 1, v160
	v_lshlrev_b32_e32 v137, 3, v158
	v_lshlrev_b32_e32 v138, 1, v138
	s_barrier
	s_barrier
	global_load_dwordx4 v[128:131], v[140:141], off
	global_load_dwordx4 v[132:135], v[140:141], off offset:64
	v_add3_u32 v144, v136, v137, v138
	global_load_dwordx4 v[136:139], v[140:141], off offset:128
	v_add_u32_e32 v145, 0x1000, v144
	global_load_dwordx4 v[140:143], v[140:141], off offset:192
	v_add_u32_e32 v146, 0x2000, v144
	v_add_u32_e32 v147, 0x3000, v144
	v_add_u32_e32 v148, 0x4000, v144
	s_add_i32 s28, s28, s78
	s_add_i32 s27, s27, s78
	s_cmp_gt_i32 s28, 63
	s_waitcnt vmcnt(3)
	v_pk_mul_f32 v[88:89], v[88:89], v[128:129]
	v_pk_mul_f32 v[90:91], v[90:91], v[130:131]
	v_pk_mul_f32 v[96:97], v[96:97], v[128:129]
	s_waitcnt vmcnt(1)
	v_pk_mul_f32 v[32:33], v[32:33], v[136:137]
	v_pk_mul_f32 v[34:35], v[34:35], v[138:139]
	s_waitcnt vmcnt(0)
	v_pk_mul_f32 v[0:1], v[0:1], v[140:141]
	v_pk_mul_f32 v[2:3], v[2:3], v[142:143]
	v_cvt_pk_bf16_f32 v32, v32, v33
	v_cvt_pk_bf16_f32 v33, v34, v35
	v_cvt_pk_bf16_f32 v0, v0, v1
	v_cvt_pk_bf16_f32 v1, v2, v3
	v_pk_mul_f32 v[34:35], v[36:37], v[136:137]
	v_pk_mul_f32 v[36:37], v[38:39], v[138:139]
	ds_write2_b64 v144, v[32:33], v[0:1] offset0:8 offset1:12
	v_pk_mul_f32 v[0:1], v[4:5], v[140:141]
	v_pk_mul_f32 v[2:3], v[6:7], v[142:143]
	v_cvt_pk_bf16_f32 v34, v34, v35
	v_cvt_pk_bf16_f32 v35, v36, v37
	v_cvt_pk_bf16_f32 v0, v0, v1
	v_cvt_pk_bf16_f32 v1, v2, v3
	v_pk_mul_f32 v[36:37], v[40:41], v[136:137]
	v_pk_mul_f32 v[38:39], v[42:43], v[138:139]
	ds_write2_b64 v145, v[34:35], v[0:1] offset0:40 offset1:44
	v_pk_mul_f32 v[0:1], v[8:9], v[140:141]
	v_pk_mul_f32 v[2:3], v[10:11], v[142:143]
	v_cvt_pk_bf16_f32 v36, v36, v37
	v_cvt_pk_bf16_f32 v37, v38, v39
	v_cvt_pk_bf16_f32 v0, v0, v1
	v_cvt_pk_bf16_f32 v1, v2, v3
	v_pk_mul_f32 v[38:39], v[44:45], v[136:137]
	v_pk_mul_f32 v[40:41], v[46:47], v[138:139]
	ds_write2_b64 v146, v[36:37], v[0:1] offset0:72 offset1:76
	v_pk_mul_f32 v[0:1], v[12:13], v[140:141]
	v_pk_mul_f32 v[2:3], v[14:15], v[142:143]
	v_cvt_pk_bf16_f32 v38, v38, v39
	v_cvt_pk_bf16_f32 v39, v40, v41
	v_cvt_pk_bf16_f32 v0, v0, v1
	v_cvt_pk_bf16_f32 v1, v2, v3
	v_pk_mul_f32 v[98:99], v[98:99], v[130:131]
	v_pk_mul_f32 v[64:65], v[64:65], v[132:133]
	v_pk_mul_f32 v[66:67], v[66:67], v[134:135]
; DI void store4(u16* dst, f32x4 v) { uint2 w; w.x = cvtpk(v[0], v[1]); w.y = cvtpk(v[2], v[3]); *(uint2*)dst = w; }
; DI void phase9(const Params& p, const Sched& sched, unsigned char* smem) {
;     ...
; #pragma unroll
;       for (int mi = 0; mi < 4; ++mi) {
;         const int f = fb + mi * 16 + lq * 4; const float4 gm = *(const float4*)(mod + (size_t)b * 6144 + 5120 + f);
; #pragma unroll
;         for (int ni = 0; ni < 8; ++ni) {
;           const f32x4 o = {gm.x * acc[mi][ni][0], gm.y * acc[mi][ni][1], gm.z * acc[mi][ni][2], gm.w * acc[mi][ni][3]};
;           store4(Ls + (wt * 128 + ni * 16 + lr) * EST + wf * 64 + mi * 16 + lq * 4, o);
;         }
;       }
;       __syncthreads();
	v_pk_mul_f32 v[76:77], v[76:77], v[132:133]
	v_pk_mul_f32 v[78:79], v[78:79], v[134:135]
	v_pk_mul_f32 v[40:41], v[48:49], v[136:137]
	v_pk_mul_f32 v[42:43], v[50:51], v[138:139]
	ds_write2_b64 v147, v[38:39], v[0:1] offset0:104 offset1:108
	v_pk_mul_f32 v[0:1], v[16:17], v[140:141]
	v_pk_mul_f32 v[2:3], v[18:19], v[142:143]
	v_cvt_pk_bf16_f32 v88, v88, v89
	v_cvt_pk_bf16_f32 v89, v90, v91
	v_cvt_pk_bf16_f32 v90, v96, v97
	v_cvt_pk_bf16_f32 v91, v98, v99
	v_cvt_pk_bf16_f32 v64, v64, v65
	v_cvt_pk_bf16_f32 v65, v66, v67
	v_cvt_pk_bf16_f32 v66, v76, v77
	v_cvt_pk_bf16_f32 v67, v78, v79
	v_cvt_pk_bf16_f32 v40, v40, v41
	v_cvt_pk_bf16_f32 v41, v42, v43
	v_cvt_pk_bf16_f32 v0, v0, v1
	v_cvt_pk_bf16_f32 v1, v2, v3
	v_pk_mul_f32 v[106:107], v[106:107], v[130:131]
	v_pk_mul_f32 v[116:117], v[116:117], v[128:129]
	v_pk_mul_f32 v[118:119], v[118:119], v[130:131]
	ds_write2_b64 v144, v[88:89], v[64:65] offset1:4
	ds_write2_b64 v145, v[90:91], v[66:67] offset0:32 offset1:36
	v_pk_mul_f32 v[64:65], v[68:69], v[132:133]
	v_pk_mul_f32 v[66:67], v[70:71], v[134:135]
	v_pk_mul_f32 v[42:43], v[52:53], v[136:137]
	v_pk_mul_f32 v[44:45], v[54:55], v[138:139]
	ds_write2_b64 v148, v[40:41], v[0:1] offset0:136 offset1:140
	v_pk_mul_f32 v[0:1], v[20:21], v[140:141]
	v_pk_mul_f32 v[2:3], v[22:23], v[142:143]
	v_cvt_pk_bf16_f32 v97, v106, v107
	v_cvt_pk_bf16_f32 v106, v116, v117
	v_cvt_pk_bf16_f32 v107, v118, v119
	v_cvt_pk_bf16_f32 v64, v64, v65
	v_cvt_pk_bf16_f32 v65, v66, v67
	v_add_u32_e32 v68, 0x5000, v144
	v_cvt_pk_bf16_f32 v42, v42, v43
	v_cvt_pk_bf16_f32 v43, v44, v45
	v_cvt_pk_bf16_f32 v0, v0, v1
	v_cvt_pk_bf16_f32 v1, v2, v3
	v_pk_mul_f32 v[108:109], v[108:109], v[128:129]
	v_pk_mul_f32 v[120:121], v[120:121], v[128:129]
	v_pk_mul_f32 v[122:123], v[122:123], v[130:131]
	ds_write2_b64 v68, v[106:107], v[64:65] offset0:160 offset1:164
	v_pk_mul_f32 v[64:65], v[80:81], v[132:133]
	v_pk_mul_f32 v[66:67], v[82:83], v[134:135]
	v_pk_mul_f32 v[44:45], v[56:57], v[136:137]
	v_pk_mul_f32 v[46:47], v[58:59], v[138:139]
	ds_write2_b64 v68, v[42:43], v[0:1] offset0:168 offset1:172
	v_pk_mul_f32 v[0:1], v[24:25], v[140:141]
	v_pk_mul_f32 v[2:3], v[26:27], v[142:143]
	v_cvt_pk_bf16_f32 v98, v108, v109
	v_cvt_pk_bf16_f32 v108, v120, v121
	v_cvt_pk_bf16_f32 v109, v122, v123
	v_cvt_pk_bf16_f32 v64, v64, v65
	v_cvt_pk_bf16_f32 v65, v66, v67
	v_add_u32_e32 v69, 0x6000, v144
	v_cvt_pk_bf16_f32 v44, v44, v45
	v_cvt_pk_bf16_f32 v45, v46, v47
	v_cvt_pk_bf16_f32 v0, v0, v1
	v_cvt_pk_bf16_f32 v1, v2, v3
	v_pk_mul_f32 v[104:105], v[104:105], v[128:129]
	v_pk_mul_f32 v[110:111], v[110:111], v[130:131]
	v_pk_mul_f32 v[112:113], v[112:113], v[128:129]
	v_pk_mul_f32 v[114:115], v[114:115], v[130:131]
	v_pk_mul_f32 v[124:125], v[124:125], v[128:129]
	v_pk_mul_f32 v[126:127], v[126:127], v[130:131]
	v_pk_mul_f32 v[84:85], v[84:85], v[132:133]
	v_pk_mul_f32 v[86:87], v[86:87], v[134:135]
	v_pk_mul_f32 v[92:93], v[92:93], v[132:133]
	v_pk_mul_f32 v[94:95], v[94:95], v[134:135]
	v_pk_mul_f32 v[100:101], v[100:101], v[132:133]
	v_pk_mul_f32 v[102:103], v[102:103], v[134:135]
	ds_write2_b64 v69, v[108:109], v[64:65] offset0:192 offset1:196
	v_pk_mul_f32 v[64:65], v[72:73], v[132:133]
	v_pk_mul_f32 v[66:67], v[74:75], v[134:135]
	v_pk_mul_f32 v[46:47], v[60:61], v[136:137]
	v_pk_mul_f32 v[48:49], v[62:63], v[138:139]
	ds_write2_b64 v69, v[44:45], v[0:1] offset0:200 offset1:204
	v_pk_mul_f32 v[0:1], v[28:29], v[140:141]
	v_pk_mul_f32 v[2:3], v[30:31], v[142:143]
	v_cvt_pk_bf16_f32 v96, v104, v105
	v_cvt_pk_bf16_f32 v99, v110, v111
	v_cvt_pk_bf16_f32 v104, v112, v113
	v_cvt_pk_bf16_f32 v105, v114, v115
	v_cvt_pk_bf16_f32 v110, v124, v125
	v_cvt_pk_bf16_f32 v111, v126, v127
	v_cvt_pk_bf16_f32 v76, v84, v85
	v_cvt_pk_bf16_f32 v77, v86, v87
	v_cvt_pk_bf16_f32 v78, v92, v93
	v_cvt_pk_bf16_f32 v79, v94, v95
	v_cvt_pk_bf16_f32 v84, v100, v101
	v_cvt_pk_bf16_f32 v85, v102, v103
	v_cvt_pk_bf16_f32 v64, v64, v65
	v_cvt_pk_bf16_f32 v65, v66, v67
	v_add_u32_e32 v66, 0x7000, v144
	v_cvt_pk_bf16_f32 v46, v46, v47
	v_cvt_pk_bf16_f32 v47, v48, v49
	v_cvt_pk_bf16_f32 v0, v0, v1
	v_cvt_pk_bf16_f32 v1, v2, v3
	v_mov_b32_e32 v2, v218
	ds_write2_b64 v146, v[96:97], v[76:77] offset0:64 offset1:68
	ds_write2_b64 v147, v[98:99], v[78:79] offset0:96 offset1:100
	ds_write2_b64 v148, v[104:105], v[84:85] offset0:128 offset1:132
	ds_write2_b64 v66, v[110:111], v[64:65] offset0:224 offset1:228
	ds_write2_b64 v66, v[46:47], v[0:1] offset0:232 offset1:236
	s_waitcnt lgkmcnt(0)
	s_barrier
; DI int tidx() { int t = __builtin_amdgcn_workitem_id_x(); asm volatile("" : "+v"(t)); return t; }
; DI unsigned cvtpk(float lo, float hi) { const f32x2_ v = {lo, hi}; return __builtin_bit_cast(unsigned, __builtin_convertvector(v, bf16x2_)); }
; DI float bflo(unsigned w) { return __uint_as_float(w << 16); }
; DI float bfhi(unsigned w) { return __uint_as_float(w & 0xffff0000u); }
; DI void phase9(const Params& p, const Sched& sched, unsigned char* smem) {
;     ...
;       const int tid = tidx();
; #pragma unroll
;       for (int i = 0; i < 16; ++i) {
;         const int c = tid + 256 * i, row = c >> 4, ch = (c & 15) * 8;
;         const size_t gi = (size_t)(tm * 256 + row) * 1024 + tn * 128 + ch;
;         const u32x4 sv = *(const u32x4*)(Ls + row * EST + ch), xv = *(const u32x4*)(x1b + gi);
;         u32x4 w;
;         w.x = cvtpk(bflo(xv.x) + bflo(sv.x), bfhi(xv.x) + bfhi(sv.x)); w.y = cvtpk(bflo(xv.y) + bflo(sv.y), bfhi(xv.y) + bfhi(sv.y));
;         w.z = cvtpk(bflo(xv.z) + bflo(sv.z), bfhi(xv.z) + bfhi(sv.z)); w.w = cvtpk(bflo(xv.w) + bflo(sv.w), bfhi(xv.w) + bfhi(sv.w));
;         *(u32x4*)(x2b + gi) = w;
;       }
	s_nop 0
	v_ashrrev_i32_e32 v3, 4, v2
	v_add_u32_e32 v4, s29, v3
	v_lshlrev_b32_e32 v0, 3, v2
	v_ashrrev_i32_e32 v5, 31, v4
	v_and_b32_e32 v1, 0x78, v0
	v_lshlrev_b64 v[4:5], 10, v[4:5]
	v_or3_b32 v4, v4, s30, v1
	v_lshlrev_b64 v[12:13], 1, v[4:5]
	v_lshl_add_u64 v[4:5], s[12:13], 0, v[12:13]
	global_load_dwordx4 v[4:7], v[4:5], off
	v_lshlrev_b32_e32 v0, 1, v1
	v_mad_u64_u32 v[8:9], s[34:35], v3, s25, v[0:1]
	ds_read_b128 v[8:11], v8
	v_add_u32_e32 v3, 0x100, v2
	v_ashrrev_i32_e32 v3, 4, v3
	s_waitcnt lgkmcnt(0)
	v_lshlrev_b32_e32 v16, 16, v8
	v_and_b32_e32 v17, 0xffff0000, v8
	v_lshlrev_b32_e32 v8, 16, v9
	v_and_b32_e32 v9, 0xffff0000, v9
	s_waitcnt vmcnt(0)
	v_lshlrev_b32_e32 v14, 16, v4
	v_and_b32_e32 v15, 0xffff0000, v4
	v_pk_add_f32 v[14:15], v[16:17], v[14:15]
	s_nop 0
	v_cvt_pk_bf16_f32 v4, v14, v15
	v_lshlrev_b32_e32 v14, 16, v5
	v_and_b32_e32 v15, 0xffff0000, v5
	v_pk_add_f32 v[8:9], v[8:9], v[14:15]
	v_lshlrev_b32_e32 v14, 16, v10
	v_cvt_pk_bf16_f32 v5, v8, v9
	v_lshlrev_b32_e32 v8, 16, v6
	v_and_b32_e32 v9, 0xffff0000, v6
	v_and_b32_e32 v15, 0xffff0000, v10
	v_pk_add_f32 v[8:9], v[14:15], v[8:9]
	v_lshlrev_b32_e32 v10, 16, v11
	v_cvt_pk_bf16_f32 v6, v8, v9
	v_lshlrev_b32_e32 v8, 16, v7
	v_and_b32_e32 v9, 0xffff0000, v7
	v_and_b32_e32 v11, 0xffff0000, v11
	v_pk_add_f32 v[8:9], v[10:11], v[8:9]
	s_nop 0
	v_cvt_pk_bf16_f32 v7, v8, v9
	v_lshl_add_u64 v[8:9], s[2:3], 0, v[12:13]
	global_store_dwordx4 v[8:9], v[4:7], off
	v_mad_u64_u32 v[8:9], s[34:35], v3, s25, v[0:1]
	s_nop 0
	v_add_u32_e32 v4, s29, v3
	v_ashrrev_i32_e32 v5, 31, v4
	v_lshlrev_b64 v[4:5], 10, v[4:5]
	v_or3_b32 v4, v4, s30, v1
	v_lshlrev_b64 v[12:13], 1, v[4:5]
	v_lshl_add_u64 v[4:5], s[12:13], 0, v[12:13]
	global_load_dwordx4 v[4:7], v[4:5], off
	ds_read_b128 v[8:11], v8
	v_add_u32_e32 v3, 0x200, v2
	v_ashrrev_i32_e32 v3, 4, v3
	v_lshl_add_u64 v[12:13], s[2:3], 0, v[12:13]
	s_waitcnt lgkmcnt(0)
	v_lshlrev_b32_e32 v14, 16, v8
	v_and_b32_e32 v15, 0xffff0000, v8
	v_lshlrev_b32_e32 v8, 16, v9
	v_and_b32_e32 v9, 0xffff0000, v9
	v_lshlrev_b32_e32 v16, 16, v10
	v_and_b32_e32 v17, 0xffff0000, v10
	v_lshlrev_b32_e32 v10, 16, v11
	v_and_b32_e32 v11, 0xffff0000, v11
	s_waitcnt vmcnt(0)
	v_lshlrev_b32_e32 v18, 16, v4
	v_and_b32_e32 v19, 0xffff0000, v4
	v_lshlrev_b32_e32 v4, 16, v5
	v_and_b32_e32 v5, 0xffff0000, v5
	v_lshlrev_b32_e32 v20, 16, v6
	v_and_b32_e32 v21, 0xffff0000, v6
	v_lshlrev_b32_e32 v6, 16, v7
	v_and_b32_e32 v7, 0xffff0000, v7
	v_pk_add_f32 v[14:15], v[14:15], v[18:19]
	v_pk_add_f32 v[8:9], v[8:9], v[4:5]
	v_pk_add_f32 v[16:17], v[16:17], v[20:21]
	v_pk_add_f32 v[10:11], v[10:11], v[6:7]
	v_cvt_pk_bf16_f32 v4, v14, v15
	v_cvt_pk_bf16_f32 v5, v8, v9
	v_cvt_pk_bf16_f32 v6, v16, v17
	v_cvt_pk_bf16_f32 v7, v10, v11
	global_store_dwordx4 v[12:13], v[4:7], off
	v_add_u32_e32 v8, 0x300, v2
	v_ashrrev_i32_e32 v26, 4, v8
	v_add_u32_e32 v4, s29, v3
	v_ashrrev_i32_e32 v5, 31, v4
	v_lshlrev_b64 v[4:5], 10, v[4:5]
	v_or3_b32 v4, v4, s30, v1
	v_lshlrev_b64 v[12:13], 1, v[4:5]
	v_lshl_add_u64 v[4:5], s[12:13], 0, v[12:13]
	global_load_dwordx4 v[4:7], v[4:5], off
	v_mad_u64_u32 v[8:9], s[34:35], v3, s25, v[0:1]
	ds_read_b128 v[8:11], v8
	v_add_u32_e32 v14, s29, v26
	v_ashrrev_i32_e32 v15, 31, v14
	v_lshlrev_b64 v[14:15], 10, v[14:15]
	v_or3_b32 v14, v14, s30, v1
	s_waitcnt lgkmcnt(0)
	v_lshlrev_b32_e32 v18, 16, v8
	v_and_b32_e32 v19, 0xffff0000, v8
	v_lshlrev_b32_e32 v8, 16, v9
	v_and_b32_e32 v9, 0xffff0000, v9
	v_lshlrev_b32_e32 v20, 16, v10
	v_and_b32_e32 v21, 0xffff0000, v10
	v_lshlrev_b32_e32 v10, 16, v11
	v_and_b32_e32 v11, 0xffff0000, v11
	v_lshlrev_b64 v[14:15], 1, v[14:15]
	v_lshl_add_u64 v[12:13], s[2:3], 0, v[12:13]
	v_lshl_add_u64 v[16:17], s[12:13], 0, v[14:15]
	v_add_u32_e32 v3, 0x400, v2
	v_ashrrev_i32_e32 v3, 4, v3
	v_lshl_add_u64 v[14:15], s[2:3], 0, v[14:15]
	s_waitcnt vmcnt(0)
	v_lshlrev_b32_e32 v22, 16, v4
	v_and_b32_e32 v23, 0xffff0000, v4
	v_lshlrev_b32_e32 v4, 16, v5
	v_and_b32_e32 v5, 0xffff0000, v5
	v_lshlrev_b32_e32 v24, 16, v6
	v_and_b32_e32 v25, 0xffff0000, v6
	v_lshlrev_b32_e32 v6, 16, v7
	v_and_b32_e32 v7, 0xffff0000, v7
	v_pk_add_f32 v[18:19], v[18:19], v[22:23]
	v_pk_add_f32 v[8:9], v[8:9], v[4:5]
	v_pk_add_f32 v[20:21], v[20:21], v[24:25]
	v_pk_add_f32 v[10:11], v[10:11], v[6:7]
	v_cvt_pk_bf16_f32 v4, v18, v19
	v_cvt_pk_bf16_f32 v5, v8, v9
	v_cvt_pk_bf16_f32 v6, v20, v21
	v_cvt_pk_bf16_f32 v7, v10, v11
	global_store_dwordx4 v[12:13], v[4:7], off
	global_load_dwordx4 v[4:7], v[16:17], off
	v_mad_u64_u32 v[8:9], s[34:35], v26, s25, v[0:1]
	ds_read_b128 v[8:11], v8
	v_add_u32_e32 v12, s29, v3
	v_ashrrev_i32_e32 v13, 31, v12
	v_lshlrev_b64 v[12:13], 10, v[12:13]
	v_or3_b32 v12, v12, s30, v1
	s_waitcnt lgkmcnt(0)
	v_lshlrev_b32_e32 v18, 16, v8
	v_and_b32_e32 v19, 0xffff0000, v8
	v_lshlrev_b32_e32 v8, 16, v9
	v_and_b32_e32 v9, 0xffff0000, v9
	v_lshlrev_b32_e32 v20, 16, v10
	v_and_b32_e32 v21, 0xffff0000, v10
	v_lshlrev_b32_e32 v10, 16, v11
	v_and_b32_e32 v11, 0xffff0000, v11
	v_lshlrev_b64 v[12:13], 1, v[12:13]
	v_lshl_add_u64 v[16:17], s[12:13], 0, v[12:13]
	v_lshl_add_u64 v[12:13], s[2:3], 0, v[12:13]
	s_waitcnt vmcnt(0)
	v_lshlrev_b32_e32 v22, 16, v4
	v_and_b32_e32 v23, 0xffff0000, v4
	v_lshlrev_b32_e32 v4, 16, v5
	v_and_b32_e32 v5, 0xffff0000, v5
	v_lshlrev_b32_e32 v24, 16, v6
	v_and_b32_e32 v25, 0xffff0000, v6
	v_lshlrev_b32_e32 v6, 16, v7
	v_and_b32_e32 v7, 0xffff0000, v7
	v_pk_add_f32 v[18:19], v[18:19], v[22:23]
	v_pk_add_f32 v[8:9], v[8:9], v[4:5]
	v_pk_add_f32 v[20:21], v[20:21], v[24:25]
	v_pk_add_f32 v[10:11], v[10:11], v[6:7]
	v_cvt_pk_bf16_f32 v4, v18, v19
	v_cvt_pk_bf16_f32 v5, v8, v9
	v_cvt_pk_bf16_f32 v6, v20, v21
	v_cvt_pk_bf16_f32 v7, v10, v11
	global_store_dwordx4 v[14:15], v[4:7], off
	global_load_dwordx4 v[4:7], v[16:17], off
	v_add_u32_e32 v8, 0x500, v2
	v_ashrrev_i32_e32 v26, 4, v8
	v_mad_u64_u32 v[8:9], s[34:35], v3, s25, v[0:1]
	ds_read_b128 v[8:11], v8
	v_add_u32_e32 v14, s29, v26
	v_ashrrev_i32_e32 v15, 31, v14
	v_lshlrev_b64 v[14:15], 10, v[14:15]
	v_or3_b32 v14, v14, s30, v1
	s_waitcnt lgkmcnt(0)
; DI int tidx() { int t = __builtin_amdgcn_workitem_id_x(); asm volatile("" : "+v"(t)); return t; }
; DI unsigned cvtpk(float lo, float hi) { const f32x2_ v = {lo, hi}; return __builtin_bit_cast(unsigned, __builtin_convertvector(v, bf16x2_)); }
; DI float bflo(unsigned w) { return __uint_as_float(w << 16); }
; DI float bfhi(unsigned w) { return __uint_as_float(w & 0xffff0000u); }
; DI void phase9(const Params& p, const Sched& sched, unsigned char* smem) {
;     ...
;       const int tid = tidx();
; #pragma unroll
;       for (int i = 0; i < 16; ++i) {
;         const int c = tid + 256 * i, row = c >> 4, ch = (c & 15) * 8;
;         const size_t gi = (size_t)(tm * 256 + row) * 1024 + tn * 128 + ch;
;         const u32x4 sv = *(const u32x4*)(Ls + row * EST + ch), xv = *(const u32x4*)(x1b + gi);
;         u32x4 w;
;         w.x = cvtpk(bflo(xv.x) + bflo(sv.x), bfhi(xv.x) + bfhi(sv.x)); w.y = cvtpk(bflo(xv.y) + bflo(sv.y), bfhi(xv.y) + bfhi(sv.y));
;         w.z = cvtpk(bflo(xv.z) + bflo(sv.z), bfhi(xv.z) + bfhi(sv.z)); w.w = cvtpk(bflo(xv.w) + bflo(sv.w), bfhi(xv.w) + bfhi(sv.w));
;         *(u32x4*)(x2b + gi) = w;
;       }
	v_lshlrev_b32_e32 v18, 16, v8
	v_and_b32_e32 v19, 0xffff0000, v8
	v_lshlrev_b32_e32 v8, 16, v9
	v_and_b32_e32 v9, 0xffff0000, v9
	v_lshlrev_b32_e32 v20, 16, v10
	v_and_b32_e32 v21, 0xffff0000, v10
	v_lshlrev_b32_e32 v10, 16, v11
	v_and_b32_e32 v11, 0xffff0000, v11
	v_lshlrev_b64 v[14:15], 1, v[14:15]
	v_lshl_add_u64 v[16:17], s[12:13], 0, v[14:15]
	v_add_u32_e32 v3, 0x600, v2
	v_ashrrev_i32_e32 v3, 4, v3
	v_lshl_add_u64 v[14:15], s[2:3], 0, v[14:15]
	s_waitcnt vmcnt(0)
	v_lshlrev_b32_e32 v22, 16, v4
	v_and_b32_e32 v23, 0xffff0000, v4
	v_lshlrev_b32_e32 v4, 16, v5
	v_and_b32_e32 v5, 0xffff0000, v5
	v_lshlrev_b32_e32 v24, 16, v6
	v_and_b32_e32 v25, 0xffff0000, v6
	v_lshlrev_b32_e32 v6, 16, v7
	v_and_b32_e32 v7, 0xffff0000, v7
	v_pk_add_f32 v[18:19], v[18:19], v[22:23]
	v_pk_add_f32 v[8:9], v[8:9], v[4:5]
	v_pk_add_f32 v[20:21], v[20:21], v[24:25]
	v_pk_add_f32 v[10:11], v[10:11], v[6:7]
	v_cvt_pk_bf16_f32 v4, v18, v19
	v_cvt_pk_bf16_f32 v5, v8, v9
	v_cvt_pk_bf16_f32 v6, v20, v21
	v_cvt_pk_bf16_f32 v7, v10, v11
	global_store_dwordx4 v[12:13], v[4:7], off
	global_load_dwordx4 v[4:7], v[16:17], off
	v_mad_u64_u32 v[8:9], s[34:35], v26, s25, v[0:1]
	ds_read_b128 v[8:11], v8
	v_add_u32_e32 v12, s29, v3
	v_ashrrev_i32_e32 v13, 31, v12
	v_lshlrev_b64 v[12:13], 10, v[12:13]
	v_or3_b32 v12, v12, s30, v1
	s_waitcnt lgkmcnt(0)
	v_lshlrev_b32_e32 v18, 16, v8
	v_and_b32_e32 v19, 0xffff0000, v8
	v_lshlrev_b32_e32 v8, 16, v9
	v_and_b32_e32 v9, 0xffff0000, v9
	v_lshlrev_b32_e32 v20, 16, v10
	v_and_b32_e32 v21, 0xffff0000, v10
	v_lshlrev_b32_e32 v10, 16, v11
	v_and_b32_e32 v11, 0xffff0000, v11
	v_lshlrev_b64 v[12:13], 1, v[12:13]
	v_lshl_add_u64 v[16:17], s[12:13], 0, v[12:13]
	v_lshl_add_u64 v[12:13], s[2:3], 0, v[12:13]
	s_waitcnt vmcnt(0)
	v_lshlrev_b32_e32 v22, 16, v4
	v_and_b32_e32 v23, 0xffff0000, v4
	v_lshlrev_b32_e32 v4, 16, v5
	v_and_b32_e32 v5, 0xffff0000, v5
	v_lshlrev_b32_e32 v24, 16, v6
	v_and_b32_e32 v25, 0xffff0000, v6
	v_lshlrev_b32_e32 v6, 16, v7
	v_and_b32_e32 v7, 0xffff0000, v7
	v_pk_add_f32 v[18:19], v[18:19], v[22:23]
	v_pk_add_f32 v[8:9], v[8:9], v[4:5]
	v_pk_add_f32 v[20:21], v[20:21], v[24:25]
	v_pk_add_f32 v[10:11], v[10:11], v[6:7]
	v_cvt_pk_bf16_f32 v4, v18, v19
	v_cvt_pk_bf16_f32 v5, v8, v9
	v_cvt_pk_bf16_f32 v6, v20, v21
	v_cvt_pk_bf16_f32 v7, v10, v11
	global_store_dwordx4 v[14:15], v[4:7], off
	global_load_dwordx4 v[4:7], v[16:17], off
	v_add_u32_e32 v8, 0x700, v2
	v_ashrrev_i32_e32 v26, 4, v8
	v_mad_u64_u32 v[8:9], s[34:35], v3, s25, v[0:1]
	ds_read_b128 v[8:11], v8
	v_add_u32_e32 v14, s29, v26
	v_ashrrev_i32_e32 v15, 31, v14
	v_lshlrev_b64 v[14:15], 10, v[14:15]
	v_or3_b32 v14, v14, s30, v1
	s_waitcnt lgkmcnt(0)
	v_lshlrev_b32_e32 v18, 16, v8
	v_and_b32_e32 v19, 0xffff0000, v8
	v_lshlrev_b32_e32 v8, 16, v9
	v_and_b32_e32 v9, 0xffff0000, v9
	v_lshlrev_b32_e32 v20, 16, v10
	v_and_b32_e32 v21, 0xffff0000, v10
	v_lshlrev_b32_e32 v10, 16, v11
	v_and_b32_e32 v11, 0xffff0000, v11
	v_lshlrev_b64 v[14:15], 1, v[14:15]
	v_lshl_add_u64 v[16:17], s[12:13], 0, v[14:15]
	v_add_u32_e32 v3, 0x800, v2
	v_ashrrev_i32_e32 v3, 4, v3
	v_lshl_add_u64 v[14:15], s[2:3], 0, v[14:15]
	s_waitcnt vmcnt(0)
	v_lshlrev_b32_e32 v22, 16, v4
	v_and_b32_e32 v23, 0xffff0000, v4
	v_lshlrev_b32_e32 v4, 16, v5
	v_and_b32_e32 v5, 0xffff0000, v5
	v_lshlrev_b32_e32 v24, 16, v6
	v_and_b32_e32 v25, 0xffff0000, v6
	v_lshlrev_b32_e32 v6, 16, v7
	v_and_b32_e32 v7, 0xffff0000, v7
	v_pk_add_f32 v[18:19], v[18:19], v[22:23]
	v_pk_add_f32 v[8:9], v[8:9], v[4:5]
	v_pk_add_f32 v[20:21], v[20:21], v[24:25]
	v_pk_add_f32 v[10:11], v[10:11], v[6:7]
	v_cvt_pk_bf16_f32 v4, v18, v19
	v_cvt_pk_bf16_f32 v5, v8, v9
	v_cvt_pk_bf16_f32 v6, v20, v21
	v_cvt_pk_bf16_f32 v7, v10, v11
	global_store_dwordx4 v[12:13], v[4:7], off
	global_load_dwordx4 v[4:7], v[16:17], off
	v_mad_u64_u32 v[8:9], s[34:35], v26, s25, v[0:1]
	ds_read_b128 v[8:11], v8
	v_add_u32_e32 v12, s29, v3
	v_ashrrev_i32_e32 v13, 31, v12
	v_lshlrev_b64 v[12:13], 10, v[12:13]
	v_or3_b32 v12, v12, s30, v1
	s_waitcnt lgkmcnt(0)
	v_lshlrev_b32_e32 v18, 16, v8
	v_and_b32_e32 v19, 0xffff0000, v8
	v_lshlrev_b32_e32 v8, 16, v9
	v_and_b32_e32 v9, 0xffff0000, v9
	v_lshlrev_b32_e32 v20, 16, v10
	v_and_b32_e32 v21, 0xffff0000, v10
	v_lshlrev_b32_e32 v10, 16, v11
	v_and_b32_e32 v11, 0xffff0000, v11
	v_lshlrev_b64 v[12:13], 1, v[12:13]
	v_lshl_add_u64 v[16:17], s[12:13], 0, v[12:13]
	v_lshl_add_u64 v[12:13], s[2:3], 0, v[12:13]
	s_waitcnt vmcnt(0)
	v_lshlrev_b32_e32 v22, 16, v4
	v_and_b32_e32 v23, 0xffff0000, v4
	v_lshlrev_b32_e32 v4, 16, v5
	v_and_b32_e32 v5, 0xffff0000, v5
	v_lshlrev_b32_e32 v24, 16, v6
	v_and_b32_e32 v25, 0xffff0000, v6
	v_lshlrev_b32_e32 v6, 16, v7
	v_and_b32_e32 v7, 0xffff0000, v7
	v_pk_add_f32 v[18:19], v[18:19], v[22:23]
	v_pk_add_f32 v[8:9], v[8:9], v[4:5]
	v_pk_add_f32 v[20:21], v[20:21], v[24:25]
	v_pk_add_f32 v[10:11], v[10:11], v[6:7]
	v_cvt_pk_bf16_f32 v4, v18, v19
	v_cvt_pk_bf16_f32 v5, v8, v9
	v_cvt_pk_bf16_f32 v6, v20, v21
	v_cvt_pk_bf16_f32 v7, v10, v11
	global_store_dwordx4 v[14:15], v[4:7], off
	global_load_dwordx4 v[4:7], v[16:17], off
	v_add_u32_e32 v8, 0x900, v2
	v_ashrrev_i32_e32 v26, 4, v8
	v_mad_u64_u32 v[8:9], s[34:35], v3, s25, v[0:1]
	ds_read_b128 v[8:11], v8
	v_add_u32_e32 v14, s29, v26
	v_ashrrev_i32_e32 v15, 31, v14
	v_lshlrev_b64 v[14:15], 10, v[14:15]
	v_or3_b32 v14, v14, s30, v1
	s_waitcnt lgkmcnt(0)
	v_lshlrev_b32_e32 v18, 16, v8
	v_and_b32_e32 v19, 0xffff0000, v8
	v_lshlrev_b32_e32 v8, 16, v9
	v_and_b32_e32 v9, 0xffff0000, v9
	v_lshlrev_b32_e32 v20, 16, v10
	v_and_b32_e32 v21, 0xffff0000, v10
	v_lshlrev_b32_e32 v10, 16, v11
	v_and_b32_e32 v11, 0xffff0000, v11
	v_lshlrev_b64 v[14:15], 1, v[14:15]
	v_lshl_add_u64 v[16:17], s[12:13], 0, v[14:15]
	v_add_u32_e32 v3, 0xa00, v2
	v_ashrrev_i32_e32 v3, 4, v3
	v_lshl_add_u64 v[14:15], s[2:3], 0, v[14:15]
	s_waitcnt vmcnt(0)
; DI int tidx() { int t = __builtin_amdgcn_workitem_id_x(); asm volatile("" : "+v"(t)); return t; }
; DI unsigned cvtpk(float lo, float hi) { const f32x2_ v = {lo, hi}; return __builtin_bit_cast(unsigned, __builtin_convertvector(v, bf16x2_)); }
; DI float bflo(unsigned w) { return __uint_as_float(w << 16); }
; DI float bfhi(unsigned w) { return __uint_as_float(w & 0xffff0000u); }
; DI void phase9(const Params& p, const Sched& sched, unsigned char* smem) {
;     ...
;       const int tid = tidx();
; #pragma unroll
;       for (int i = 0; i < 16; ++i) {
;         const int c = tid + 256 * i, row = c >> 4, ch = (c & 15) * 8;
;         const size_t gi = (size_t)(tm * 256 + row) * 1024 + tn * 128 + ch;
;         const u32x4 sv = *(const u32x4*)(Ls + row * EST + ch), xv = *(const u32x4*)(x1b + gi);
;         u32x4 w;
;         w.x = cvtpk(bflo(xv.x) + bflo(sv.x), bfhi(xv.x) + bfhi(sv.x)); w.y = cvtpk(bflo(xv.y) + bflo(sv.y), bfhi(xv.y) + bfhi(sv.y));
;         w.z = cvtpk(bflo(xv.z) + bflo(sv.z), bfhi(xv.z) + bfhi(sv.z)); w.w = cvtpk(bflo(xv.w) + bflo(sv.w), bfhi(xv.w) + bfhi(sv.w));
;         *(u32x4*)(x2b + gi) = w;
;       }
	v_lshlrev_b32_e32 v22, 16, v4
	v_and_b32_e32 v23, 0xffff0000, v4
	v_lshlrev_b32_e32 v4, 16, v5
	v_and_b32_e32 v5, 0xffff0000, v5
	v_lshlrev_b32_e32 v24, 16, v6
	v_and_b32_e32 v25, 0xffff0000, v6
	v_lshlrev_b32_e32 v6, 16, v7
	v_and_b32_e32 v7, 0xffff0000, v7
	v_pk_add_f32 v[18:19], v[18:19], v[22:23]
	v_pk_add_f32 v[8:9], v[8:9], v[4:5]
	v_pk_add_f32 v[20:21], v[20:21], v[24:25]
	v_pk_add_f32 v[10:11], v[10:11], v[6:7]
	v_cvt_pk_bf16_f32 v4, v18, v19
	v_cvt_pk_bf16_f32 v5, v8, v9
	v_cvt_pk_bf16_f32 v6, v20, v21
	v_cvt_pk_bf16_f32 v7, v10, v11
	global_store_dwordx4 v[12:13], v[4:7], off
	global_load_dwordx4 v[4:7], v[16:17], off
	v_mad_u64_u32 v[8:9], s[34:35], v26, s25, v[0:1]
	ds_read_b128 v[8:11], v8
	v_add_u32_e32 v12, s29, v3
	v_ashrrev_i32_e32 v13, 31, v12
	v_lshlrev_b64 v[12:13], 10, v[12:13]
	v_or3_b32 v12, v12, s30, v1
	s_waitcnt lgkmcnt(0)
	v_lshlrev_b32_e32 v18, 16, v8
	v_and_b32_e32 v19, 0xffff0000, v8
	v_lshlrev_b32_e32 v8, 16, v9
	v_and_b32_e32 v9, 0xffff0000, v9
	v_lshlrev_b32_e32 v20, 16, v10
	v_and_b32_e32 v21, 0xffff0000, v10
	v_lshlrev_b32_e32 v10, 16, v11
	v_and_b32_e32 v11, 0xffff0000, v11
	v_lshlrev_b64 v[12:13], 1, v[12:13]
	v_lshl_add_u64 v[16:17], s[12:13], 0, v[12:13]
	v_lshl_add_u64 v[12:13], s[2:3], 0, v[12:13]
	s_waitcnt vmcnt(0)
	v_lshlrev_b32_e32 v22, 16, v4
	v_and_b32_e32 v23, 0xffff0000, v4
	v_lshlrev_b32_e32 v4, 16, v5
	v_and_b32_e32 v5, 0xffff0000, v5
	v_lshlrev_b32_e32 v24, 16, v6
	v_and_b32_e32 v25, 0xffff0000, v6
	v_lshlrev_b32_e32 v6, 16, v7
	v_and_b32_e32 v7, 0xffff0000, v7
	v_pk_add_f32 v[18:19], v[18:19], v[22:23]
	v_pk_add_f32 v[8:9], v[8:9], v[4:5]
	v_pk_add_f32 v[20:21], v[20:21], v[24:25]
	v_pk_add_f32 v[10:11], v[10:11], v[6:7]
	v_cvt_pk_bf16_f32 v4, v18, v19
	v_cvt_pk_bf16_f32 v5, v8, v9
	v_cvt_pk_bf16_f32 v6, v20, v21
	v_cvt_pk_bf16_f32 v7, v10, v11
	global_store_dwordx4 v[14:15], v[4:7], off
	global_load_dwordx4 v[4:7], v[16:17], off
	v_add_u32_e32 v8, 0xb00, v2
	v_ashrrev_i32_e32 v26, 4, v8
	v_mad_u64_u32 v[8:9], s[34:35], v3, s25, v[0:1]
	ds_read_b128 v[8:11], v8
	v_add_u32_e32 v14, s29, v26
	v_ashrrev_i32_e32 v15, 31, v14
	v_lshlrev_b64 v[14:15], 10, v[14:15]
	v_or3_b32 v14, v14, s30, v1
	s_waitcnt lgkmcnt(0)
	v_lshlrev_b32_e32 v18, 16, v8
	v_and_b32_e32 v19, 0xffff0000, v8
	v_lshlrev_b32_e32 v8, 16, v9
	v_and_b32_e32 v9, 0xffff0000, v9
	v_lshlrev_b32_e32 v20, 16, v10
	v_and_b32_e32 v21, 0xffff0000, v10
	v_lshlrev_b32_e32 v10, 16, v11
	v_and_b32_e32 v11, 0xffff0000, v11
	v_lshlrev_b64 v[14:15], 1, v[14:15]
	v_lshl_add_u64 v[16:17], s[12:13], 0, v[14:15]
	v_add_u32_e32 v3, 0xc00, v2
	v_ashrrev_i32_e32 v3, 4, v3
	v_lshl_add_u64 v[14:15], s[2:3], 0, v[14:15]
	s_waitcnt vmcnt(0)
	v_lshlrev_b32_e32 v22, 16, v4
	v_and_b32_e32 v23, 0xffff0000, v4
	v_lshlrev_b32_e32 v4, 16, v5
	v_and_b32_e32 v5, 0xffff0000, v5
	v_lshlrev_b32_e32 v24, 16, v6
	v_and_b32_e32 v25, 0xffff0000, v6
	v_lshlrev_b32_e32 v6, 16, v7
	v_and_b32_e32 v7, 0xffff0000, v7
	v_pk_add_f32 v[18:19], v[18:19], v[22:23]
	v_pk_add_f32 v[8:9], v[8:9], v[4:5]
	v_pk_add_f32 v[20:21], v[20:21], v[24:25]
	v_pk_add_f32 v[10:11], v[10:11], v[6:7]
	v_cvt_pk_bf16_f32 v4, v18, v19
	v_cvt_pk_bf16_f32 v5, v8, v9
	v_cvt_pk_bf16_f32 v6, v20, v21
	v_cvt_pk_bf16_f32 v7, v10, v11
	global_store_dwordx4 v[12:13], v[4:7], off
	global_load_dwordx4 v[4:7], v[16:17], off
	v_mad_u64_u32 v[8:9], s[34:35], v26, s25, v[0:1]
	ds_read_b128 v[8:11], v8
	v_add_u32_e32 v12, s29, v3
	v_ashrrev_i32_e32 v13, 31, v12
	v_lshlrev_b64 v[12:13], 10, v[12:13]
	v_or3_b32 v12, v12, s30, v1
	s_waitcnt lgkmcnt(0)
	v_lshlrev_b32_e32 v18, 16, v8
	v_and_b32_e32 v19, 0xffff0000, v8
	v_lshlrev_b32_e32 v8, 16, v9
	v_and_b32_e32 v9, 0xffff0000, v9
	v_lshlrev_b32_e32 v20, 16, v10
	v_and_b32_e32 v21, 0xffff0000, v10
	v_lshlrev_b32_e32 v10, 16, v11
	v_and_b32_e32 v11, 0xffff0000, v11
	v_lshlrev_b64 v[12:13], 1, v[12:13]
	v_lshl_add_u64 v[16:17], s[12:13], 0, v[12:13]
	v_lshl_add_u64 v[12:13], s[2:3], 0, v[12:13]
	s_waitcnt vmcnt(0)
	v_lshlrev_b32_e32 v22, 16, v4
	v_and_b32_e32 v23, 0xffff0000, v4
	v_lshlrev_b32_e32 v4, 16, v5
	v_and_b32_e32 v5, 0xffff0000, v5
	v_lshlrev_b32_e32 v24, 16, v6
	v_and_b32_e32 v25, 0xffff0000, v6
	v_lshlrev_b32_e32 v6, 16, v7
	v_and_b32_e32 v7, 0xffff0000, v7
	v_pk_add_f32 v[18:19], v[18:19], v[22:23]
	v_pk_add_f32 v[8:9], v[8:9], v[4:5]
	v_pk_add_f32 v[20:21], v[20:21], v[24:25]
	v_pk_add_f32 v[10:11], v[10:11], v[6:7]
	v_cvt_pk_bf16_f32 v4, v18, v19
	v_cvt_pk_bf16_f32 v5, v8, v9
	v_cvt_pk_bf16_f32 v6, v20, v21
	v_cvt_pk_bf16_f32 v7, v10, v11
	global_store_dwordx4 v[14:15], v[4:7], off
	global_load_dwordx4 v[4:7], v[16:17], off
	v_add_u32_e32 v8, 0xd00, v2
	v_ashrrev_i32_e32 v26, 4, v8
	v_mad_u64_u32 v[8:9], s[34:35], v3, s25, v[0:1]
	ds_read_b128 v[8:11], v8
	v_add_u32_e32 v14, s29, v26
	v_ashrrev_i32_e32 v15, 31, v14
	v_lshlrev_b64 v[14:15], 10, v[14:15]
	v_or3_b32 v14, v14, s30, v1
	s_waitcnt lgkmcnt(0)
; DI int tidx() { int t = __builtin_amdgcn_workitem_id_x(); asm volatile("" : "+v"(t)); return t; }
; DI unsigned cvtpk(float lo, float hi) { const f32x2_ v = {lo, hi}; return __builtin_bit_cast(unsigned, __builtin_convertvector(v, bf16x2_)); }
; DI float bflo(unsigned w) { return __uint_as_float(w << 16); }
; DI float bfhi(unsigned w) { return __uint_as_float(w & 0xffff0000u); }
; DI void phase9(const Params& p, const Sched& sched, unsigned char* smem) {
;     ...
;       const int tid = tidx();
; #pragma unroll
;       for (int i = 0; i < 16; ++i) {
;         const int c = tid + 256 * i, row = c >> 4, ch = (c & 15) * 8;
;         const size_t gi = (size_t)(tm * 256 + row) * 1024 + tn * 128 + ch;
;         const u32x4 sv = *(const u32x4*)(Ls + row * EST + ch), xv = *(const u32x4*)(x1b + gi);
;         u32x4 w;
;         w.x = cvtpk(bflo(xv.x) + bflo(sv.x), bfhi(xv.x) + bfhi(sv.x)); w.y = cvtpk(bflo(xv.y) + bflo(sv.y), bfhi(xv.y) + bfhi(sv.y));
;         w.z = cvtpk(bflo(xv.z) + bflo(sv.z), bfhi(xv.z) + bfhi(sv.z)); w.w = cvtpk(bflo(xv.w) + bflo(sv.w), bfhi(xv.w) + bfhi(sv.w));
;         *(u32x4*)(x2b + gi) = w;
;       }
	v_lshlrev_b32_e32 v18, 16, v8
	v_and_b32_e32 v19, 0xffff0000, v8
	v_lshlrev_b32_e32 v8, 16, v9
	v_and_b32_e32 v9, 0xffff0000, v9
	v_lshlrev_b32_e32 v20, 16, v10
	v_and_b32_e32 v21, 0xffff0000, v10
	v_lshlrev_b32_e32 v10, 16, v11
	v_and_b32_e32 v11, 0xffff0000, v11
	v_lshlrev_b64 v[14:15], 1, v[14:15]
	v_lshl_add_u64 v[16:17], s[12:13], 0, v[14:15]
	v_add_u32_e32 v3, 0xe00, v2
	v_ashrrev_i32_e32 v3, 4, v3
	v_lshl_add_u64 v[14:15], s[2:3], 0, v[14:15]
	v_add_u32_e32 v2, 0xf00, v2
	s_waitcnt vmcnt(0)
	v_lshlrev_b32_e32 v22, 16, v4
	v_and_b32_e32 v23, 0xffff0000, v4
	v_lshlrev_b32_e32 v4, 16, v5
	v_and_b32_e32 v5, 0xffff0000, v5
	v_lshlrev_b32_e32 v24, 16, v6
	v_and_b32_e32 v25, 0xffff0000, v6
	v_lshlrev_b32_e32 v6, 16, v7
	v_and_b32_e32 v7, 0xffff0000, v7
	v_pk_add_f32 v[18:19], v[18:19], v[22:23]
	v_pk_add_f32 v[8:9], v[8:9], v[4:5]
	v_pk_add_f32 v[20:21], v[20:21], v[24:25]
	v_pk_add_f32 v[10:11], v[10:11], v[6:7]
	v_cvt_pk_bf16_f32 v4, v18, v19
	v_cvt_pk_bf16_f32 v5, v8, v9
	v_cvt_pk_bf16_f32 v6, v20, v21
	v_cvt_pk_bf16_f32 v7, v10, v11
	global_store_dwordx4 v[12:13], v[4:7], off
	global_load_dwordx4 v[4:7], v[16:17], off
	v_mad_u64_u32 v[8:9], s[34:35], v26, s25, v[0:1]
	ds_read_b128 v[8:11], v8
	v_add_u32_e32 v12, s29, v3
	v_ashrrev_i32_e32 v13, 31, v12
	v_lshlrev_b64 v[12:13], 10, v[12:13]
	v_or3_b32 v12, v12, s30, v1
	s_waitcnt lgkmcnt(0)
	v_lshlrev_b32_e32 v18, 16, v8
	v_and_b32_e32 v19, 0xffff0000, v8
	v_lshlrev_b32_e32 v8, 16, v9
	v_and_b32_e32 v9, 0xffff0000, v9
	v_lshlrev_b32_e32 v20, 16, v10
	v_and_b32_e32 v21, 0xffff0000, v10
	v_lshlrev_b32_e32 v10, 16, v11
	v_and_b32_e32 v11, 0xffff0000, v11
	v_lshlrev_b64 v[12:13], 1, v[12:13]
	v_lshl_add_u64 v[16:17], s[12:13], 0, v[12:13]
	v_lshl_add_u64 v[12:13], s[2:3], 0, v[12:13]
	s_waitcnt vmcnt(0)
	v_lshlrev_b32_e32 v22, 16, v4
	v_and_b32_e32 v23, 0xffff0000, v4
	v_lshlrev_b32_e32 v4, 16, v5
	v_and_b32_e32 v5, 0xffff0000, v5
	v_lshlrev_b32_e32 v24, 16, v6
	v_and_b32_e32 v25, 0xffff0000, v6
	v_lshlrev_b32_e32 v6, 16, v7
	v_and_b32_e32 v7, 0xffff0000, v7
	v_pk_add_f32 v[18:19], v[18:19], v[22:23]
	v_pk_add_f32 v[8:9], v[8:9], v[4:5]
	v_pk_add_f32 v[20:21], v[20:21], v[24:25]
	v_pk_add_f32 v[10:11], v[10:11], v[6:7]
	v_cvt_pk_bf16_f32 v4, v18, v19
	v_cvt_pk_bf16_f32 v5, v8, v9
	v_cvt_pk_bf16_f32 v6, v20, v21
	v_cvt_pk_bf16_f32 v7, v10, v11
	global_store_dwordx4 v[14:15], v[4:7], off
	global_load_dwordx4 v[4:7], v[16:17], off
	v_mad_u64_u32 v[8:9], s[34:35], v3, s25, v[0:1]
	v_ashrrev_i32_e32 v24, 4, v2
	ds_read_b128 v[8:11], v8
	v_add_u32_e32 v2, s29, v24
	v_ashrrev_i32_e32 v3, 31, v2
	v_lshlrev_b64 v[2:3], 10, v[2:3]
	v_or3_b32 v2, v2, s30, v1
	v_lshlrev_b64 v[14:15], 1, v[2:3]
	s_waitcnt lgkmcnt(0)
	v_lshlrev_b32_e32 v2, 16, v8
	v_and_b32_e32 v3, 0xffff0000, v8
	v_lshlrev_b32_e32 v8, 16, v9
	v_and_b32_e32 v9, 0xffff0000, v9
	v_lshlrev_b32_e32 v18, 16, v10
	v_and_b32_e32 v19, 0xffff0000, v10
	v_lshlrev_b32_e32 v10, 16, v11
	v_and_b32_e32 v11, 0xffff0000, v11
	v_lshl_add_u64 v[16:17], s[12:13], 0, v[14:15]
	v_mad_u64_u32 v[0:1], s[30:31], v24, s25, v[0:1]
	s_waitcnt vmcnt(0)
	v_lshlrev_b32_e32 v20, 16, v4
	v_and_b32_e32 v21, 0xffff0000, v4
	v_lshlrev_b32_e32 v4, 16, v5
	v_and_b32_e32 v5, 0xffff0000, v5
	v_lshlrev_b32_e32 v22, 16, v6
	v_and_b32_e32 v23, 0xffff0000, v6
	v_lshlrev_b32_e32 v6, 16, v7
	v_and_b32_e32 v7, 0xffff0000, v7
	v_pk_add_f32 v[2:3], v[2:3], v[20:21]
	v_pk_add_f32 v[4:5], v[8:9], v[4:5]
	v_pk_add_f32 v[8:9], v[18:19], v[22:23]
	v_pk_add_f32 v[6:7], v[10:11], v[6:7]
	v_cvt_pk_bf16_f32 v2, v2, v3
	v_cvt_pk_bf16_f32 v3, v4, v5
	v_cvt_pk_bf16_f32 v4, v8, v9
	v_cvt_pk_bf16_f32 v5, v6, v7
	global_store_dwordx4 v[12:13], v[2:5], off
	global_load_dwordx4 v[2:5], v[16:17], off
	ds_read_b128 v[6:9], v0
	v_lshl_add_u64 v[10:11], s[2:3], 0, v[14:15]
	s_waitcnt lgkmcnt(0)
	v_lshlrev_b32_e32 v0, 16, v6
	v_and_b32_e32 v1, 0xffff0000, v6
	v_lshlrev_b32_e32 v6, 16, v7
	v_and_b32_e32 v7, 0xffff0000, v7
	v_lshlrev_b32_e32 v12, 16, v8
	v_and_b32_e32 v13, 0xffff0000, v8
	v_lshlrev_b32_e32 v8, 16, v9
	v_and_b32_e32 v9, 0xffff0000, v9
	s_waitcnt vmcnt(0)
	v_lshlrev_b32_e32 v14, 16, v2
	v_and_b32_e32 v15, 0xffff0000, v2
	v_lshlrev_b32_e32 v2, 16, v3
	v_and_b32_e32 v3, 0xffff0000, v3
	v_lshlrev_b32_e32 v16, 16, v4
	v_and_b32_e32 v17, 0xffff0000, v4
	v_lshlrev_b32_e32 v4, 16, v5
	v_and_b32_e32 v5, 0xffff0000, v5
	v_pk_add_f32 v[0:1], v[0:1], v[14:15]
	v_pk_add_f32 v[2:3], v[6:7], v[2:3]
	v_pk_add_f32 v[6:7], v[12:13], v[16:17]
	v_pk_add_f32 v[4:5], v[8:9], v[4:5]
	v_cvt_pk_bf16_f32 v0, v0, v1
	v_cvt_pk_bf16_f32 v1, v2, v3
	v_cvt_pk_bf16_f32 v2, v6, v7
	v_cvt_pk_bf16_f32 v3, v4, v5
	global_store_dwordx4 v[10:11], v[0:3], off
	s_cbranch_scc0 .LBB0_1094
	s_branch .LBB0_1091
